# GEMM K-loops (22 loops): LDS-DMA pieces issued in saddr form (SGPR base + 32-bit VGPR offset), per-piece v_lshl_add_u64 removed
# speedup vs baseline: 1.0073x; 1.0073x over previous
.LBB0_162:
	s_ashr_i32 s19, s18, 31
	s_lshl_b64 s[20:21], s[18:19], 19
	s_add_u32 s20, s8, s20
	s_addc_u32 s21, s9, s21
	s_and_b64 s[22:23], s[4:5], exec
	s_cselect_b32 s19, s21, s27
	s_cselect_b32 s51, s20, s26
	s_ashr_i32 s17, s16, 31
	s_lshl_b64 s[22:23], s[16:17], 19
	s_add_u32 s22, s31, s22
	s_addc_u32 s23, s34, s23
	s_and_b64 s[28:29], s[4:5], exec
	s_cselect_b32 s17, s23, s25
	s_cselect_b32 s52, s22, s24
	s_add_u32 s53, s24, 0x100
	s_addc_u32 s54, s25, 0
	s_add_u32 s24, s26, 0x40080
	v_mov_b32_e32 v0, 0
	s_addc_u32 s25, s27, 0
	s_mov_b32 s55, -2
	v_mov_b32_e32 v1, v0
	v_mov_b32_e32 v2, v0
	v_mov_b32_e32 v3, v0
	v_mov_b32_e32 v4, v0
	v_mov_b32_e32 v5, v0
	v_mov_b32_e32 v6, v0
	v_mov_b32_e32 v7, v0
	v_mov_b32_e32 v16, v0
	v_mov_b32_e32 v17, v0
	s_waitcnt vmcnt(0)
	v_mov_b32_e32 v18, v0
	v_mov_b32_e32 v19, v0
	v_mov_b32_e32 v20, v0
	v_mov_b32_e32 v21, v0
	v_mov_b32_e32 v22, v0
	v_mov_b32_e32 v23, v0
	v_mov_b32_e32 v32, v0
	v_mov_b32_e32 v33, v0
	v_mov_b32_e32 v34, v0
	v_mov_b32_e32 v35, v0
	v_mov_b32_e32 v36, v0
	v_mov_b32_e32 v37, v0
	v_mov_b32_e32 v38, v0
	v_mov_b32_e32 v39, v0
	v_mov_b32_e32 v48, v0
	v_mov_b32_e32 v49, v0
	v_mov_b32_e32 v50, v0
	v_mov_b32_e32 v51, v0
	v_mov_b32_e32 v52, v0
	v_mov_b32_e32 v53, v0
	v_mov_b32_e32 v54, v0
	v_mov_b32_e32 v55, v0
	v_mov_b32_e32 v8, v0
	v_mov_b32_e32 v9, v0
	v_mov_b32_e32 v10, v0
	v_mov_b32_e32 v11, v0
	v_mov_b32_e32 v12, v0
	v_mov_b32_e32 v13, v0
	v_mov_b32_e32 v14, v0
	v_mov_b32_e32 v15, v0
	v_mov_b32_e32 v24, v0
	v_mov_b32_e32 v25, v0
	v_mov_b32_e32 v26, v0
	v_mov_b32_e32 v27, v0
	v_mov_b32_e32 v28, v0
	v_mov_b32_e32 v29, v0
	v_mov_b32_e32 v30, v0
	v_mov_b32_e32 v31, v0
	v_mov_b32_e32 v40, v0
	v_mov_b32_e32 v41, v0
	v_mov_b32_e32 v42, v0
	v_mov_b32_e32 v43, v0
	v_mov_b32_e32 v44, v0
	v_mov_b32_e32 v45, v0
	v_mov_b32_e32 v46, v0
	v_mov_b32_e32 v47, v0
	v_mov_b32_e32 v56, v0
	v_mov_b32_e32 v57, v0
	v_mov_b32_e32 v58, v0
	v_mov_b32_e32 v59, v0
	v_mov_b32_e32 v60, v0
	v_mov_b32_e32 v61, v0
	v_mov_b32_e32 v62, v0
	v_mov_b32_e32 v63, v0
	v_mov_b32_e32 v64, v0
	v_mov_b32_e32 v65, v0
	v_mov_b32_e32 v66, v0
	v_mov_b32_e32 v67, v0
	v_mov_b32_e32 v68, v0
	v_mov_b32_e32 v69, v0
	v_mov_b32_e32 v70, v0
	v_mov_b32_e32 v71, v0
	v_mov_b32_e32 v80, v0
	v_mov_b32_e32 v81, v0
	v_mov_b32_e32 v82, v0
	v_mov_b32_e32 v83, v0
	v_mov_b32_e32 v84, v0
	v_mov_b32_e32 v85, v0
	v_mov_b32_e32 v86, v0
	v_mov_b32_e32 v87, v0
	v_mov_b32_e32 v96, v0
	v_mov_b32_e32 v97, v0
	v_mov_b32_e32 v98, v0
	v_mov_b32_e32 v99, v0
	v_mov_b32_e32 v100, v0
	v_mov_b32_e32 v101, v0
	v_mov_b32_e32 v102, v0
	v_mov_b32_e32 v103, v0
	v_mov_b32_e32 v112, v0
	v_mov_b32_e32 v113, v0
	v_mov_b32_e32 v114, v0
	v_mov_b32_e32 v115, v0
	v_mov_b32_e32 v116, v0
	v_mov_b32_e32 v117, v0
	v_mov_b32_e32 v118, v0
	v_mov_b32_e32 v119, v0
	v_mov_b32_e32 v72, v0
	v_mov_b32_e32 v73, v0
	v_mov_b32_e32 v74, v0
	v_mov_b32_e32 v75, v0
	v_mov_b32_e32 v76, v0
	v_mov_b32_e32 v77, v0
	v_mov_b32_e32 v78, v0
	v_mov_b32_e32 v79, v0
	v_mov_b32_e32 v88, v0
	v_mov_b32_e32 v89, v0
	v_mov_b32_e32 v90, v0
	v_mov_b32_e32 v91, v0
	v_mov_b32_e32 v92, v0
	v_mov_b32_e32 v93, v0
	v_mov_b32_e32 v94, v0
	v_mov_b32_e32 v95, v0
	v_mov_b32_e32 v104, v0
	v_mov_b32_e32 v105, v0
	v_mov_b32_e32 v106, v0
	v_mov_b32_e32 v107, v0
	v_mov_b32_e32 v108, v0
	v_mov_b32_e32 v109, v0
	v_mov_b32_e32 v110, v0
	v_mov_b32_e32 v111, v0
	v_mov_b32_e32 v120, v0
	v_mov_b32_e32 v121, v0
	v_mov_b32_e32 v122, v0
	v_mov_b32_e32 v123, v0
	v_mov_b32_e32 v124, v0
	v_mov_b32_e32 v125, v0
	v_mov_b32_e32 v126, v0
	v_mov_b32_e32 v127, v0
	v_add_u32_e32 v204, 0x80, v128
	v_add_u32_e32 v205, 0x80, v130
	v_add_u32_e32 v220, 0x80, v132
	v_add_u32_e32 v221, 0x80, v134
.LBB0_163:
	ds_read_b128 v[144:147], v151
	ds_read_b128 v[156:159], v151 offset:1024
	ds_read_b128 v[160:163], v151 offset:2048
	ds_read_b128 v[164:167], v151 offset:3072
	ds_read_b128 v[168:171], v152
	ds_read_b128 v[172:175], v152 offset:1024
	ds_read_b128 v[176:179], v152 offset:2048
	ds_read_b128 v[180:183], v152 offset:3072
	s_add_u32 s26, s24, 0xfffc0080
	s_addc_u32 s27, s25, -1
	s_cmp_eq_u32 s55, 12
	s_cselect_b32 s29, s19, s27
	s_cselect_b32 s28, s51, s26
	s_cselect_b32 s27, s17, s54
	s_cselect_b32 s26, s52, s53
	s_add_i32 m0, s38, 0xc000
	ds_read_b128 v[184:187], v153
	ds_read_b128 v[188:191], v153 offset:1024
	ds_read_b128 v[192:195], v153 offset:2048
	ds_read_b128 v[196:199], v153 offset:3072
	ds_read_b128 v[200:203], v153 offset:4096
	ds_read_b128 v[208:211], v153 offset:5120
	ds_read_b128 v[212:215], v153 offset:6144
	ds_read_b128 v[216:219], v153 offset:7168
	global_load_lds_dwordx4 v138, s[24:25]
	s_add_i32 m0, s38, 0xe000
	s_nop 0
	global_load_lds_dwordx4 v136, s[24:25]
	s_waitcnt vmcnt(8)
	s_waitcnt lgkmcnt(0)
	s_barrier
	s_waitcnt lgkmcnt(0)
	v_mfma_f32_16x16x32_bf16 v[124:127], v[144:147], v[184:187], v[124:127]
	v_mfma_f32_16x16x32_bf16 v[120:123], v[160:163], v[184:187], v[120:123]
	v_mfma_f32_16x16x32_bf16 v[108:111], v[144:147], v[192:195], v[108:111]
	v_mfma_f32_16x16x32_bf16 v[104:107], v[160:163], v[192:195], v[104:107]
	v_mfma_f32_16x16x32_bf16 v[92:95], v[144:147], v[200:203], v[92:95]
	v_mfma_f32_16x16x32_bf16 v[88:91], v[160:163], v[200:203], v[88:91]
	v_mfma_f32_16x16x32_bf16 v[76:79], v[144:147], v[212:215], v[76:79]
	v_mfma_f32_16x16x32_bf16 v[72:75], v[160:163], v[212:215], v[72:75]
	v_mfma_f32_16x16x32_bf16 v[124:127], v[156:159], v[188:191], v[124:127]
	v_mfma_f32_16x16x32_bf16 v[120:123], v[164:167], v[188:191], v[120:123]
	v_mfma_f32_16x16x32_bf16 v[108:111], v[156:159], v[196:199], v[108:111]
	v_mfma_f32_16x16x32_bf16 v[104:107], v[164:167], v[196:199], v[104:107]
	v_mfma_f32_16x16x32_bf16 v[92:95], v[156:159], v[208:211], v[92:95]
	v_mfma_f32_16x16x32_bf16 v[88:91], v[164:167], v[208:211], v[88:91]
	v_mfma_f32_16x16x32_bf16 v[76:79], v[156:159], v[216:219], v[76:79]
	v_mfma_f32_16x16x32_bf16 v[72:75], v[164:167], v[216:219], v[72:75]
	v_mfma_f32_16x16x32_bf16 v[116:119], v[168:171], v[184:187], v[116:119]
	v_mfma_f32_16x16x32_bf16 v[112:115], v[176:179], v[184:187], v[112:115]
	v_mfma_f32_16x16x32_bf16 v[100:103], v[168:171], v[192:195], v[100:103]
	v_mfma_f32_16x16x32_bf16 v[96:99], v[176:179], v[192:195], v[96:99]
	v_mfma_f32_16x16x32_bf16 v[84:87], v[168:171], v[200:203], v[84:87]
	v_mfma_f32_16x16x32_bf16 v[80:83], v[176:179], v[200:203], v[80:83]
	v_mfma_f32_16x16x32_bf16 v[68:71], v[168:171], v[212:215], v[68:71]
	v_mfma_f32_16x16x32_bf16 v[64:67], v[176:179], v[212:215], v[64:67]
	v_mfma_f32_16x16x32_bf16 v[116:119], v[172:175], v[188:191], v[116:119]
	v_mfma_f32_16x16x32_bf16 v[112:115], v[180:183], v[188:191], v[112:115]
	v_mfma_f32_16x16x32_bf16 v[100:103], v[172:175], v[196:199], v[100:103]
	v_mfma_f32_16x16x32_bf16 v[96:99], v[180:183], v[196:199], v[96:99]
	v_mfma_f32_16x16x32_bf16 v[84:87], v[172:175], v[208:211], v[84:87]
	v_mfma_f32_16x16x32_bf16 v[80:83], v[180:183], v[208:211], v[80:83]
	v_mfma_f32_16x16x32_bf16 v[68:71], v[172:175], v[216:219], v[68:71]
	v_mfma_f32_16x16x32_bf16 v[64:67], v[180:183], v[216:219], v[64:67]
	s_barrier
	s_add_i32 s56, s48, s35
	s_mov_b32 m0, s56
	ds_read_b128 v[184:187], v153 offset:16384
	ds_read_b128 v[188:191], v153 offset:17408
	ds_read_b128 v[192:195], v153 offset:18432
	ds_read_b128 v[196:199], v153 offset:19456
	ds_read_b128 v[200:203], v153 offset:20480
	ds_read_b128 v[208:211], v153 offset:21504
	ds_read_b128 v[212:215], v153 offset:22528
	ds_read_b128 v[216:219], v153 offset:23552
	global_load_lds_dwordx4 v132, s[26:27]
	s_add_i32 m0, s56, 0x2000
	s_add_u32 s56, s26, 0x40000
	s_mov_b64 s[98:99], s[26:27]
	s_addc_u32 s57, s27, 0
	s_add_i32 s58, s49, s35
	global_load_lds_dwordx4 v128, s[26:27]
	s_mov_b32 m0, s58
	s_mov_b64 s[100:101], s[28:29]
	global_load_lds_dwordx4 v132, s[56:57]
	s_add_i32 m0, s58, 0x2000
	s_nop 0
	global_load_lds_dwordx4 v128, s[56:57]
	s_mov_b32 m0, s38
	s_nop 0
	global_load_lds_dwordx4 v134, s[28:29]
	s_mov_b32 m0, s39
	s_nop 0
	global_load_lds_dwordx4 v130, s[28:29]
	s_waitcnt vmcnt(8)
	s_waitcnt lgkmcnt(0)
	s_barrier
	s_waitcnt lgkmcnt(0)
	v_mfma_f32_16x16x32_bf16 v[60:63], v[144:147], v[184:187], v[60:63]
	v_mfma_f32_16x16x32_bf16 v[56:59], v[160:163], v[184:187], v[56:59]
	v_mfma_f32_16x16x32_bf16 v[44:47], v[144:147], v[192:195], v[44:47]
	v_mfma_f32_16x16x32_bf16 v[40:43], v[160:163], v[192:195], v[40:43]
	v_mfma_f32_16x16x32_bf16 v[28:31], v[144:147], v[200:203], v[28:31]
	v_mfma_f32_16x16x32_bf16 v[24:27], v[160:163], v[200:203], v[24:27]
	v_mfma_f32_16x16x32_bf16 v[12:15], v[144:147], v[212:215], v[12:15]
	v_mfma_f32_16x16x32_bf16 v[8:11], v[160:163], v[212:215], v[8:11]
	v_mfma_f32_16x16x32_bf16 v[60:63], v[156:159], v[188:191], v[60:63]
	v_mfma_f32_16x16x32_bf16 v[56:59], v[164:167], v[188:191], v[56:59]
	v_mfma_f32_16x16x32_bf16 v[44:47], v[156:159], v[196:199], v[44:47]
	v_mfma_f32_16x16x32_bf16 v[40:43], v[164:167], v[196:199], v[40:43]
	v_mfma_f32_16x16x32_bf16 v[28:31], v[156:159], v[208:211], v[28:31]
	v_mfma_f32_16x16x32_bf16 v[24:27], v[164:167], v[208:211], v[24:27]
	v_mfma_f32_16x16x32_bf16 v[12:15], v[156:159], v[216:219], v[12:15]
	v_mfma_f32_16x16x32_bf16 v[8:11], v[164:167], v[216:219], v[8:11]
	v_mfma_f32_16x16x32_bf16 v[52:55], v[168:171], v[184:187], v[52:55]
	v_mfma_f32_16x16x32_bf16 v[48:51], v[176:179], v[184:187], v[48:51]
	v_mfma_f32_16x16x32_bf16 v[36:39], v[168:171], v[192:195], v[36:39]
	v_mfma_f32_16x16x32_bf16 v[32:35], v[176:179], v[192:195], v[32:35]
	v_mfma_f32_16x16x32_bf16 v[20:23], v[168:171], v[200:203], v[20:23]
	v_mfma_f32_16x16x32_bf16 v[16:19], v[176:179], v[200:203], v[16:19]
	v_mfma_f32_16x16x32_bf16 v[4:7], v[168:171], v[212:215], v[4:7]
	v_mfma_f32_16x16x32_bf16 v[0:3], v[176:179], v[212:215], v[0:3]
	v_mfma_f32_16x16x32_bf16 v[52:55], v[172:175], v[188:191], v[52:55]
	v_mfma_f32_16x16x32_bf16 v[48:51], v[180:183], v[188:191], v[48:51]
	v_mfma_f32_16x16x32_bf16 v[36:39], v[172:175], v[196:199], v[36:39]
	v_mfma_f32_16x16x32_bf16 v[32:35], v[180:183], v[196:199], v[32:35]
	v_mfma_f32_16x16x32_bf16 v[20:23], v[172:175], v[208:211], v[20:23]
	v_mfma_f32_16x16x32_bf16 v[16:19], v[180:183], v[208:211], v[16:19]
	v_mfma_f32_16x16x32_bf16 v[4:7], v[172:175], v[216:219], v[4:7]
	v_mfma_f32_16x16x32_bf16 v[0:3], v[180:183], v[216:219], v[0:3]
	s_barrier
	s_add_i32 s56, 0, 0x18000
	s_add_i32 s57, 0, 0x1c000
	v_add_u32_e32 v164, s56, v149
	v_add_u32_e32 v180, s57, v149
	ds_read_b128 v[144:147], v164
	ds_read_b128 v[156:159], v164 offset:1024
	ds_read_b128 v[160:163], v164 offset:2048
	ds_read_b128 v[164:167], v164 offset:3072
	ds_read_b128 v[168:171], v180
	ds_read_b128 v[172:175], v180 offset:1024
	ds_read_b128 v[176:179], v180 offset:2048
	ds_read_b128 v[180:183], v180 offset:3072
	s_add_u32 s28, s28, 0x40000
	s_addc_u32 s29, s29, 0
	s_mov_b32 m0, s40
	ds_read_b128 v[184:187], v153 offset:32768
	ds_read_b128 v[188:191], v153 offset:33792
	ds_read_b128 v[192:195], v153 offset:34816
	ds_read_b128 v[196:199], v153 offset:35840
	ds_read_b128 v[200:203], v153 offset:36864
	ds_read_b128 v[208:211], v153 offset:37888
	ds_read_b128 v[212:215], v153 offset:38912
	ds_read_b128 v[216:219], v153 offset:39936
	global_load_lds_dwordx4 v134, s[28:29]
	s_mov_b32 m0, s41
	s_nop 0
	global_load_lds_dwordx4 v130, s[28:29]
	s_waitcnt vmcnt(8)
	s_waitcnt lgkmcnt(0)
	s_barrier
	s_waitcnt lgkmcnt(0)
	v_mfma_f32_16x16x32_bf16 v[124:127], v[144:147], v[184:187], v[124:127]
	v_mfma_f32_16x16x32_bf16 v[120:123], v[160:163], v[184:187], v[120:123]
	v_mfma_f32_16x16x32_bf16 v[108:111], v[144:147], v[192:195], v[108:111]
	v_mfma_f32_16x16x32_bf16 v[104:107], v[160:163], v[192:195], v[104:107]
	v_mfma_f32_16x16x32_bf16 v[92:95], v[144:147], v[200:203], v[92:95]
	v_mfma_f32_16x16x32_bf16 v[88:91], v[160:163], v[200:203], v[88:91]
	v_mfma_f32_16x16x32_bf16 v[76:79], v[144:147], v[212:215], v[76:79]
	v_mfma_f32_16x16x32_bf16 v[72:75], v[160:163], v[212:215], v[72:75]
	v_mfma_f32_16x16x32_bf16 v[124:127], v[156:159], v[188:191], v[124:127]
	v_mfma_f32_16x16x32_bf16 v[120:123], v[164:167], v[188:191], v[120:123]
	v_mfma_f32_16x16x32_bf16 v[108:111], v[156:159], v[196:199], v[108:111]
	v_mfma_f32_16x16x32_bf16 v[104:107], v[164:167], v[196:199], v[104:107]
	v_mfma_f32_16x16x32_bf16 v[92:95], v[156:159], v[208:211], v[92:95]
	v_mfma_f32_16x16x32_bf16 v[88:91], v[164:167], v[208:211], v[88:91]
	v_mfma_f32_16x16x32_bf16 v[76:79], v[156:159], v[216:219], v[76:79]
	v_mfma_f32_16x16x32_bf16 v[72:75], v[164:167], v[216:219], v[72:75]
	v_mfma_f32_16x16x32_bf16 v[116:119], v[168:171], v[184:187], v[116:119]
	v_mfma_f32_16x16x32_bf16 v[112:115], v[176:179], v[184:187], v[112:115]
	v_mfma_f32_16x16x32_bf16 v[100:103], v[168:171], v[192:195], v[100:103]
	v_mfma_f32_16x16x32_bf16 v[96:99], v[176:179], v[192:195], v[96:99]
	v_mfma_f32_16x16x32_bf16 v[84:87], v[168:171], v[200:203], v[84:87]
	v_mfma_f32_16x16x32_bf16 v[80:83], v[176:179], v[200:203], v[80:83]
	v_mfma_f32_16x16x32_bf16 v[68:71], v[168:171], v[212:215], v[68:71]
	v_mfma_f32_16x16x32_bf16 v[64:67], v[176:179], v[212:215], v[64:67]
	v_mfma_f32_16x16x32_bf16 v[116:119], v[172:175], v[188:191], v[116:119]
	v_mfma_f32_16x16x32_bf16 v[112:115], v[180:183], v[188:191], v[112:115]
	v_mfma_f32_16x16x32_bf16 v[100:103], v[172:175], v[196:199], v[100:103]
	v_mfma_f32_16x16x32_bf16 v[96:99], v[180:183], v[196:199], v[96:99]
	v_mfma_f32_16x16x32_bf16 v[84:87], v[172:175], v[208:211], v[84:87]
	v_mfma_f32_16x16x32_bf16 v[80:83], v[180:183], v[208:211], v[80:83]
	v_mfma_f32_16x16x32_bf16 v[68:71], v[172:175], v[216:219], v[68:71]
	v_mfma_f32_16x16x32_bf16 v[64:67], v[180:183], v[216:219], v[64:67]
	s_barrier
	s_add_i32 s28, s56, s35
	s_mov_b32 m0, s28
	ds_read_b128 v[184:187], v153 offset:49152
	ds_read_b128 v[188:191], v153 offset:50176
	ds_read_b128 v[192:195], v153 offset:51200
	ds_read_b128 v[196:199], v153 offset:52224
	ds_read_b128 v[200:203], v153 offset:53248
	ds_read_b128 v[208:211], v153 offset:54272
	ds_read_b128 v[212:215], v153 offset:55296
	ds_read_b128 v[216:219], v153 offset:56320
	global_load_lds_dwordx4 v220, s[26:27]
	s_add_i32 m0, s28, 0x2000
	s_add_u32 s26, s26, 0x40080
	s_addc_u32 s27, s27, 0
	s_add_i32 s28, s57, s35
	global_load_lds_dwordx4 v204, s[98:99]
	s_mov_b32 m0, s28
	s_nop 0
	global_load_lds_dwordx4 v132, s[26:27]
	s_add_i32 m0, s28, 0x2000
	s_nop 0
	global_load_lds_dwordx4 v128, s[26:27]
	s_mov_b32 m0, s45
	s_nop 0
	global_load_lds_dwordx4 v221, s[100:101]
	s_mov_b32 m0, s46
	s_nop 0
	global_load_lds_dwordx4 v205, s[100:101]
	s_waitcnt vmcnt(8)
	s_waitcnt lgkmcnt(0)
	s_barrier
	s_waitcnt lgkmcnt(0)
	v_mfma_f32_16x16x32_bf16 v[60:63], v[144:147], v[184:187], v[60:63]
	v_mfma_f32_16x16x32_bf16 v[56:59], v[160:163], v[184:187], v[56:59]
	v_mfma_f32_16x16x32_bf16 v[44:47], v[144:147], v[192:195], v[44:47]
	v_mfma_f32_16x16x32_bf16 v[40:43], v[160:163], v[192:195], v[40:43]
	v_mfma_f32_16x16x32_bf16 v[28:31], v[144:147], v[200:203], v[28:31]
	v_mfma_f32_16x16x32_bf16 v[24:27], v[160:163], v[200:203], v[24:27]
	v_mfma_f32_16x16x32_bf16 v[12:15], v[144:147], v[212:215], v[12:15]
	v_mfma_f32_16x16x32_bf16 v[8:11], v[160:163], v[212:215], v[8:11]
	v_mfma_f32_16x16x32_bf16 v[60:63], v[156:159], v[188:191], v[60:63]
	v_mfma_f32_16x16x32_bf16 v[56:59], v[164:167], v[188:191], v[56:59]
	v_mfma_f32_16x16x32_bf16 v[44:47], v[156:159], v[196:199], v[44:47]
	v_mfma_f32_16x16x32_bf16 v[40:43], v[164:167], v[196:199], v[40:43]
	v_mfma_f32_16x16x32_bf16 v[28:31], v[156:159], v[208:211], v[28:31]
	v_mfma_f32_16x16x32_bf16 v[24:27], v[164:167], v[208:211], v[24:27]
	v_mfma_f32_16x16x32_bf16 v[12:15], v[156:159], v[216:219], v[12:15]
	v_mfma_f32_16x16x32_bf16 v[8:11], v[164:167], v[216:219], v[8:11]
	v_mfma_f32_16x16x32_bf16 v[52:55], v[168:171], v[184:187], v[52:55]
	v_mfma_f32_16x16x32_bf16 v[48:51], v[176:179], v[184:187], v[48:51]
	v_mfma_f32_16x16x32_bf16 v[36:39], v[168:171], v[192:195], v[36:39]
	v_mfma_f32_16x16x32_bf16 v[32:35], v[176:179], v[192:195], v[32:35]
	v_mfma_f32_16x16x32_bf16 v[20:23], v[168:171], v[200:203], v[20:23]
	v_mfma_f32_16x16x32_bf16 v[16:19], v[176:179], v[200:203], v[16:19]
	v_mfma_f32_16x16x32_bf16 v[4:7], v[168:171], v[212:215], v[4:7]
	v_mfma_f32_16x16x32_bf16 v[0:3], v[176:179], v[212:215], v[0:3]
	v_mfma_f32_16x16x32_bf16 v[52:55], v[172:175], v[188:191], v[52:55]
	v_mfma_f32_16x16x32_bf16 v[48:51], v[180:183], v[188:191], v[48:51]
	v_mfma_f32_16x16x32_bf16 v[36:39], v[172:175], v[196:199], v[36:39]
	v_mfma_f32_16x16x32_bf16 v[32:35], v[180:183], v[196:199], v[32:35]
	v_mfma_f32_16x16x32_bf16 v[20:23], v[172:175], v[208:211], v[20:23]
	v_mfma_f32_16x16x32_bf16 v[16:19], v[180:183], v[208:211], v[16:19]
	v_mfma_f32_16x16x32_bf16 v[4:7], v[172:175], v[216:219], v[4:7]
	v_mfma_f32_16x16x32_bf16 v[0:3], v[180:183], v[216:219], v[0:3]
	s_barrier
	s_add_i32 s55, s55, 2
	s_add_u32 s53, s53, 0x100
	s_addc_u32 s54, s54, 0
	s_add_u32 s24, s24, 0x100
	s_addc_u32 s25, s25, 0
	s_cmp_gt_u32 s55, 13
	s_cbranch_scc0 .LBB0_163
	s_and_b64 vcc, exec, s[14:15]
	s_cbranch_vccz .LBB0_166
	s_barrier

.LBB0_605:
	s_ashr_i32 s21, s20, 31
	s_lshl_b64 s[22:23], s[20:21], 19
	s_add_u32 s22, s39, s22
	s_addc_u32 s23, s40, s23
	s_and_b64 s[24:25], s[6:7], exec
	s_cselect_b32 s21, s23, s29
	s_cselect_b32 s27, s22, s28
	s_ashr_i32 s19, s18, 31
	s_lshl_b64 s[24:25], s[18:19], 19
	s_add_u32 s24, s41, s24
	s_addc_u32 s25, s42, s25
	s_and_b64 s[34:35], s[6:7], exec
	s_cselect_b32 s19, s25, s31
	s_cselect_b32 s55, s24, s30
	s_add_u32 s56, s30, 0x100
	v_mov_b32_e32 v0, 0
	s_addc_u32 s57, s31, 0
	s_mov_b32 s58, -2
	v_mov_b32_e32 v1, v0
	v_mov_b32_e32 v2, v0
	v_mov_b32_e32 v3, v0
	v_mov_b32_e32 v4, v0
	v_mov_b32_e32 v5, v0
	v_mov_b32_e32 v6, v0
	v_mov_b32_e32 v7, v0
	v_mov_b32_e32 v16, v0
	v_mov_b32_e32 v17, v0
	v_mov_b32_e32 v18, v0
	v_mov_b32_e32 v19, v0
	v_mov_b32_e32 v20, v0
	v_mov_b32_e32 v21, v0
	v_mov_b32_e32 v22, v0
	v_mov_b32_e32 v23, v0
	v_mov_b32_e32 v32, v0
	v_mov_b32_e32 v33, v0
	v_mov_b32_e32 v34, v0
	v_mov_b32_e32 v35, v0
	v_mov_b32_e32 v36, v0
	v_mov_b32_e32 v37, v0
	v_mov_b32_e32 v38, v0
	v_mov_b32_e32 v39, v0
	v_mov_b32_e32 v48, v0
	v_mov_b32_e32 v49, v0
	v_mov_b32_e32 v50, v0
	v_mov_b32_e32 v51, v0
	v_mov_b32_e32 v52, v0
	v_mov_b32_e32 v53, v0
	v_mov_b32_e32 v54, v0
	v_mov_b32_e32 v55, v0
	v_mov_b32_e32 v8, v0
	v_mov_b32_e32 v9, v0
	v_mov_b32_e32 v10, v0
	v_mov_b32_e32 v11, v0
	v_mov_b32_e32 v12, v0
	v_mov_b32_e32 v13, v0
	v_mov_b32_e32 v14, v0
	v_mov_b32_e32 v15, v0
	v_mov_b32_e32 v24, v0
	v_mov_b32_e32 v25, v0
	v_mov_b32_e32 v26, v0
	v_mov_b32_e32 v27, v0
	v_mov_b32_e32 v28, v0
	v_mov_b32_e32 v29, v0
	v_mov_b32_e32 v30, v0
	v_mov_b32_e32 v31, v0
	v_mov_b32_e32 v40, v0
	v_mov_b32_e32 v41, v0
	v_mov_b32_e32 v42, v0
	v_mov_b32_e32 v43, v0
	v_mov_b32_e32 v44, v0
	v_mov_b32_e32 v45, v0
	v_mov_b32_e32 v46, v0
	v_mov_b32_e32 v47, v0
	v_mov_b32_e32 v56, v0
	v_mov_b32_e32 v57, v0
	v_mov_b32_e32 v58, v0
	v_mov_b32_e32 v59, v0
	v_mov_b32_e32 v60, v0
	v_mov_b32_e32 v61, v0
	v_mov_b32_e32 v62, v0
	v_mov_b32_e32 v63, v0
	v_mov_b32_e32 v64, v0
	v_mov_b32_e32 v65, v0
	v_mov_b32_e32 v66, v0
	v_mov_b32_e32 v67, v0
	v_mov_b32_e32 v68, v0
	v_mov_b32_e32 v69, v0
	v_mov_b32_e32 v70, v0
	v_mov_b32_e32 v71, v0
	v_mov_b32_e32 v80, v0
	v_mov_b32_e32 v81, v0
	v_mov_b32_e32 v82, v0
	v_mov_b32_e32 v83, v0
	v_mov_b32_e32 v84, v0
	v_mov_b32_e32 v85, v0
	v_mov_b32_e32 v86, v0
	v_mov_b32_e32 v87, v0
	v_mov_b32_e32 v96, v0
	v_mov_b32_e32 v97, v0
	v_mov_b32_e32 v98, v0
	v_mov_b32_e32 v99, v0
	v_mov_b32_e32 v100, v0
	v_mov_b32_e32 v101, v0
	v_mov_b32_e32 v102, v0
	v_mov_b32_e32 v103, v0
	v_mov_b32_e32 v112, v0
	v_mov_b32_e32 v113, v0
	v_mov_b32_e32 v114, v0
	v_mov_b32_e32 v115, v0
	v_mov_b32_e32 v116, v0
	v_mov_b32_e32 v117, v0
	v_mov_b32_e32 v118, v0
	v_mov_b32_e32 v119, v0
	v_mov_b32_e32 v72, v0
	v_mov_b32_e32 v73, v0
	v_mov_b32_e32 v74, v0
	v_mov_b32_e32 v75, v0
	v_mov_b32_e32 v76, v0
	v_mov_b32_e32 v77, v0
	v_mov_b32_e32 v78, v0
	v_mov_b32_e32 v79, v0
	v_mov_b32_e32 v88, v0
	v_mov_b32_e32 v89, v0
	v_mov_b32_e32 v90, v0
	v_mov_b32_e32 v91, v0
	v_mov_b32_e32 v92, v0
	v_mov_b32_e32 v93, v0
	v_mov_b32_e32 v94, v0
	v_mov_b32_e32 v95, v0
	v_mov_b32_e32 v104, v0
	v_mov_b32_e32 v105, v0
	v_mov_b32_e32 v106, v0
	v_mov_b32_e32 v107, v0
	v_mov_b32_e32 v108, v0
	v_mov_b32_e32 v109, v0
	v_mov_b32_e32 v110, v0
	v_mov_b32_e32 v111, v0
	v_mov_b32_e32 v120, v0
	v_mov_b32_e32 v121, v0
	v_mov_b32_e32 v122, v0
	v_mov_b32_e32 v123, v0
	v_mov_b32_e32 v124, v0
	v_mov_b32_e32 v125, v0
	v_mov_b32_e32 v126, v0
	v_mov_b32_e32 v127, v0
	v_add_u32_e32 v212, 0x80, v128
	v_add_u32_e32 v213, 0x80, v130
.LBB0_606:
	ds_read_b128 v[140:143], v147
	ds_read_b128 v[150:153], v147 offset:1024
	ds_read_b128 v[154:157], v147 offset:2048
	ds_read_b128 v[158:161], v147 offset:3072
	ds_read_b128 v[162:165], v148
	ds_read_b128 v[166:169], v148 offset:1024
	ds_read_b128 v[170:173], v148 offset:2048
	ds_read_b128 v[174:177], v148 offset:3072
	s_add_u32 s30, s28, 0x100
	s_addc_u32 s31, s29, 0
	s_cmp_eq_u32 s58, 12
	s_cselect_b32 s37, s21, s31
	s_cselect_b32 s36, s27, s30
	s_cselect_b32 s35, s19, s57
	s_cselect_b32 s34, s55, s56
	s_add_i32 m0, s44, 0xc000
	ds_read_b128 v[178:181], v149
	ds_read_b128 v[182:185], v149 offset:1024
	ds_read_b128 v[186:189], v149 offset:2048
	ds_read_b128 v[190:193], v149 offset:3072
	ds_read_b128 v[194:197], v149 offset:4096
	ds_read_b128 v[198:201], v149 offset:5120
	ds_read_b128 v[202:205], v149 offset:6144
	ds_read_b128 v[208:211], v149 offset:7168
	global_load_lds_dwordx4 v134, s[28:29]
	s_add_i32 m0, s44, 0xe000
	s_nop 0
	global_load_lds_dwordx4 v132, s[28:29]
	s_waitcnt vmcnt(8)
	s_waitcnt lgkmcnt(0)
	s_barrier
	s_waitcnt lgkmcnt(0)
	v_mfma_f32_16x16x32_bf16 v[124:127], v[140:143], v[178:181], v[124:127]
	v_mfma_f32_16x16x32_bf16 v[120:123], v[154:157], v[178:181], v[120:123]
	v_mfma_f32_16x16x32_bf16 v[108:111], v[140:143], v[186:189], v[108:111]
	v_mfma_f32_16x16x32_bf16 v[104:107], v[154:157], v[186:189], v[104:107]
	v_mfma_f32_16x16x32_bf16 v[92:95], v[140:143], v[194:197], v[92:95]
	v_mfma_f32_16x16x32_bf16 v[88:91], v[154:157], v[194:197], v[88:91]
	v_mfma_f32_16x16x32_bf16 v[76:79], v[140:143], v[202:205], v[76:79]
	v_mfma_f32_16x16x32_bf16 v[72:75], v[154:157], v[202:205], v[72:75]
	v_mfma_f32_16x16x32_bf16 v[124:127], v[150:153], v[182:185], v[124:127]
	v_mfma_f32_16x16x32_bf16 v[120:123], v[158:161], v[182:185], v[120:123]
	v_mfma_f32_16x16x32_bf16 v[108:111], v[150:153], v[190:193], v[108:111]
	v_mfma_f32_16x16x32_bf16 v[104:107], v[158:161], v[190:193], v[104:107]
	v_mfma_f32_16x16x32_bf16 v[92:95], v[150:153], v[198:201], v[92:95]
	v_mfma_f32_16x16x32_bf16 v[88:91], v[158:161], v[198:201], v[88:91]
	v_mfma_f32_16x16x32_bf16 v[76:79], v[150:153], v[208:211], v[76:79]
	v_mfma_f32_16x16x32_bf16 v[72:75], v[158:161], v[208:211], v[72:75]
	v_mfma_f32_16x16x32_bf16 v[116:119], v[162:165], v[178:181], v[116:119]
	v_mfma_f32_16x16x32_bf16 v[112:115], v[170:173], v[178:181], v[112:115]
	v_mfma_f32_16x16x32_bf16 v[100:103], v[162:165], v[186:189], v[100:103]
	v_mfma_f32_16x16x32_bf16 v[96:99], v[170:173], v[186:189], v[96:99]
	v_mfma_f32_16x16x32_bf16 v[84:87], v[162:165], v[194:197], v[84:87]
	v_mfma_f32_16x16x32_bf16 v[80:83], v[170:173], v[194:197], v[80:83]
	v_mfma_f32_16x16x32_bf16 v[68:71], v[162:165], v[202:205], v[68:71]
	v_mfma_f32_16x16x32_bf16 v[64:67], v[170:173], v[202:205], v[64:67]
	v_mfma_f32_16x16x32_bf16 v[116:119], v[166:169], v[182:185], v[116:119]
	v_mfma_f32_16x16x32_bf16 v[112:115], v[174:177], v[182:185], v[112:115]
	v_mfma_f32_16x16x32_bf16 v[100:103], v[166:169], v[190:193], v[100:103]
	v_mfma_f32_16x16x32_bf16 v[96:99], v[174:177], v[190:193], v[96:99]
	v_mfma_f32_16x16x32_bf16 v[84:87], v[166:169], v[198:201], v[84:87]
	v_mfma_f32_16x16x32_bf16 v[80:83], v[174:177], v[198:201], v[80:83]
	v_mfma_f32_16x16x32_bf16 v[68:71], v[166:169], v[208:211], v[68:71]
	v_mfma_f32_16x16x32_bf16 v[64:67], v[174:177], v[208:211], v[64:67]
	s_barrier
	s_add_i32 s28, s52, s43
	s_mov_b32 m0, s28
	ds_read_b128 v[178:181], v149 offset:16384
	ds_read_b128 v[182:185], v149 offset:17408
	ds_read_b128 v[186:189], v149 offset:18432
	ds_read_b128 v[190:193], v149 offset:19456
	ds_read_b128 v[194:197], v149 offset:20480
	ds_read_b128 v[198:201], v149 offset:21504
	ds_read_b128 v[202:205], v149 offset:22528
	ds_read_b128 v[208:211], v149 offset:23552
	global_load_lds_dwordx4 v128, s[34:35]
	s_add_i32 m0, s28, 0x2000
	s_add_u32 s28, s34, 0x40000
	s_mov_b64 s[98:99], s[34:35]
	s_addc_u32 s29, s35, 0
	s_add_i32 s59, s53, s43
	global_load_lds_dwordx4 v130, s[34:35]
	s_mov_b32 m0, s59
	s_nop 0
	global_load_lds_dwordx4 v128, s[28:29]
	s_add_i32 m0, s59, 0x2000
	s_nop 0
	global_load_lds_dwordx4 v130, s[28:29]
	s_mov_b32 m0, s44
	s_nop 0
	global_load_lds_dwordx4 v128, s[36:37]
	s_mov_b32 m0, s45
	s_nop 0
	global_load_lds_dwordx4 v130, s[36:37]
	s_waitcnt vmcnt(8)
	s_waitcnt lgkmcnt(0)
	s_barrier
	s_waitcnt lgkmcnt(0)
	v_mfma_f32_16x16x32_bf16 v[60:63], v[140:143], v[178:181], v[60:63]
	v_mfma_f32_16x16x32_bf16 v[56:59], v[154:157], v[178:181], v[56:59]
	v_mfma_f32_16x16x32_bf16 v[44:47], v[140:143], v[186:189], v[44:47]
	v_mfma_f32_16x16x32_bf16 v[40:43], v[154:157], v[186:189], v[40:43]
	v_mfma_f32_16x16x32_bf16 v[28:31], v[140:143], v[194:197], v[28:31]
	v_mfma_f32_16x16x32_bf16 v[24:27], v[154:157], v[194:197], v[24:27]
	v_mfma_f32_16x16x32_bf16 v[12:15], v[140:143], v[202:205], v[12:15]
	v_mfma_f32_16x16x32_bf16 v[8:11], v[154:157], v[202:205], v[8:11]
	v_mfma_f32_16x16x32_bf16 v[60:63], v[150:153], v[182:185], v[60:63]
	v_mfma_f32_16x16x32_bf16 v[56:59], v[158:161], v[182:185], v[56:59]
	v_mfma_f32_16x16x32_bf16 v[44:47], v[150:153], v[190:193], v[44:47]
	v_mfma_f32_16x16x32_bf16 v[40:43], v[158:161], v[190:193], v[40:43]
	v_mfma_f32_16x16x32_bf16 v[28:31], v[150:153], v[198:201], v[28:31]
	v_mfma_f32_16x16x32_bf16 v[24:27], v[158:161], v[198:201], v[24:27]
	v_mfma_f32_16x16x32_bf16 v[12:15], v[150:153], v[208:211], v[12:15]
	v_mfma_f32_16x16x32_bf16 v[8:11], v[158:161], v[208:211], v[8:11]
	v_mfma_f32_16x16x32_bf16 v[52:55], v[162:165], v[178:181], v[52:55]
	v_mfma_f32_16x16x32_bf16 v[48:51], v[170:173], v[178:181], v[48:51]
	v_mfma_f32_16x16x32_bf16 v[36:39], v[162:165], v[186:189], v[36:39]
	v_mfma_f32_16x16x32_bf16 v[32:35], v[170:173], v[186:189], v[32:35]
	v_mfma_f32_16x16x32_bf16 v[20:23], v[162:165], v[194:197], v[20:23]
	v_mfma_f32_16x16x32_bf16 v[16:19], v[170:173], v[194:197], v[16:19]
	v_mfma_f32_16x16x32_bf16 v[4:7], v[162:165], v[202:205], v[4:7]
	v_mfma_f32_16x16x32_bf16 v[0:3], v[170:173], v[202:205], v[0:3]
	v_mfma_f32_16x16x32_bf16 v[52:55], v[166:169], v[182:185], v[52:55]
	v_mfma_f32_16x16x32_bf16 v[48:51], v[174:177], v[182:185], v[48:51]
	v_mfma_f32_16x16x32_bf16 v[36:39], v[166:169], v[190:193], v[36:39]
	v_mfma_f32_16x16x32_bf16 v[32:35], v[174:177], v[190:193], v[32:35]
	v_mfma_f32_16x16x32_bf16 v[20:23], v[166:169], v[198:201], v[20:23]
	v_mfma_f32_16x16x32_bf16 v[16:19], v[174:177], v[198:201], v[16:19]
	v_mfma_f32_16x16x32_bf16 v[4:7], v[166:169], v[208:211], v[4:7]
	v_mfma_f32_16x16x32_bf16 v[0:3], v[174:177], v[208:211], v[0:3]
	s_barrier
	s_add_i32 s59, 0, 0x18000
	s_add_i32 s60, 0, 0x1c000
	v_add_u32_e32 v158, s59, v145
	v_add_u32_e32 v174, s60, v145
	ds_read_b128 v[140:143], v158
	ds_read_b128 v[150:153], v158 offset:1024
	ds_read_b128 v[154:157], v158 offset:2048
	ds_read_b128 v[158:161], v158 offset:3072
	ds_read_b128 v[162:165], v174
	ds_read_b128 v[166:169], v174 offset:1024
	ds_read_b128 v[170:173], v174 offset:2048
	ds_read_b128 v[174:177], v174 offset:3072
	s_add_u32 s28, s36, 0x40000
	s_addc_u32 s29, s37, 0
	s_mov_b32 m0, s46
	ds_read_b128 v[178:181], v149 offset:32768
	ds_read_b128 v[182:185], v149 offset:33792
	ds_read_b128 v[186:189], v149 offset:34816
	ds_read_b128 v[190:193], v149 offset:35840
	ds_read_b128 v[194:197], v149 offset:36864
	ds_read_b128 v[198:201], v149 offset:37888
	ds_read_b128 v[202:205], v149 offset:38912
	ds_read_b128 v[208:211], v149 offset:39936
	global_load_lds_dwordx4 v128, s[28:29]
	s_mov_b32 m0, s47
	s_nop 0
	global_load_lds_dwordx4 v130, s[28:29]
	s_waitcnt vmcnt(8)
	s_waitcnt lgkmcnt(0)
	s_barrier
	s_waitcnt lgkmcnt(0)
	v_mfma_f32_16x16x32_bf16 v[124:127], v[140:143], v[178:181], v[124:127]
	v_mfma_f32_16x16x32_bf16 v[120:123], v[154:157], v[178:181], v[120:123]
	v_mfma_f32_16x16x32_bf16 v[108:111], v[140:143], v[186:189], v[108:111]
	v_mfma_f32_16x16x32_bf16 v[104:107], v[154:157], v[186:189], v[104:107]
	v_mfma_f32_16x16x32_bf16 v[92:95], v[140:143], v[194:197], v[92:95]
	v_mfma_f32_16x16x32_bf16 v[88:91], v[154:157], v[194:197], v[88:91]
	v_mfma_f32_16x16x32_bf16 v[76:79], v[140:143], v[202:205], v[76:79]
	v_mfma_f32_16x16x32_bf16 v[72:75], v[154:157], v[202:205], v[72:75]
	v_mfma_f32_16x16x32_bf16 v[124:127], v[150:153], v[182:185], v[124:127]
	v_mfma_f32_16x16x32_bf16 v[120:123], v[158:161], v[182:185], v[120:123]
	v_mfma_f32_16x16x32_bf16 v[108:111], v[150:153], v[190:193], v[108:111]
	v_mfma_f32_16x16x32_bf16 v[104:107], v[158:161], v[190:193], v[104:107]
	v_mfma_f32_16x16x32_bf16 v[92:95], v[150:153], v[198:201], v[92:95]
	v_mfma_f32_16x16x32_bf16 v[88:91], v[158:161], v[198:201], v[88:91]
	v_mfma_f32_16x16x32_bf16 v[76:79], v[150:153], v[208:211], v[76:79]
	v_mfma_f32_16x16x32_bf16 v[72:75], v[158:161], v[208:211], v[72:75]
	v_mfma_f32_16x16x32_bf16 v[116:119], v[162:165], v[178:181], v[116:119]
	v_mfma_f32_16x16x32_bf16 v[112:115], v[170:173], v[178:181], v[112:115]
	v_mfma_f32_16x16x32_bf16 v[100:103], v[162:165], v[186:189], v[100:103]
	v_mfma_f32_16x16x32_bf16 v[96:99], v[170:173], v[186:189], v[96:99]
	v_mfma_f32_16x16x32_bf16 v[84:87], v[162:165], v[194:197], v[84:87]
	v_mfma_f32_16x16x32_bf16 v[80:83], v[170:173], v[194:197], v[80:83]
	v_mfma_f32_16x16x32_bf16 v[68:71], v[162:165], v[202:205], v[68:71]
	v_mfma_f32_16x16x32_bf16 v[64:67], v[170:173], v[202:205], v[64:67]
	v_mfma_f32_16x16x32_bf16 v[116:119], v[166:169], v[182:185], v[116:119]
	v_mfma_f32_16x16x32_bf16 v[112:115], v[174:177], v[182:185], v[112:115]
	v_mfma_f32_16x16x32_bf16 v[100:103], v[166:169], v[190:193], v[100:103]
	v_mfma_f32_16x16x32_bf16 v[96:99], v[174:177], v[190:193], v[96:99]
	v_mfma_f32_16x16x32_bf16 v[84:87], v[166:169], v[198:201], v[84:87]
	v_mfma_f32_16x16x32_bf16 v[80:83], v[174:177], v[198:201], v[80:83]
	v_mfma_f32_16x16x32_bf16 v[68:71], v[166:169], v[208:211], v[68:71]
	v_mfma_f32_16x16x32_bf16 v[64:67], v[174:177], v[208:211], v[64:67]
	s_barrier
	s_add_i32 s28, s59, s43
	s_mov_b32 m0, s28
	ds_read_b128 v[178:181], v149 offset:49152
	ds_read_b128 v[182:185], v149 offset:50176
	ds_read_b128 v[186:189], v149 offset:51200
	ds_read_b128 v[190:193], v149 offset:52224
	ds_read_b128 v[194:197], v149 offset:53248
	ds_read_b128 v[198:201], v149 offset:54272
	ds_read_b128 v[202:205], v149 offset:55296
	ds_read_b128 v[208:211], v149 offset:56320
	global_load_lds_dwordx4 v212, s[34:35]
	s_add_i32 m0, s28, 0x2000
	s_add_u32 s28, s34, 0x40080
	s_addc_u32 s29, s35, 0
	s_add_i32 s34, s60, s43
	global_load_lds_dwordx4 v213, s[98:99]
	s_mov_b32 m0, s34
	s_nop 0
	global_load_lds_dwordx4 v128, s[28:29]
	s_add_i32 m0, s34, 0x2000
	s_nop 0
	global_load_lds_dwordx4 v130, s[28:29]
	s_mov_b32 m0, s49
	s_nop 0
	global_load_lds_dwordx4 v212, s[36:37]
	s_mov_b32 m0, s50
	s_nop 0
	global_load_lds_dwordx4 v213, s[36:37]
	s_waitcnt vmcnt(8)
	s_waitcnt lgkmcnt(0)
	s_barrier
	s_waitcnt lgkmcnt(0)
	v_mfma_f32_16x16x32_bf16 v[60:63], v[140:143], v[178:181], v[60:63]
	v_mfma_f32_16x16x32_bf16 v[56:59], v[154:157], v[178:181], v[56:59]
	v_mfma_f32_16x16x32_bf16 v[44:47], v[140:143], v[186:189], v[44:47]
	v_mfma_f32_16x16x32_bf16 v[40:43], v[154:157], v[186:189], v[40:43]
	v_mfma_f32_16x16x32_bf16 v[28:31], v[140:143], v[194:197], v[28:31]
	v_mfma_f32_16x16x32_bf16 v[24:27], v[154:157], v[194:197], v[24:27]
	v_mfma_f32_16x16x32_bf16 v[12:15], v[140:143], v[202:205], v[12:15]
	v_mfma_f32_16x16x32_bf16 v[8:11], v[154:157], v[202:205], v[8:11]
	v_mfma_f32_16x16x32_bf16 v[60:63], v[150:153], v[182:185], v[60:63]
	v_mfma_f32_16x16x32_bf16 v[56:59], v[158:161], v[182:185], v[56:59]
	v_mfma_f32_16x16x32_bf16 v[44:47], v[150:153], v[190:193], v[44:47]
	v_mfma_f32_16x16x32_bf16 v[40:43], v[158:161], v[190:193], v[40:43]
	v_mfma_f32_16x16x32_bf16 v[28:31], v[150:153], v[198:201], v[28:31]
	v_mfma_f32_16x16x32_bf16 v[24:27], v[158:161], v[198:201], v[24:27]
	v_mfma_f32_16x16x32_bf16 v[12:15], v[150:153], v[208:211], v[12:15]
	v_mfma_f32_16x16x32_bf16 v[8:11], v[158:161], v[208:211], v[8:11]
	v_mfma_f32_16x16x32_bf16 v[52:55], v[162:165], v[178:181], v[52:55]
	v_mfma_f32_16x16x32_bf16 v[48:51], v[170:173], v[178:181], v[48:51]
	v_mfma_f32_16x16x32_bf16 v[36:39], v[162:165], v[186:189], v[36:39]
	v_mfma_f32_16x16x32_bf16 v[32:35], v[170:173], v[186:189], v[32:35]
	v_mfma_f32_16x16x32_bf16 v[20:23], v[162:165], v[194:197], v[20:23]
	v_mfma_f32_16x16x32_bf16 v[16:19], v[170:173], v[194:197], v[16:19]
	v_mfma_f32_16x16x32_bf16 v[4:7], v[162:165], v[202:205], v[4:7]
	v_mfma_f32_16x16x32_bf16 v[0:3], v[170:173], v[202:205], v[0:3]
	v_mfma_f32_16x16x32_bf16 v[52:55], v[166:169], v[182:185], v[52:55]
	v_mfma_f32_16x16x32_bf16 v[48:51], v[174:177], v[182:185], v[48:51]
	v_mfma_f32_16x16x32_bf16 v[36:39], v[166:169], v[190:193], v[36:39]
	v_mfma_f32_16x16x32_bf16 v[32:35], v[174:177], v[190:193], v[32:35]
	v_mfma_f32_16x16x32_bf16 v[20:23], v[166:169], v[198:201], v[20:23]
	v_mfma_f32_16x16x32_bf16 v[16:19], v[174:177], v[198:201], v[16:19]
	v_mfma_f32_16x16x32_bf16 v[4:7], v[166:169], v[208:211], v[4:7]
	v_mfma_f32_16x16x32_bf16 v[0:3], v[174:177], v[208:211], v[0:3]
	s_barrier
	s_add_i32 s58, s58, 2
	s_add_u32 s56, s56, 0x100
	s_addc_u32 s57, s57, 0
	s_cmp_gt_u32 s58, 13
	s_mov_b64 s[28:29], s[30:31]
	s_cbranch_scc0 .LBB0_606
	s_and_b64 vcc, exec, s[16:17]
	s_cbranch_vccz .LBB0_609
	s_barrier

.LBB0_698:
	s_ashr_i32 s21, s20, 31
	s_lshl_b64 s[22:23], s[20:21], 19
	s_add_u32 s22, s8, s22
	s_addc_u32 s23, s9, s23
	s_and_b64 s[24:25], s[4:5], exec
	s_cselect_b32 s21, s23, s29
	s_cselect_b32 s49, s22, s28
	s_ashr_i32 s19, s18, 31
	s_lshl_b64 s[24:25], s[18:19], 19
	s_add_u32 s24, s36, s24
	s_addc_u32 s25, s37, s25
	s_and_b64 s[30:31], s[4:5], exec
	s_cselect_b32 s19, s25, s27
	s_cselect_b32 s50, s24, s26
	s_add_u32 s51, s26, 0x100
	s_addc_u32 s52, s27, 0
	s_add_u32 s26, s28, 0x40080
	v_mov_b32_e32 v0, 0
	s_addc_u32 s27, s29, 0
	s_mov_b32 s53, -2
	v_mov_b32_e32 v1, v0
	v_mov_b32_e32 v2, v0
	v_mov_b32_e32 v3, v0
	v_mov_b32_e32 v4, v0
	v_mov_b32_e32 v5, v0
	v_mov_b32_e32 v6, v0
	v_mov_b32_e32 v7, v0
	v_mov_b32_e32 v16, v0
	v_mov_b32_e32 v17, v0
	v_mov_b32_e32 v18, v0
	v_mov_b32_e32 v19, v0
	v_mov_b32_e32 v20, v0
	v_mov_b32_e32 v21, v0
	v_mov_b32_e32 v22, v0
	v_mov_b32_e32 v23, v0
	v_mov_b32_e32 v32, v0
	v_mov_b32_e32 v33, v0
	v_mov_b32_e32 v34, v0
	v_mov_b32_e32 v35, v0
	v_mov_b32_e32 v36, v0
	v_mov_b32_e32 v37, v0
	v_mov_b32_e32 v38, v0
	v_mov_b32_e32 v39, v0
	v_mov_b32_e32 v48, v0
	v_mov_b32_e32 v49, v0
	v_mov_b32_e32 v50, v0
	v_mov_b32_e32 v51, v0
	v_mov_b32_e32 v52, v0
	v_mov_b32_e32 v53, v0
	v_mov_b32_e32 v54, v0
	v_mov_b32_e32 v55, v0
	v_mov_b32_e32 v8, v0
	v_mov_b32_e32 v9, v0
	v_mov_b32_e32 v10, v0
	v_mov_b32_e32 v11, v0
	v_mov_b32_e32 v12, v0
	v_mov_b32_e32 v13, v0
	v_mov_b32_e32 v14, v0
	v_mov_b32_e32 v15, v0
	v_mov_b32_e32 v24, v0
	v_mov_b32_e32 v25, v0
	v_mov_b32_e32 v26, v0
	v_mov_b32_e32 v27, v0
	v_mov_b32_e32 v28, v0
	v_mov_b32_e32 v29, v0
	v_mov_b32_e32 v30, v0
	v_mov_b32_e32 v31, v0
	v_mov_b32_e32 v40, v0
	v_mov_b32_e32 v41, v0
	v_mov_b32_e32 v42, v0
	v_mov_b32_e32 v43, v0
	v_mov_b32_e32 v44, v0
	v_mov_b32_e32 v45, v0
	v_mov_b32_e32 v46, v0
	v_mov_b32_e32 v47, v0
	v_mov_b32_e32 v56, v0
	v_mov_b32_e32 v57, v0
	v_mov_b32_e32 v58, v0
	v_mov_b32_e32 v59, v0
	v_mov_b32_e32 v60, v0
	v_mov_b32_e32 v61, v0
	v_mov_b32_e32 v62, v0
	v_mov_b32_e32 v63, v0
	v_mov_b32_e32 v64, v0
	v_mov_b32_e32 v65, v0
	v_mov_b32_e32 v66, v0
	v_mov_b32_e32 v67, v0
	v_mov_b32_e32 v68, v0
	v_mov_b32_e32 v69, v0
	v_mov_b32_e32 v70, v0
	v_mov_b32_e32 v71, v0
	v_mov_b32_e32 v80, v0
	v_mov_b32_e32 v81, v0
	v_mov_b32_e32 v82, v0
	v_mov_b32_e32 v83, v0
	v_mov_b32_e32 v84, v0
	v_mov_b32_e32 v85, v0
	v_mov_b32_e32 v86, v0
	v_mov_b32_e32 v87, v0
	v_mov_b32_e32 v96, v0
	v_mov_b32_e32 v97, v0
	v_mov_b32_e32 v98, v0
	v_mov_b32_e32 v99, v0
	v_mov_b32_e32 v100, v0
	v_mov_b32_e32 v101, v0
	v_mov_b32_e32 v102, v0
	v_mov_b32_e32 v103, v0
	v_mov_b32_e32 v112, v0
	v_mov_b32_e32 v113, v0
	v_mov_b32_e32 v114, v0
	v_mov_b32_e32 v115, v0
	v_mov_b32_e32 v116, v0
	v_mov_b32_e32 v117, v0
	v_mov_b32_e32 v118, v0
	v_mov_b32_e32 v119, v0
	v_mov_b32_e32 v72, v0
	v_mov_b32_e32 v73, v0
	v_mov_b32_e32 v74, v0
	v_mov_b32_e32 v75, v0
	v_mov_b32_e32 v76, v0
	v_mov_b32_e32 v77, v0
	v_mov_b32_e32 v78, v0
	v_mov_b32_e32 v79, v0
	v_mov_b32_e32 v88, v0
	v_mov_b32_e32 v89, v0
	v_mov_b32_e32 v90, v0
	v_mov_b32_e32 v91, v0
	v_mov_b32_e32 v92, v0
	v_mov_b32_e32 v93, v0
	v_mov_b32_e32 v94, v0
	v_mov_b32_e32 v95, v0
	v_mov_b32_e32 v104, v0
	v_mov_b32_e32 v105, v0
	v_mov_b32_e32 v106, v0
	v_mov_b32_e32 v107, v0
	v_mov_b32_e32 v108, v0
	v_mov_b32_e32 v109, v0
	v_mov_b32_e32 v110, v0
	v_mov_b32_e32 v111, v0
	v_mov_b32_e32 v120, v0
	v_mov_b32_e32 v121, v0
	v_mov_b32_e32 v122, v0
	v_mov_b32_e32 v123, v0
	v_mov_b32_e32 v124, v0
	v_mov_b32_e32 v125, v0
	v_mov_b32_e32 v126, v0
	v_mov_b32_e32 v127, v0
	v_add_u32_e32 v204, 0x80, v128
	v_add_u32_e32 v205, 0x80, v130
	v_add_u32_e32 v220, 0x80, v132
	v_add_u32_e32 v221, 0x80, v134
.LBB0_699:
	ds_read_b128 v[144:147], v151
	ds_read_b128 v[156:159], v151 offset:1024
	ds_read_b128 v[160:163], v151 offset:2048
	ds_read_b128 v[164:167], v151 offset:3072
	ds_read_b128 v[168:171], v152
	ds_read_b128 v[172:175], v152 offset:1024
	ds_read_b128 v[176:179], v152 offset:2048
	ds_read_b128 v[180:183], v152 offset:3072
	s_add_u32 s28, s26, 0xfffc0080
	s_addc_u32 s29, s27, -1
	s_cmp_eq_u32 s53, 12
	s_cselect_b32 s31, s21, s29
	s_cselect_b32 s30, s49, s28
	s_cselect_b32 s29, s19, s52
	s_cselect_b32 s28, s50, s51
	s_add_i32 m0, s39, 0xc000
	ds_read_b128 v[184:187], v153
	ds_read_b128 v[188:191], v153 offset:1024
	ds_read_b128 v[192:195], v153 offset:2048
	ds_read_b128 v[196:199], v153 offset:3072
	ds_read_b128 v[200:203], v153 offset:4096
	ds_read_b128 v[208:211], v153 offset:5120
	ds_read_b128 v[212:215], v153 offset:6144
	ds_read_b128 v[216:219], v153 offset:7168
	global_load_lds_dwordx4 v138, s[26:27]
	s_add_i32 m0, s39, 0xe000
	s_nop 0
	global_load_lds_dwordx4 v136, s[26:27]
	s_waitcnt vmcnt(8)
	s_waitcnt lgkmcnt(0)
	s_barrier
	s_waitcnt lgkmcnt(0)
	v_mfma_f32_16x16x32_bf16 v[124:127], v[144:147], v[184:187], v[124:127]
	v_mfma_f32_16x16x32_bf16 v[120:123], v[160:163], v[184:187], v[120:123]
	v_mfma_f32_16x16x32_bf16 v[108:111], v[144:147], v[192:195], v[108:111]
	v_mfma_f32_16x16x32_bf16 v[104:107], v[160:163], v[192:195], v[104:107]
	v_mfma_f32_16x16x32_bf16 v[92:95], v[144:147], v[200:203], v[92:95]
	v_mfma_f32_16x16x32_bf16 v[88:91], v[160:163], v[200:203], v[88:91]
	v_mfma_f32_16x16x32_bf16 v[76:79], v[144:147], v[212:215], v[76:79]
	v_mfma_f32_16x16x32_bf16 v[72:75], v[160:163], v[212:215], v[72:75]
	v_mfma_f32_16x16x32_bf16 v[124:127], v[156:159], v[188:191], v[124:127]
	v_mfma_f32_16x16x32_bf16 v[120:123], v[164:167], v[188:191], v[120:123]
	v_mfma_f32_16x16x32_bf16 v[108:111], v[156:159], v[196:199], v[108:111]
	v_mfma_f32_16x16x32_bf16 v[104:107], v[164:167], v[196:199], v[104:107]
	v_mfma_f32_16x16x32_bf16 v[92:95], v[156:159], v[208:211], v[92:95]
	v_mfma_f32_16x16x32_bf16 v[88:91], v[164:167], v[208:211], v[88:91]
	v_mfma_f32_16x16x32_bf16 v[76:79], v[156:159], v[216:219], v[76:79]
	v_mfma_f32_16x16x32_bf16 v[72:75], v[164:167], v[216:219], v[72:75]
	v_mfma_f32_16x16x32_bf16 v[116:119], v[168:171], v[184:187], v[116:119]
	v_mfma_f32_16x16x32_bf16 v[112:115], v[176:179], v[184:187], v[112:115]
	v_mfma_f32_16x16x32_bf16 v[100:103], v[168:171], v[192:195], v[100:103]
	v_mfma_f32_16x16x32_bf16 v[96:99], v[176:179], v[192:195], v[96:99]
	v_mfma_f32_16x16x32_bf16 v[84:87], v[168:171], v[200:203], v[84:87]
	v_mfma_f32_16x16x32_bf16 v[80:83], v[176:179], v[200:203], v[80:83]
	v_mfma_f32_16x16x32_bf16 v[68:71], v[168:171], v[212:215], v[68:71]
	v_mfma_f32_16x16x32_bf16 v[64:67], v[176:179], v[212:215], v[64:67]
	v_mfma_f32_16x16x32_bf16 v[116:119], v[172:175], v[188:191], v[116:119]
	v_mfma_f32_16x16x32_bf16 v[112:115], v[180:183], v[188:191], v[112:115]
	v_mfma_f32_16x16x32_bf16 v[100:103], v[172:175], v[196:199], v[100:103]
	v_mfma_f32_16x16x32_bf16 v[96:99], v[180:183], v[196:199], v[96:99]
	v_mfma_f32_16x16x32_bf16 v[84:87], v[172:175], v[208:211], v[84:87]
	v_mfma_f32_16x16x32_bf16 v[80:83], v[180:183], v[208:211], v[80:83]
	v_mfma_f32_16x16x32_bf16 v[68:71], v[172:175], v[216:219], v[68:71]
	v_mfma_f32_16x16x32_bf16 v[64:67], v[180:183], v[216:219], v[64:67]
	s_barrier
	s_add_i32 s54, s46, s38
	s_mov_b32 m0, s54
	ds_read_b128 v[184:187], v153 offset:16384
	ds_read_b128 v[188:191], v153 offset:17408
	ds_read_b128 v[192:195], v153 offset:18432
	ds_read_b128 v[196:199], v153 offset:19456
	ds_read_b128 v[200:203], v153 offset:20480
	ds_read_b128 v[208:211], v153 offset:21504
	ds_read_b128 v[212:215], v153 offset:22528
	ds_read_b128 v[216:219], v153 offset:23552
	global_load_lds_dwordx4 v130, s[28:29]
	s_add_i32 m0, s54, 0x2000
	s_add_u32 s54, s28, 0x40000
	s_mov_b64 s[98:99], s[28:29]
	s_addc_u32 s55, s29, 0
	s_add_i32 s56, s47, s38
	global_load_lds_dwordx4 v134, s[28:29]
	s_mov_b32 m0, s56
	s_mov_b64 s[100:101], s[30:31]
	global_load_lds_dwordx4 v130, s[54:55]
	s_add_i32 m0, s56, 0x2000
	s_nop 0
	global_load_lds_dwordx4 v134, s[54:55]
	s_mov_b32 m0, s39
	s_nop 0
	global_load_lds_dwordx4 v128, s[30:31]
	s_mov_b32 m0, s40
	s_nop 0
	global_load_lds_dwordx4 v132, s[30:31]
	s_waitcnt vmcnt(8)
	s_waitcnt lgkmcnt(0)
	s_barrier
	s_waitcnt lgkmcnt(0)
	v_mfma_f32_16x16x32_bf16 v[60:63], v[144:147], v[184:187], v[60:63]
	v_mfma_f32_16x16x32_bf16 v[56:59], v[160:163], v[184:187], v[56:59]
	v_mfma_f32_16x16x32_bf16 v[44:47], v[144:147], v[192:195], v[44:47]
	v_mfma_f32_16x16x32_bf16 v[40:43], v[160:163], v[192:195], v[40:43]
	v_mfma_f32_16x16x32_bf16 v[28:31], v[144:147], v[200:203], v[28:31]
	v_mfma_f32_16x16x32_bf16 v[24:27], v[160:163], v[200:203], v[24:27]
	v_mfma_f32_16x16x32_bf16 v[12:15], v[144:147], v[212:215], v[12:15]
	v_mfma_f32_16x16x32_bf16 v[8:11], v[160:163], v[212:215], v[8:11]
	v_mfma_f32_16x16x32_bf16 v[60:63], v[156:159], v[188:191], v[60:63]
	v_mfma_f32_16x16x32_bf16 v[56:59], v[164:167], v[188:191], v[56:59]
	v_mfma_f32_16x16x32_bf16 v[44:47], v[156:159], v[196:199], v[44:47]
	v_mfma_f32_16x16x32_bf16 v[40:43], v[164:167], v[196:199], v[40:43]
	v_mfma_f32_16x16x32_bf16 v[28:31], v[156:159], v[208:211], v[28:31]
	v_mfma_f32_16x16x32_bf16 v[24:27], v[164:167], v[208:211], v[24:27]
	v_mfma_f32_16x16x32_bf16 v[12:15], v[156:159], v[216:219], v[12:15]
	v_mfma_f32_16x16x32_bf16 v[8:11], v[164:167], v[216:219], v[8:11]
	v_mfma_f32_16x16x32_bf16 v[52:55], v[168:171], v[184:187], v[52:55]
	v_mfma_f32_16x16x32_bf16 v[48:51], v[176:179], v[184:187], v[48:51]
	v_mfma_f32_16x16x32_bf16 v[36:39], v[168:171], v[192:195], v[36:39]
	v_mfma_f32_16x16x32_bf16 v[32:35], v[176:179], v[192:195], v[32:35]
	v_mfma_f32_16x16x32_bf16 v[20:23], v[168:171], v[200:203], v[20:23]
	v_mfma_f32_16x16x32_bf16 v[16:19], v[176:179], v[200:203], v[16:19]
	v_mfma_f32_16x16x32_bf16 v[4:7], v[168:171], v[212:215], v[4:7]
	v_mfma_f32_16x16x32_bf16 v[0:3], v[176:179], v[212:215], v[0:3]
	v_mfma_f32_16x16x32_bf16 v[52:55], v[172:175], v[188:191], v[52:55]
	v_mfma_f32_16x16x32_bf16 v[48:51], v[180:183], v[188:191], v[48:51]
	v_mfma_f32_16x16x32_bf16 v[36:39], v[172:175], v[196:199], v[36:39]
	v_mfma_f32_16x16x32_bf16 v[32:35], v[180:183], v[196:199], v[32:35]
	v_mfma_f32_16x16x32_bf16 v[20:23], v[172:175], v[208:211], v[20:23]
	v_mfma_f32_16x16x32_bf16 v[16:19], v[180:183], v[208:211], v[16:19]
	v_mfma_f32_16x16x32_bf16 v[4:7], v[172:175], v[216:219], v[4:7]
	v_mfma_f32_16x16x32_bf16 v[0:3], v[180:183], v[216:219], v[0:3]
	s_barrier
	s_add_i32 s54, 0, 0x18000
	v_add_u32_e32 v155, s54, v149
	s_add_i32 s55, 0, 0x1c000
	ds_read_b128 v[144:147], v155
	ds_read_b128 v[156:159], v155 offset:1024
	ds_read_b128 v[160:163], v155 offset:2048
	ds_read_b128 v[164:167], v155 offset:3072
	v_add_u32_e32 v155, s55, v149
	ds_read_b128 v[168:171], v155
	ds_read_b128 v[172:175], v155 offset:1024
	ds_read_b128 v[176:179], v155 offset:2048
	ds_read_b128 v[180:183], v155 offset:3072
	s_add_u32 s30, s30, 0x40000
	s_addc_u32 s31, s31, 0
	s_mov_b32 m0, s41
	ds_read_b128 v[184:187], v153 offset:32768
	ds_read_b128 v[188:191], v153 offset:33792
	ds_read_b128 v[192:195], v153 offset:34816
	ds_read_b128 v[196:199], v153 offset:35840
	ds_read_b128 v[200:203], v153 offset:36864
	ds_read_b128 v[208:211], v153 offset:37888
	ds_read_b128 v[212:215], v153 offset:38912
	ds_read_b128 v[216:219], v153 offset:39936
	global_load_lds_dwordx4 v128, s[30:31]
	s_mov_b32 m0, s42
	s_nop 0
	global_load_lds_dwordx4 v132, s[30:31]
	s_waitcnt vmcnt(8)
	s_waitcnt lgkmcnt(0)
	s_barrier
	s_waitcnt lgkmcnt(0)
	v_mfma_f32_16x16x32_bf16 v[124:127], v[144:147], v[184:187], v[124:127]
	v_mfma_f32_16x16x32_bf16 v[120:123], v[160:163], v[184:187], v[120:123]
	v_mfma_f32_16x16x32_bf16 v[108:111], v[144:147], v[192:195], v[108:111]
	v_mfma_f32_16x16x32_bf16 v[104:107], v[160:163], v[192:195], v[104:107]
	v_mfma_f32_16x16x32_bf16 v[92:95], v[144:147], v[200:203], v[92:95]
	v_mfma_f32_16x16x32_bf16 v[88:91], v[160:163], v[200:203], v[88:91]
	v_mfma_f32_16x16x32_bf16 v[76:79], v[144:147], v[212:215], v[76:79]
	v_mfma_f32_16x16x32_bf16 v[72:75], v[160:163], v[212:215], v[72:75]
	v_mfma_f32_16x16x32_bf16 v[124:127], v[156:159], v[188:191], v[124:127]
	v_mfma_f32_16x16x32_bf16 v[120:123], v[164:167], v[188:191], v[120:123]
	v_mfma_f32_16x16x32_bf16 v[108:111], v[156:159], v[196:199], v[108:111]
	v_mfma_f32_16x16x32_bf16 v[104:107], v[164:167], v[196:199], v[104:107]
	v_mfma_f32_16x16x32_bf16 v[92:95], v[156:159], v[208:211], v[92:95]
	v_mfma_f32_16x16x32_bf16 v[88:91], v[164:167], v[208:211], v[88:91]
	v_mfma_f32_16x16x32_bf16 v[76:79], v[156:159], v[216:219], v[76:79]
	v_mfma_f32_16x16x32_bf16 v[72:75], v[164:167], v[216:219], v[72:75]
	v_mfma_f32_16x16x32_bf16 v[116:119], v[168:171], v[184:187], v[116:119]
	v_mfma_f32_16x16x32_bf16 v[112:115], v[176:179], v[184:187], v[112:115]
	v_mfma_f32_16x16x32_bf16 v[100:103], v[168:171], v[192:195], v[100:103]
	v_mfma_f32_16x16x32_bf16 v[96:99], v[176:179], v[192:195], v[96:99]
	v_mfma_f32_16x16x32_bf16 v[84:87], v[168:171], v[200:203], v[84:87]
	v_mfma_f32_16x16x32_bf16 v[80:83], v[176:179], v[200:203], v[80:83]
	v_mfma_f32_16x16x32_bf16 v[68:71], v[168:171], v[212:215], v[68:71]
	v_mfma_f32_16x16x32_bf16 v[64:67], v[176:179], v[212:215], v[64:67]
	v_mfma_f32_16x16x32_bf16 v[116:119], v[172:175], v[188:191], v[116:119]
	v_mfma_f32_16x16x32_bf16 v[112:115], v[180:183], v[188:191], v[112:115]
	v_mfma_f32_16x16x32_bf16 v[100:103], v[172:175], v[196:199], v[100:103]
	v_mfma_f32_16x16x32_bf16 v[96:99], v[180:183], v[196:199], v[96:99]
	v_mfma_f32_16x16x32_bf16 v[84:87], v[172:175], v[208:211], v[84:87]
	v_mfma_f32_16x16x32_bf16 v[80:83], v[180:183], v[208:211], v[80:83]
	v_mfma_f32_16x16x32_bf16 v[68:71], v[172:175], v[216:219], v[68:71]
	v_mfma_f32_16x16x32_bf16 v[64:67], v[180:183], v[216:219], v[64:67]
	s_barrier
	s_add_i32 s30, s54, s38
	s_mov_b32 m0, s30
	ds_read_b128 v[184:187], v153 offset:49152
	ds_read_b128 v[188:191], v153 offset:50176
	ds_read_b128 v[192:195], v153 offset:51200
	ds_read_b128 v[196:199], v153 offset:52224
	ds_read_b128 v[200:203], v153 offset:53248
	ds_read_b128 v[208:211], v153 offset:54272
	ds_read_b128 v[212:215], v153 offset:55296
	ds_read_b128 v[216:219], v153 offset:56320
	global_load_lds_dwordx4 v205, s[28:29]
	s_add_i32 m0, s30, 0x2000
	s_add_u32 s28, s28, 0x40080
	s_addc_u32 s29, s29, 0
	s_add_i32 s30, s55, s38
	global_load_lds_dwordx4 v221, s[98:99]
	s_mov_b32 m0, s30
	s_nop 0
	global_load_lds_dwordx4 v130, s[28:29]
	s_add_i32 m0, s30, 0x2000
	s_nop 0
	global_load_lds_dwordx4 v134, s[28:29]
	s_mov_b32 m0, s44
	s_nop 0
	global_load_lds_dwordx4 v204, s[100:101]
	s_mov_b32 m0, s45
	s_nop 0
	global_load_lds_dwordx4 v220, s[100:101]
	s_waitcnt vmcnt(8)
	s_waitcnt lgkmcnt(0)
	s_barrier
	s_waitcnt lgkmcnt(0)
	v_mfma_f32_16x16x32_bf16 v[60:63], v[144:147], v[184:187], v[60:63]
	v_mfma_f32_16x16x32_bf16 v[56:59], v[160:163], v[184:187], v[56:59]
	v_mfma_f32_16x16x32_bf16 v[44:47], v[144:147], v[192:195], v[44:47]
	v_mfma_f32_16x16x32_bf16 v[40:43], v[160:163], v[192:195], v[40:43]
	v_mfma_f32_16x16x32_bf16 v[28:31], v[144:147], v[200:203], v[28:31]
	v_mfma_f32_16x16x32_bf16 v[24:27], v[160:163], v[200:203], v[24:27]
	v_mfma_f32_16x16x32_bf16 v[12:15], v[144:147], v[212:215], v[12:15]
	v_mfma_f32_16x16x32_bf16 v[8:11], v[160:163], v[212:215], v[8:11]
	v_mfma_f32_16x16x32_bf16 v[60:63], v[156:159], v[188:191], v[60:63]
	v_mfma_f32_16x16x32_bf16 v[56:59], v[164:167], v[188:191], v[56:59]
	v_mfma_f32_16x16x32_bf16 v[44:47], v[156:159], v[196:199], v[44:47]
	v_mfma_f32_16x16x32_bf16 v[40:43], v[164:167], v[196:199], v[40:43]
	v_mfma_f32_16x16x32_bf16 v[28:31], v[156:159], v[208:211], v[28:31]
	v_mfma_f32_16x16x32_bf16 v[24:27], v[164:167], v[208:211], v[24:27]
	v_mfma_f32_16x16x32_bf16 v[12:15], v[156:159], v[216:219], v[12:15]
	v_mfma_f32_16x16x32_bf16 v[8:11], v[164:167], v[216:219], v[8:11]
	v_mfma_f32_16x16x32_bf16 v[52:55], v[168:171], v[184:187], v[52:55]
	v_mfma_f32_16x16x32_bf16 v[48:51], v[176:179], v[184:187], v[48:51]
	v_mfma_f32_16x16x32_bf16 v[36:39], v[168:171], v[192:195], v[36:39]
	v_mfma_f32_16x16x32_bf16 v[32:35], v[176:179], v[192:195], v[32:35]
	v_mfma_f32_16x16x32_bf16 v[20:23], v[168:171], v[200:203], v[20:23]
	v_mfma_f32_16x16x32_bf16 v[16:19], v[176:179], v[200:203], v[16:19]
	v_mfma_f32_16x16x32_bf16 v[4:7], v[168:171], v[212:215], v[4:7]
	v_mfma_f32_16x16x32_bf16 v[0:3], v[176:179], v[212:215], v[0:3]
	v_mfma_f32_16x16x32_bf16 v[52:55], v[172:175], v[188:191], v[52:55]
	v_mfma_f32_16x16x32_bf16 v[48:51], v[180:183], v[188:191], v[48:51]
	v_mfma_f32_16x16x32_bf16 v[36:39], v[172:175], v[196:199], v[36:39]
	v_mfma_f32_16x16x32_bf16 v[32:35], v[180:183], v[196:199], v[32:35]
	v_mfma_f32_16x16x32_bf16 v[20:23], v[172:175], v[208:211], v[20:23]
	v_mfma_f32_16x16x32_bf16 v[16:19], v[180:183], v[208:211], v[16:19]
	v_mfma_f32_16x16x32_bf16 v[4:7], v[172:175], v[216:219], v[4:7]
	v_mfma_f32_16x16x32_bf16 v[0:3], v[180:183], v[216:219], v[0:3]
	s_barrier
	s_add_i32 s53, s53, 2
	s_add_u32 s51, s51, 0x100
	s_addc_u32 s52, s52, 0
	s_add_u32 s26, s26, 0x100
	s_addc_u32 s27, s27, 0
	s_cmp_gt_u32 s53, 13
	s_cbranch_scc0 .LBB0_699
	s_and_b64 vcc, exec, s[16:17]
	s_cbranch_vccz .LBB0_702
	s_barrier

.LBB0_777:
	s_ashr_i32 s21, s20, 31
	s_lshl_b64 s[22:23], s[20:21], 21
	s_add_u32 s22, s39, s22
	s_addc_u32 s23, s40, s23
	s_and_b64 s[24:25], s[6:7], exec
	s_cselect_b32 s21, s23, s29
	s_cselect_b32 s27, s22, s28
	s_ashr_i32 s19, s18, 31
	s_lshl_b64 s[24:25], s[18:19], 21
	s_add_u32 s24, s41, s24
	s_addc_u32 s25, s42, s25
	s_and_b64 s[34:35], s[6:7], exec
	s_cselect_b32 s19, s25, s31
	s_cselect_b32 s55, s24, s30
	s_add_u32 s56, s30, 0x100
	v_mov_b32_e32 v0, 0
	s_addc_u32 s57, s31, 0
	s_mov_b32 s58, -2
	v_mov_b32_e32 v1, v0
	v_mov_b32_e32 v2, v0
	v_mov_b32_e32 v3, v0
	v_mov_b32_e32 v4, v0
	v_mov_b32_e32 v5, v0
	v_mov_b32_e32 v6, v0
	v_mov_b32_e32 v7, v0
	v_mov_b32_e32 v16, v0
	v_mov_b32_e32 v17, v0
	v_mov_b32_e32 v18, v0
	v_mov_b32_e32 v19, v0
	v_mov_b32_e32 v20, v0
	v_mov_b32_e32 v21, v0
	v_mov_b32_e32 v22, v0
	v_mov_b32_e32 v23, v0
	v_mov_b32_e32 v32, v0
	v_mov_b32_e32 v33, v0
	v_mov_b32_e32 v34, v0
	v_mov_b32_e32 v35, v0
	v_mov_b32_e32 v36, v0
	v_mov_b32_e32 v37, v0
	v_mov_b32_e32 v38, v0
	v_mov_b32_e32 v39, v0
	v_mov_b32_e32 v48, v0
	v_mov_b32_e32 v49, v0
	v_mov_b32_e32 v50, v0
	v_mov_b32_e32 v51, v0
	v_mov_b32_e32 v52, v0
	v_mov_b32_e32 v53, v0
	v_mov_b32_e32 v54, v0
	v_mov_b32_e32 v55, v0
	v_mov_b32_e32 v8, v0
	v_mov_b32_e32 v9, v0
	v_mov_b32_e32 v10, v0
	v_mov_b32_e32 v11, v0
	v_mov_b32_e32 v12, v0
	v_mov_b32_e32 v13, v0
	v_mov_b32_e32 v14, v0
	v_mov_b32_e32 v15, v0
	v_mov_b32_e32 v24, v0
	v_mov_b32_e32 v25, v0
	v_mov_b32_e32 v26, v0
	v_mov_b32_e32 v27, v0
	v_mov_b32_e32 v28, v0
	v_mov_b32_e32 v29, v0
	v_mov_b32_e32 v30, v0
	v_mov_b32_e32 v31, v0
	v_mov_b32_e32 v40, v0
	v_mov_b32_e32 v41, v0
	v_mov_b32_e32 v42, v0
	v_mov_b32_e32 v43, v0
	v_mov_b32_e32 v44, v0
	v_mov_b32_e32 v45, v0
	v_mov_b32_e32 v46, v0
	v_mov_b32_e32 v47, v0
	v_mov_b32_e32 v56, v0
	v_mov_b32_e32 v57, v0
	v_mov_b32_e32 v58, v0
	v_mov_b32_e32 v59, v0
	v_mov_b32_e32 v60, v0
	v_mov_b32_e32 v61, v0
	v_mov_b32_e32 v62, v0
	v_mov_b32_e32 v63, v0
	v_mov_b32_e32 v64, v0
	v_mov_b32_e32 v65, v0
	v_mov_b32_e32 v66, v0
	v_mov_b32_e32 v67, v0
	v_mov_b32_e32 v68, v0
	v_mov_b32_e32 v69, v0
	v_mov_b32_e32 v70, v0
	v_mov_b32_e32 v71, v0
	v_mov_b32_e32 v80, v0
	v_mov_b32_e32 v81, v0
	v_mov_b32_e32 v82, v0
	v_mov_b32_e32 v83, v0
	v_mov_b32_e32 v84, v0
	v_mov_b32_e32 v85, v0
	v_mov_b32_e32 v86, v0
	v_mov_b32_e32 v87, v0
	v_mov_b32_e32 v96, v0
	v_mov_b32_e32 v97, v0
	v_mov_b32_e32 v98, v0
	v_mov_b32_e32 v99, v0
	v_mov_b32_e32 v100, v0
	v_mov_b32_e32 v101, v0
	v_mov_b32_e32 v102, v0
	v_mov_b32_e32 v103, v0
	v_mov_b32_e32 v112, v0
	v_mov_b32_e32 v113, v0
	v_mov_b32_e32 v114, v0
	v_mov_b32_e32 v115, v0
	v_mov_b32_e32 v116, v0
	v_mov_b32_e32 v117, v0
	v_mov_b32_e32 v118, v0
	v_mov_b32_e32 v119, v0
	v_mov_b32_e32 v72, v0
	v_mov_b32_e32 v73, v0
	v_mov_b32_e32 v74, v0
	v_mov_b32_e32 v75, v0
	v_mov_b32_e32 v76, v0
	v_mov_b32_e32 v77, v0
	v_mov_b32_e32 v78, v0
	v_mov_b32_e32 v79, v0
	v_mov_b32_e32 v88, v0
	v_mov_b32_e32 v89, v0
	v_mov_b32_e32 v90, v0
	v_mov_b32_e32 v91, v0
	v_mov_b32_e32 v92, v0
	v_mov_b32_e32 v93, v0
	v_mov_b32_e32 v94, v0
	v_mov_b32_e32 v95, v0
	v_mov_b32_e32 v104, v0
	v_mov_b32_e32 v105, v0
	v_mov_b32_e32 v106, v0
	v_mov_b32_e32 v107, v0
	v_mov_b32_e32 v108, v0
	v_mov_b32_e32 v109, v0
	v_mov_b32_e32 v110, v0
	v_mov_b32_e32 v111, v0
	v_mov_b32_e32 v120, v0
	v_mov_b32_e32 v121, v0
	v_mov_b32_e32 v122, v0
	v_mov_b32_e32 v123, v0
	v_mov_b32_e32 v124, v0
	v_mov_b32_e32 v125, v0
	v_mov_b32_e32 v126, v0
	v_mov_b32_e32 v127, v0
	v_add_u32_e32 v212, 0x80, v128
	v_add_u32_e32 v213, 0x80, v130
.LBB0_778:
	ds_read_b128 v[140:143], v147
	ds_read_b128 v[150:153], v147 offset:1024
	ds_read_b128 v[154:157], v147 offset:2048
	ds_read_b128 v[158:161], v147 offset:3072
	ds_read_b128 v[162:165], v148
	ds_read_b128 v[166:169], v148 offset:1024
	ds_read_b128 v[170:173], v148 offset:2048
	ds_read_b128 v[174:177], v148 offset:3072
	s_add_u32 s30, s28, 0x100
	s_addc_u32 s31, s29, 0
	s_cmp_eq_u32 s58, 60
	s_cselect_b32 s37, s21, s31
	s_cselect_b32 s36, s27, s30
	s_cselect_b32 s35, s19, s57
	s_cselect_b32 s34, s55, s56
	s_add_i32 m0, s44, 0xc000
	ds_read_b128 v[178:181], v149
	ds_read_b128 v[182:185], v149 offset:1024
	ds_read_b128 v[186:189], v149 offset:2048
	ds_read_b128 v[190:193], v149 offset:3072
	ds_read_b128 v[194:197], v149 offset:4096
	ds_read_b128 v[198:201], v149 offset:5120
	ds_read_b128 v[202:205], v149 offset:6144
	ds_read_b128 v[208:211], v149 offset:7168
	global_load_lds_dwordx4 v134, s[28:29]
	s_add_i32 m0, s44, 0xe000
	s_nop 0
	global_load_lds_dwordx4 v132, s[28:29]
	s_waitcnt vmcnt(8)
	s_waitcnt lgkmcnt(0)
	s_barrier
	s_waitcnt lgkmcnt(0)
	v_mfma_f32_16x16x32_bf16 v[124:127], v[140:143], v[178:181], v[124:127]
	v_mfma_f32_16x16x32_bf16 v[120:123], v[154:157], v[178:181], v[120:123]
	v_mfma_f32_16x16x32_bf16 v[108:111], v[140:143], v[186:189], v[108:111]
	v_mfma_f32_16x16x32_bf16 v[104:107], v[154:157], v[186:189], v[104:107]
	v_mfma_f32_16x16x32_bf16 v[92:95], v[140:143], v[194:197], v[92:95]
	v_mfma_f32_16x16x32_bf16 v[88:91], v[154:157], v[194:197], v[88:91]
	v_mfma_f32_16x16x32_bf16 v[76:79], v[140:143], v[202:205], v[76:79]
	v_mfma_f32_16x16x32_bf16 v[72:75], v[154:157], v[202:205], v[72:75]
	v_mfma_f32_16x16x32_bf16 v[124:127], v[150:153], v[182:185], v[124:127]
	v_mfma_f32_16x16x32_bf16 v[120:123], v[158:161], v[182:185], v[120:123]
	v_mfma_f32_16x16x32_bf16 v[108:111], v[150:153], v[190:193], v[108:111]
	v_mfma_f32_16x16x32_bf16 v[104:107], v[158:161], v[190:193], v[104:107]
	v_mfma_f32_16x16x32_bf16 v[92:95], v[150:153], v[198:201], v[92:95]
	v_mfma_f32_16x16x32_bf16 v[88:91], v[158:161], v[198:201], v[88:91]
	v_mfma_f32_16x16x32_bf16 v[76:79], v[150:153], v[208:211], v[76:79]
	v_mfma_f32_16x16x32_bf16 v[72:75], v[158:161], v[208:211], v[72:75]
	v_mfma_f32_16x16x32_bf16 v[116:119], v[162:165], v[178:181], v[116:119]
	v_mfma_f32_16x16x32_bf16 v[112:115], v[170:173], v[178:181], v[112:115]
	v_mfma_f32_16x16x32_bf16 v[100:103], v[162:165], v[186:189], v[100:103]
	v_mfma_f32_16x16x32_bf16 v[96:99], v[170:173], v[186:189], v[96:99]
	v_mfma_f32_16x16x32_bf16 v[84:87], v[162:165], v[194:197], v[84:87]
	v_mfma_f32_16x16x32_bf16 v[80:83], v[170:173], v[194:197], v[80:83]
	v_mfma_f32_16x16x32_bf16 v[68:71], v[162:165], v[202:205], v[68:71]
	v_mfma_f32_16x16x32_bf16 v[64:67], v[170:173], v[202:205], v[64:67]
	v_mfma_f32_16x16x32_bf16 v[116:119], v[166:169], v[182:185], v[116:119]
	v_mfma_f32_16x16x32_bf16 v[112:115], v[174:177], v[182:185], v[112:115]
	v_mfma_f32_16x16x32_bf16 v[100:103], v[166:169], v[190:193], v[100:103]
	v_mfma_f32_16x16x32_bf16 v[96:99], v[174:177], v[190:193], v[96:99]
	v_mfma_f32_16x16x32_bf16 v[84:87], v[166:169], v[198:201], v[84:87]
	v_mfma_f32_16x16x32_bf16 v[80:83], v[174:177], v[198:201], v[80:83]
	v_mfma_f32_16x16x32_bf16 v[68:71], v[166:169], v[208:211], v[68:71]
	v_mfma_f32_16x16x32_bf16 v[64:67], v[174:177], v[208:211], v[64:67]
	s_barrier
	s_add_i32 s28, s52, s43
	s_mov_b32 m0, s28
	ds_read_b128 v[178:181], v149 offset:16384
	ds_read_b128 v[182:185], v149 offset:17408
	ds_read_b128 v[186:189], v149 offset:18432
	ds_read_b128 v[190:193], v149 offset:19456
	ds_read_b128 v[194:197], v149 offset:20480
	ds_read_b128 v[198:201], v149 offset:21504
	ds_read_b128 v[202:205], v149 offset:22528
	ds_read_b128 v[208:211], v149 offset:23552
	global_load_lds_dwordx4 v128, s[34:35]
	s_add_i32 m0, s28, 0x2000
	s_add_u32 s28, s34, 0x100000
	s_mov_b64 s[98:99], s[34:35]
	s_addc_u32 s29, s35, 0
	s_add_i32 s59, s53, s43
	global_load_lds_dwordx4 v130, s[34:35]
	s_mov_b32 m0, s59
	s_nop 0
	global_load_lds_dwordx4 v128, s[28:29]
	s_add_i32 m0, s59, 0x2000
	s_nop 0
	global_load_lds_dwordx4 v130, s[28:29]
	s_mov_b32 m0, s44
	s_nop 0
	global_load_lds_dwordx4 v128, s[36:37]
	s_mov_b32 m0, s45
	s_nop 0
	global_load_lds_dwordx4 v130, s[36:37]
	s_waitcnt vmcnt(8)
	s_waitcnt lgkmcnt(0)
	s_barrier
	s_waitcnt lgkmcnt(0)
	v_mfma_f32_16x16x32_bf16 v[60:63], v[140:143], v[178:181], v[60:63]
	v_mfma_f32_16x16x32_bf16 v[56:59], v[154:157], v[178:181], v[56:59]
	v_mfma_f32_16x16x32_bf16 v[44:47], v[140:143], v[186:189], v[44:47]
	v_mfma_f32_16x16x32_bf16 v[40:43], v[154:157], v[186:189], v[40:43]
	v_mfma_f32_16x16x32_bf16 v[28:31], v[140:143], v[194:197], v[28:31]
	v_mfma_f32_16x16x32_bf16 v[24:27], v[154:157], v[194:197], v[24:27]
	v_mfma_f32_16x16x32_bf16 v[12:15], v[140:143], v[202:205], v[12:15]
	v_mfma_f32_16x16x32_bf16 v[8:11], v[154:157], v[202:205], v[8:11]
	v_mfma_f32_16x16x32_bf16 v[60:63], v[150:153], v[182:185], v[60:63]
	v_mfma_f32_16x16x32_bf16 v[56:59], v[158:161], v[182:185], v[56:59]
	v_mfma_f32_16x16x32_bf16 v[44:47], v[150:153], v[190:193], v[44:47]
	v_mfma_f32_16x16x32_bf16 v[40:43], v[158:161], v[190:193], v[40:43]
	v_mfma_f32_16x16x32_bf16 v[28:31], v[150:153], v[198:201], v[28:31]
	v_mfma_f32_16x16x32_bf16 v[24:27], v[158:161], v[198:201], v[24:27]
	v_mfma_f32_16x16x32_bf16 v[12:15], v[150:153], v[208:211], v[12:15]
	v_mfma_f32_16x16x32_bf16 v[8:11], v[158:161], v[208:211], v[8:11]
	v_mfma_f32_16x16x32_bf16 v[52:55], v[162:165], v[178:181], v[52:55]
	v_mfma_f32_16x16x32_bf16 v[48:51], v[170:173], v[178:181], v[48:51]
	v_mfma_f32_16x16x32_bf16 v[36:39], v[162:165], v[186:189], v[36:39]
	v_mfma_f32_16x16x32_bf16 v[32:35], v[170:173], v[186:189], v[32:35]
	v_mfma_f32_16x16x32_bf16 v[20:23], v[162:165], v[194:197], v[20:23]
	v_mfma_f32_16x16x32_bf16 v[16:19], v[170:173], v[194:197], v[16:19]
	v_mfma_f32_16x16x32_bf16 v[4:7], v[162:165], v[202:205], v[4:7]
	v_mfma_f32_16x16x32_bf16 v[0:3], v[170:173], v[202:205], v[0:3]
	v_mfma_f32_16x16x32_bf16 v[52:55], v[166:169], v[182:185], v[52:55]
	v_mfma_f32_16x16x32_bf16 v[48:51], v[174:177], v[182:185], v[48:51]
	v_mfma_f32_16x16x32_bf16 v[36:39], v[166:169], v[190:193], v[36:39]
	v_mfma_f32_16x16x32_bf16 v[32:35], v[174:177], v[190:193], v[32:35]
	v_mfma_f32_16x16x32_bf16 v[20:23], v[166:169], v[198:201], v[20:23]
	v_mfma_f32_16x16x32_bf16 v[16:19], v[174:177], v[198:201], v[16:19]
	v_mfma_f32_16x16x32_bf16 v[4:7], v[166:169], v[208:211], v[4:7]
	v_mfma_f32_16x16x32_bf16 v[0:3], v[174:177], v[208:211], v[0:3]
	s_barrier
	s_add_i32 s59, 0, 0x18000
	s_add_i32 s60, 0, 0x1c000
	v_add_u32_e32 v158, s59, v145
	v_add_u32_e32 v174, s60, v145
	ds_read_b128 v[140:143], v158
	ds_read_b128 v[150:153], v158 offset:1024
	ds_read_b128 v[154:157], v158 offset:2048
	ds_read_b128 v[158:161], v158 offset:3072
	ds_read_b128 v[162:165], v174
	ds_read_b128 v[166:169], v174 offset:1024
	ds_read_b128 v[170:173], v174 offset:2048
	ds_read_b128 v[174:177], v174 offset:3072
	s_add_u32 s28, s36, 0x100000
	s_addc_u32 s29, s37, 0
	s_mov_b32 m0, s46
	ds_read_b128 v[178:181], v149 offset:32768
	ds_read_b128 v[182:185], v149 offset:33792
	ds_read_b128 v[186:189], v149 offset:34816
	ds_read_b128 v[190:193], v149 offset:35840
	ds_read_b128 v[194:197], v149 offset:36864
	ds_read_b128 v[198:201], v149 offset:37888
	ds_read_b128 v[202:205], v149 offset:38912
	ds_read_b128 v[208:211], v149 offset:39936
	global_load_lds_dwordx4 v128, s[28:29]
	s_mov_b32 m0, s47
	s_nop 0
	global_load_lds_dwordx4 v130, s[28:29]
	s_waitcnt vmcnt(8)
	s_waitcnt lgkmcnt(0)
	s_barrier
	s_waitcnt lgkmcnt(0)
	v_mfma_f32_16x16x32_bf16 v[124:127], v[140:143], v[178:181], v[124:127]
	v_mfma_f32_16x16x32_bf16 v[120:123], v[154:157], v[178:181], v[120:123]
	v_mfma_f32_16x16x32_bf16 v[108:111], v[140:143], v[186:189], v[108:111]
	v_mfma_f32_16x16x32_bf16 v[104:107], v[154:157], v[186:189], v[104:107]
	v_mfma_f32_16x16x32_bf16 v[92:95], v[140:143], v[194:197], v[92:95]
	v_mfma_f32_16x16x32_bf16 v[88:91], v[154:157], v[194:197], v[88:91]
	v_mfma_f32_16x16x32_bf16 v[76:79], v[140:143], v[202:205], v[76:79]
	v_mfma_f32_16x16x32_bf16 v[72:75], v[154:157], v[202:205], v[72:75]
	v_mfma_f32_16x16x32_bf16 v[124:127], v[150:153], v[182:185], v[124:127]
	v_mfma_f32_16x16x32_bf16 v[120:123], v[158:161], v[182:185], v[120:123]
	v_mfma_f32_16x16x32_bf16 v[108:111], v[150:153], v[190:193], v[108:111]
	v_mfma_f32_16x16x32_bf16 v[104:107], v[158:161], v[190:193], v[104:107]
	v_mfma_f32_16x16x32_bf16 v[92:95], v[150:153], v[198:201], v[92:95]
	v_mfma_f32_16x16x32_bf16 v[88:91], v[158:161], v[198:201], v[88:91]
	v_mfma_f32_16x16x32_bf16 v[76:79], v[150:153], v[208:211], v[76:79]
	v_mfma_f32_16x16x32_bf16 v[72:75], v[158:161], v[208:211], v[72:75]
	v_mfma_f32_16x16x32_bf16 v[116:119], v[162:165], v[178:181], v[116:119]
	v_mfma_f32_16x16x32_bf16 v[112:115], v[170:173], v[178:181], v[112:115]
	v_mfma_f32_16x16x32_bf16 v[100:103], v[162:165], v[186:189], v[100:103]
	v_mfma_f32_16x16x32_bf16 v[96:99], v[170:173], v[186:189], v[96:99]
	v_mfma_f32_16x16x32_bf16 v[84:87], v[162:165], v[194:197], v[84:87]
	v_mfma_f32_16x16x32_bf16 v[80:83], v[170:173], v[194:197], v[80:83]
	v_mfma_f32_16x16x32_bf16 v[68:71], v[162:165], v[202:205], v[68:71]
	v_mfma_f32_16x16x32_bf16 v[64:67], v[170:173], v[202:205], v[64:67]
	v_mfma_f32_16x16x32_bf16 v[116:119], v[166:169], v[182:185], v[116:119]
	v_mfma_f32_16x16x32_bf16 v[112:115], v[174:177], v[182:185], v[112:115]
	v_mfma_f32_16x16x32_bf16 v[100:103], v[166:169], v[190:193], v[100:103]
	v_mfma_f32_16x16x32_bf16 v[96:99], v[174:177], v[190:193], v[96:99]
	v_mfma_f32_16x16x32_bf16 v[84:87], v[166:169], v[198:201], v[84:87]
	v_mfma_f32_16x16x32_bf16 v[80:83], v[174:177], v[198:201], v[80:83]
	v_mfma_f32_16x16x32_bf16 v[68:71], v[166:169], v[208:211], v[68:71]
	v_mfma_f32_16x16x32_bf16 v[64:67], v[174:177], v[208:211], v[64:67]
	s_barrier
	s_add_i32 s28, s59, s43
	s_mov_b32 m0, s28
	ds_read_b128 v[178:181], v149 offset:49152
	ds_read_b128 v[182:185], v149 offset:50176
	ds_read_b128 v[186:189], v149 offset:51200
	ds_read_b128 v[190:193], v149 offset:52224
	ds_read_b128 v[194:197], v149 offset:53248
	ds_read_b128 v[198:201], v149 offset:54272
	ds_read_b128 v[202:205], v149 offset:55296
	ds_read_b128 v[208:211], v149 offset:56320
	global_load_lds_dwordx4 v212, s[34:35]
	s_add_i32 m0, s28, 0x2000
	s_add_u32 s28, s34, 0x100080
	s_addc_u32 s29, s35, 0
	s_add_i32 s34, s60, s43
	global_load_lds_dwordx4 v213, s[98:99]
	s_mov_b32 m0, s34
	s_nop 0
	global_load_lds_dwordx4 v128, s[28:29]
	s_add_i32 m0, s34, 0x2000
	s_nop 0
	global_load_lds_dwordx4 v130, s[28:29]
	s_mov_b32 m0, s49
	s_nop 0
	global_load_lds_dwordx4 v212, s[36:37]
	s_mov_b32 m0, s50
	s_nop 0
	global_load_lds_dwordx4 v213, s[36:37]
	s_waitcnt vmcnt(8)
	s_waitcnt lgkmcnt(0)
	s_barrier
	s_waitcnt lgkmcnt(0)
	v_mfma_f32_16x16x32_bf16 v[60:63], v[140:143], v[178:181], v[60:63]
	v_mfma_f32_16x16x32_bf16 v[56:59], v[154:157], v[178:181], v[56:59]
	v_mfma_f32_16x16x32_bf16 v[44:47], v[140:143], v[186:189], v[44:47]
	v_mfma_f32_16x16x32_bf16 v[40:43], v[154:157], v[186:189], v[40:43]
	v_mfma_f32_16x16x32_bf16 v[28:31], v[140:143], v[194:197], v[28:31]
	v_mfma_f32_16x16x32_bf16 v[24:27], v[154:157], v[194:197], v[24:27]
	v_mfma_f32_16x16x32_bf16 v[12:15], v[140:143], v[202:205], v[12:15]
	v_mfma_f32_16x16x32_bf16 v[8:11], v[154:157], v[202:205], v[8:11]
	v_mfma_f32_16x16x32_bf16 v[60:63], v[150:153], v[182:185], v[60:63]
	v_mfma_f32_16x16x32_bf16 v[56:59], v[158:161], v[182:185], v[56:59]
	v_mfma_f32_16x16x32_bf16 v[44:47], v[150:153], v[190:193], v[44:47]
	v_mfma_f32_16x16x32_bf16 v[40:43], v[158:161], v[190:193], v[40:43]
	v_mfma_f32_16x16x32_bf16 v[28:31], v[150:153], v[198:201], v[28:31]
	v_mfma_f32_16x16x32_bf16 v[24:27], v[158:161], v[198:201], v[24:27]
	v_mfma_f32_16x16x32_bf16 v[12:15], v[150:153], v[208:211], v[12:15]
	v_mfma_f32_16x16x32_bf16 v[8:11], v[158:161], v[208:211], v[8:11]
	v_mfma_f32_16x16x32_bf16 v[52:55], v[162:165], v[178:181], v[52:55]
	v_mfma_f32_16x16x32_bf16 v[48:51], v[170:173], v[178:181], v[48:51]
	v_mfma_f32_16x16x32_bf16 v[36:39], v[162:165], v[186:189], v[36:39]
	v_mfma_f32_16x16x32_bf16 v[32:35], v[170:173], v[186:189], v[32:35]
	v_mfma_f32_16x16x32_bf16 v[20:23], v[162:165], v[194:197], v[20:23]
	v_mfma_f32_16x16x32_bf16 v[16:19], v[170:173], v[194:197], v[16:19]
	v_mfma_f32_16x16x32_bf16 v[4:7], v[162:165], v[202:205], v[4:7]
	v_mfma_f32_16x16x32_bf16 v[0:3], v[170:173], v[202:205], v[0:3]
	v_mfma_f32_16x16x32_bf16 v[52:55], v[166:169], v[182:185], v[52:55]
	v_mfma_f32_16x16x32_bf16 v[48:51], v[174:177], v[182:185], v[48:51]
	v_mfma_f32_16x16x32_bf16 v[36:39], v[166:169], v[190:193], v[36:39]
	v_mfma_f32_16x16x32_bf16 v[32:35], v[174:177], v[190:193], v[32:35]
	v_mfma_f32_16x16x32_bf16 v[20:23], v[166:169], v[198:201], v[20:23]
	v_mfma_f32_16x16x32_bf16 v[16:19], v[174:177], v[198:201], v[16:19]
	v_mfma_f32_16x16x32_bf16 v[4:7], v[166:169], v[208:211], v[4:7]
	v_mfma_f32_16x16x32_bf16 v[0:3], v[174:177], v[208:211], v[0:3]
	s_barrier
	s_add_i32 s58, s58, 2
	s_add_u32 s56, s56, 0x100
	s_addc_u32 s57, s57, 0
	s_cmp_gt_u32 s58, 61
	s_mov_b64 s[28:29], s[30:31]
	s_cbranch_scc0 .LBB0_778
	s_and_b64 vcc, exec, s[16:17]
	s_cbranch_vccz .LBB0_781
	s_barrier

.LBB0_894:
	s_ashr_i32 s29, s28, 31
	s_lshl_b64 s[30:31], s[28:29], 19
	s_add_u32 s30, s8, s30
	s_addc_u32 s31, s9, s31
	s_and_b64 s[34:35], s[6:7], exec
	s_cselect_b32 s3, s31, s39
	s_cselect_b32 s29, s30, s38
	s_ashr_i32 s27, s26, 31
	s_lshl_b64 s[34:35], s[26:27], 19
	s_add_u32 s34, s43, s34
	s_addc_u32 s35, s44, s35
	s_and_b64 s[40:41], s[6:7], exec
	s_cselect_b32 s27, s35, s37
	s_cselect_b32 s58, s34, s36
	s_add_u32 s59, s36, 0x100
	s_addc_u32 s60, s37, 0
	s_add_u32 s36, s38, 0x40080
	v_mov_b32_e32 v0, 0
	s_addc_u32 s37, s39, 0
	s_mov_b32 s61, -2
	v_mov_b32_e32 v1, v0
	v_mov_b32_e32 v2, v0
	v_mov_b32_e32 v3, v0
	v_mov_b32_e32 v4, v0
	v_mov_b32_e32 v5, v0
	v_mov_b32_e32 v6, v0
	v_mov_b32_e32 v7, v0
	v_mov_b32_e32 v16, v0
	v_mov_b32_e32 v17, v0
	v_mov_b32_e32 v18, v0
	v_mov_b32_e32 v19, v0
	v_mov_b32_e32 v20, v0
	v_mov_b32_e32 v21, v0
	v_mov_b32_e32 v22, v0
	v_mov_b32_e32 v23, v0
	v_mov_b32_e32 v32, v0
	v_mov_b32_e32 v33, v0
	v_mov_b32_e32 v34, v0
	v_mov_b32_e32 v35, v0
	v_mov_b32_e32 v36, v0
	v_mov_b32_e32 v37, v0
	v_mov_b32_e32 v38, v0
	v_mov_b32_e32 v39, v0
	v_mov_b32_e32 v48, v0
	v_mov_b32_e32 v49, v0
	v_mov_b32_e32 v50, v0
	v_mov_b32_e32 v51, v0
	v_mov_b32_e32 v52, v0
	v_mov_b32_e32 v53, v0
	v_mov_b32_e32 v54, v0
	v_mov_b32_e32 v55, v0
	v_mov_b32_e32 v8, v0
	v_mov_b32_e32 v9, v0
	v_mov_b32_e32 v10, v0
	v_mov_b32_e32 v11, v0
	v_mov_b32_e32 v12, v0
	v_mov_b32_e32 v13, v0
	v_mov_b32_e32 v14, v0
	v_mov_b32_e32 v15, v0
	v_mov_b32_e32 v24, v0
	v_mov_b32_e32 v25, v0
	v_mov_b32_e32 v26, v0
	v_mov_b32_e32 v27, v0
	v_mov_b32_e32 v28, v0
	v_mov_b32_e32 v29, v0
	v_mov_b32_e32 v30, v0
	v_mov_b32_e32 v31, v0
	v_mov_b32_e32 v40, v0
	v_mov_b32_e32 v41, v0
	v_mov_b32_e32 v42, v0
	v_mov_b32_e32 v43, v0
	v_mov_b32_e32 v44, v0
	v_mov_b32_e32 v45, v0
	v_mov_b32_e32 v46, v0
	v_mov_b32_e32 v47, v0
	v_mov_b32_e32 v56, v0
	v_mov_b32_e32 v57, v0
	v_mov_b32_e32 v58, v0
	v_mov_b32_e32 v59, v0
	v_mov_b32_e32 v60, v0
	v_mov_b32_e32 v61, v0
	v_mov_b32_e32 v62, v0
	v_mov_b32_e32 v63, v0
	v_mov_b32_e32 v64, v0
	v_mov_b32_e32 v65, v0
	v_mov_b32_e32 v66, v0
	v_mov_b32_e32 v67, v0
	v_mov_b32_e32 v68, v0
	v_mov_b32_e32 v69, v0
	v_mov_b32_e32 v70, v0
	v_mov_b32_e32 v71, v0
	v_mov_b32_e32 v80, v0
	v_mov_b32_e32 v81, v0
	v_mov_b32_e32 v82, v0
	v_mov_b32_e32 v83, v0
	v_mov_b32_e32 v84, v0
	v_mov_b32_e32 v85, v0
	v_mov_b32_e32 v86, v0
	v_mov_b32_e32 v87, v0
	v_mov_b32_e32 v96, v0
	v_mov_b32_e32 v97, v0
	v_mov_b32_e32 v98, v0
	v_mov_b32_e32 v99, v0
	v_mov_b32_e32 v100, v0
	v_mov_b32_e32 v101, v0
	v_mov_b32_e32 v102, v0
	v_mov_b32_e32 v103, v0
	v_mov_b32_e32 v112, v0
	v_mov_b32_e32 v113, v0
	v_mov_b32_e32 v114, v0
	v_mov_b32_e32 v115, v0
	v_mov_b32_e32 v116, v0
	v_mov_b32_e32 v117, v0
	v_mov_b32_e32 v118, v0
	v_mov_b32_e32 v119, v0
	v_mov_b32_e32 v72, v0
	v_mov_b32_e32 v73, v0
	v_mov_b32_e32 v74, v0
	v_mov_b32_e32 v75, v0
	v_mov_b32_e32 v76, v0
	v_mov_b32_e32 v77, v0
	v_mov_b32_e32 v78, v0
	v_mov_b32_e32 v79, v0
	v_mov_b32_e32 v88, v0
	v_mov_b32_e32 v89, v0
	v_mov_b32_e32 v90, v0
	v_mov_b32_e32 v91, v0
	v_mov_b32_e32 v92, v0
	v_mov_b32_e32 v93, v0
	v_mov_b32_e32 v94, v0
	v_mov_b32_e32 v95, v0
	v_mov_b32_e32 v104, v0
	v_mov_b32_e32 v105, v0
	v_mov_b32_e32 v106, v0
	v_mov_b32_e32 v107, v0
	v_mov_b32_e32 v108, v0
	v_mov_b32_e32 v109, v0
	v_mov_b32_e32 v110, v0
	v_mov_b32_e32 v111, v0
	v_mov_b32_e32 v120, v0
	v_mov_b32_e32 v121, v0
	v_mov_b32_e32 v122, v0
	v_mov_b32_e32 v123, v0
	v_mov_b32_e32 v124, v0
	v_mov_b32_e32 v125, v0
	v_mov_b32_e32 v126, v0
	v_mov_b32_e32 v127, v0
	v_add_u32_e32 v148, 0x80, v128
	v_add_u32_e32 v149, 0x80, v130
.LBB0_895:
	ds_read_b128 v[140:143], v153
	ds_read_b128 v[144:147], v153 offset:1024
	ds_read_b128 v[158:161], v153 offset:2048
	ds_read_b128 v[162:165], v153 offset:3072
	ds_read_b128 v[166:169], v154
	ds_read_b128 v[170:173], v154 offset:1024
	ds_read_b128 v[174:177], v154 offset:2048
	ds_read_b128 v[178:181], v154 offset:3072
	s_add_u32 s38, s36, 0xfffc0080
	s_addc_u32 s39, s37, -1
	s_cmp_eq_u32 s61, 12
	s_cselect_b32 s41, s3, s39
	s_cselect_b32 s40, s29, s38
	s_cselect_b32 s39, s27, s60
	s_cselect_b32 s38, s58, s59
	s_add_i32 m0, s46, 0xc000
	ds_read_b128 v[182:185], v155
	ds_read_b128 v[186:189], v155 offset:1024
	ds_read_b128 v[190:193], v155 offset:2048
	ds_read_b128 v[194:197], v155 offset:3072
	ds_read_b128 v[198:201], v155 offset:4096
	ds_read_b128 v[202:205], v155 offset:5120
	ds_read_b128 v[208:211], v155 offset:6144
	ds_read_b128 v[212:215], v155 offset:7168
	global_load_lds_dwordx4 v134, s[36:37]
	s_add_i32 m0, s46, 0xe000
	s_nop 0
	global_load_lds_dwordx4 v132, s[36:37]
	s_waitcnt vmcnt(8)
	s_waitcnt lgkmcnt(0)
	s_barrier
	s_waitcnt lgkmcnt(0)
	v_mfma_f32_16x16x32_bf16 v[124:127], v[140:143], v[182:185], v[124:127]
	v_mfma_f32_16x16x32_bf16 v[120:123], v[158:161], v[182:185], v[120:123]
	v_mfma_f32_16x16x32_bf16 v[108:111], v[140:143], v[190:193], v[108:111]
	v_mfma_f32_16x16x32_bf16 v[104:107], v[158:161], v[190:193], v[104:107]
	v_mfma_f32_16x16x32_bf16 v[92:95], v[140:143], v[198:201], v[92:95]
	v_mfma_f32_16x16x32_bf16 v[88:91], v[158:161], v[198:201], v[88:91]
	v_mfma_f32_16x16x32_bf16 v[76:79], v[140:143], v[208:211], v[76:79]
	v_mfma_f32_16x16x32_bf16 v[72:75], v[158:161], v[208:211], v[72:75]
	v_mfma_f32_16x16x32_bf16 v[124:127], v[144:147], v[186:189], v[124:127]
	v_mfma_f32_16x16x32_bf16 v[120:123], v[162:165], v[186:189], v[120:123]
	v_mfma_f32_16x16x32_bf16 v[108:111], v[144:147], v[194:197], v[108:111]
	v_mfma_f32_16x16x32_bf16 v[104:107], v[162:165], v[194:197], v[104:107]
	v_mfma_f32_16x16x32_bf16 v[92:95], v[144:147], v[202:205], v[92:95]
	v_mfma_f32_16x16x32_bf16 v[88:91], v[162:165], v[202:205], v[88:91]
	v_mfma_f32_16x16x32_bf16 v[76:79], v[144:147], v[212:215], v[76:79]
	v_mfma_f32_16x16x32_bf16 v[72:75], v[162:165], v[212:215], v[72:75]
	v_mfma_f32_16x16x32_bf16 v[116:119], v[166:169], v[182:185], v[116:119]
	v_mfma_f32_16x16x32_bf16 v[112:115], v[174:177], v[182:185], v[112:115]
	v_mfma_f32_16x16x32_bf16 v[100:103], v[166:169], v[190:193], v[100:103]
	v_mfma_f32_16x16x32_bf16 v[96:99], v[174:177], v[190:193], v[96:99]
	v_mfma_f32_16x16x32_bf16 v[84:87], v[166:169], v[198:201], v[84:87]
	v_mfma_f32_16x16x32_bf16 v[80:83], v[174:177], v[198:201], v[80:83]
	v_mfma_f32_16x16x32_bf16 v[68:71], v[166:169], v[208:211], v[68:71]
	v_mfma_f32_16x16x32_bf16 v[64:67], v[174:177], v[208:211], v[64:67]
	v_mfma_f32_16x16x32_bf16 v[116:119], v[170:173], v[186:189], v[116:119]
	v_mfma_f32_16x16x32_bf16 v[112:115], v[178:181], v[186:189], v[112:115]
	v_mfma_f32_16x16x32_bf16 v[100:103], v[170:173], v[194:197], v[100:103]
	v_mfma_f32_16x16x32_bf16 v[96:99], v[178:181], v[194:197], v[96:99]
	v_mfma_f32_16x16x32_bf16 v[84:87], v[170:173], v[202:205], v[84:87]
	v_mfma_f32_16x16x32_bf16 v[80:83], v[178:181], v[202:205], v[80:83]
	v_mfma_f32_16x16x32_bf16 v[68:71], v[170:173], v[212:215], v[68:71]
	v_mfma_f32_16x16x32_bf16 v[64:67], v[178:181], v[212:215], v[64:67]
	s_barrier
	s_add_i32 s62, s54, s45
	s_mov_b32 m0, s62
	ds_read_b128 v[182:185], v155 offset:16384
	ds_read_b128 v[186:189], v155 offset:17408
	ds_read_b128 v[190:193], v155 offset:18432
	ds_read_b128 v[194:197], v155 offset:19456
	ds_read_b128 v[198:201], v155 offset:20480
	ds_read_b128 v[202:205], v155 offset:21504
	ds_read_b128 v[208:211], v155 offset:22528
	ds_read_b128 v[212:215], v155 offset:23552
	global_load_lds_dwordx4 v128, s[38:39]
	s_add_i32 m0, s62, 0x2000
	s_add_u32 s62, s38, 0x40000
	s_mov_b64 s[98:99], s[38:39]
	s_addc_u32 s63, s39, 0
	s_add_i32 s64, s55, s45
	global_load_lds_dwordx4 v130, s[38:39]
	s_mov_b32 m0, s64
	s_mov_b64 s[100:101], s[40:41]
	global_load_lds_dwordx4 v128, s[62:63]
	s_add_i32 m0, s64, 0x2000
	s_nop 0
	global_load_lds_dwordx4 v130, s[62:63]
	s_mov_b32 m0, s46
	s_nop 0
	global_load_lds_dwordx4 v128, s[40:41]
	s_mov_b32 m0, s47
	s_nop 0
	global_load_lds_dwordx4 v130, s[40:41]
	s_waitcnt vmcnt(8)
	s_waitcnt lgkmcnt(0)
	s_barrier
	s_waitcnt lgkmcnt(0)
	v_mfma_f32_16x16x32_bf16 v[60:63], v[140:143], v[182:185], v[60:63]
	v_mfma_f32_16x16x32_bf16 v[56:59], v[158:161], v[182:185], v[56:59]
	v_mfma_f32_16x16x32_bf16 v[44:47], v[140:143], v[190:193], v[44:47]
	v_mfma_f32_16x16x32_bf16 v[40:43], v[158:161], v[190:193], v[40:43]
	v_mfma_f32_16x16x32_bf16 v[28:31], v[140:143], v[198:201], v[28:31]
	v_mfma_f32_16x16x32_bf16 v[24:27], v[158:161], v[198:201], v[24:27]
	v_mfma_f32_16x16x32_bf16 v[12:15], v[140:143], v[208:211], v[12:15]
	v_mfma_f32_16x16x32_bf16 v[8:11], v[158:161], v[208:211], v[8:11]
	v_mfma_f32_16x16x32_bf16 v[60:63], v[144:147], v[186:189], v[60:63]
	v_mfma_f32_16x16x32_bf16 v[56:59], v[162:165], v[186:189], v[56:59]
	v_mfma_f32_16x16x32_bf16 v[44:47], v[144:147], v[194:197], v[44:47]
	v_mfma_f32_16x16x32_bf16 v[40:43], v[162:165], v[194:197], v[40:43]
	v_mfma_f32_16x16x32_bf16 v[28:31], v[144:147], v[202:205], v[28:31]
	v_mfma_f32_16x16x32_bf16 v[24:27], v[162:165], v[202:205], v[24:27]
	v_mfma_f32_16x16x32_bf16 v[12:15], v[144:147], v[212:215], v[12:15]
	v_mfma_f32_16x16x32_bf16 v[8:11], v[162:165], v[212:215], v[8:11]
	v_mfma_f32_16x16x32_bf16 v[52:55], v[166:169], v[182:185], v[52:55]
	v_mfma_f32_16x16x32_bf16 v[48:51], v[174:177], v[182:185], v[48:51]
	v_mfma_f32_16x16x32_bf16 v[36:39], v[166:169], v[190:193], v[36:39]
	v_mfma_f32_16x16x32_bf16 v[32:35], v[174:177], v[190:193], v[32:35]
	v_mfma_f32_16x16x32_bf16 v[20:23], v[166:169], v[198:201], v[20:23]
	v_mfma_f32_16x16x32_bf16 v[16:19], v[174:177], v[198:201], v[16:19]
	v_mfma_f32_16x16x32_bf16 v[4:7], v[166:169], v[208:211], v[4:7]
	v_mfma_f32_16x16x32_bf16 v[0:3], v[174:177], v[208:211], v[0:3]
	v_mfma_f32_16x16x32_bf16 v[52:55], v[170:173], v[186:189], v[52:55]
	v_mfma_f32_16x16x32_bf16 v[48:51], v[178:181], v[186:189], v[48:51]
	v_mfma_f32_16x16x32_bf16 v[36:39], v[170:173], v[194:197], v[36:39]
	v_mfma_f32_16x16x32_bf16 v[32:35], v[178:181], v[194:197], v[32:35]
	v_mfma_f32_16x16x32_bf16 v[20:23], v[170:173], v[202:205], v[20:23]
	v_mfma_f32_16x16x32_bf16 v[16:19], v[178:181], v[202:205], v[16:19]
	v_mfma_f32_16x16x32_bf16 v[4:7], v[170:173], v[212:215], v[4:7]
	v_mfma_f32_16x16x32_bf16 v[0:3], v[178:181], v[212:215], v[0:3]
	s_barrier
	s_add_i32 s62, 0, 0x18000
	v_add_u32_e32 v157, s62, v151
	s_add_i32 s63, 0, 0x1c000
	ds_read_b128 v[140:143], v157
	ds_read_b128 v[144:147], v157 offset:1024
	ds_read_b128 v[158:161], v157 offset:2048
	ds_read_b128 v[162:165], v157 offset:3072
	v_add_u32_e32 v157, s63, v151
	ds_read_b128 v[166:169], v157
	ds_read_b128 v[170:173], v157 offset:1024
	ds_read_b128 v[174:177], v157 offset:2048
	ds_read_b128 v[178:181], v157 offset:3072
	s_add_u32 s40, s40, 0x40000
	s_addc_u32 s41, s41, 0
	s_mov_b32 m0, s48
	ds_read_b128 v[182:185], v155 offset:32768
	ds_read_b128 v[186:189], v155 offset:33792
	ds_read_b128 v[190:193], v155 offset:34816
	ds_read_b128 v[194:197], v155 offset:35840
	ds_read_b128 v[198:201], v155 offset:36864
	ds_read_b128 v[202:205], v155 offset:37888
	ds_read_b128 v[208:211], v155 offset:38912
	ds_read_b128 v[212:215], v155 offset:39936
	global_load_lds_dwordx4 v128, s[40:41]
	s_mov_b32 m0, s49
	s_nop 0
	global_load_lds_dwordx4 v130, s[40:41]
	s_waitcnt vmcnt(8)
	s_waitcnt lgkmcnt(0)
	s_barrier
	s_waitcnt lgkmcnt(0)
	v_mfma_f32_16x16x32_bf16 v[124:127], v[140:143], v[182:185], v[124:127]
	v_mfma_f32_16x16x32_bf16 v[120:123], v[158:161], v[182:185], v[120:123]
	v_mfma_f32_16x16x32_bf16 v[108:111], v[140:143], v[190:193], v[108:111]
	v_mfma_f32_16x16x32_bf16 v[104:107], v[158:161], v[190:193], v[104:107]
	v_mfma_f32_16x16x32_bf16 v[92:95], v[140:143], v[198:201], v[92:95]
	v_mfma_f32_16x16x32_bf16 v[88:91], v[158:161], v[198:201], v[88:91]
	v_mfma_f32_16x16x32_bf16 v[76:79], v[140:143], v[208:211], v[76:79]
	v_mfma_f32_16x16x32_bf16 v[72:75], v[158:161], v[208:211], v[72:75]
	v_mfma_f32_16x16x32_bf16 v[124:127], v[144:147], v[186:189], v[124:127]
	v_mfma_f32_16x16x32_bf16 v[120:123], v[162:165], v[186:189], v[120:123]
	v_mfma_f32_16x16x32_bf16 v[108:111], v[144:147], v[194:197], v[108:111]
	v_mfma_f32_16x16x32_bf16 v[104:107], v[162:165], v[194:197], v[104:107]
	v_mfma_f32_16x16x32_bf16 v[92:95], v[144:147], v[202:205], v[92:95]
	v_mfma_f32_16x16x32_bf16 v[88:91], v[162:165], v[202:205], v[88:91]
	v_mfma_f32_16x16x32_bf16 v[76:79], v[144:147], v[212:215], v[76:79]
	v_mfma_f32_16x16x32_bf16 v[72:75], v[162:165], v[212:215], v[72:75]
	v_mfma_f32_16x16x32_bf16 v[116:119], v[166:169], v[182:185], v[116:119]
	v_mfma_f32_16x16x32_bf16 v[112:115], v[174:177], v[182:185], v[112:115]
	v_mfma_f32_16x16x32_bf16 v[100:103], v[166:169], v[190:193], v[100:103]
	v_mfma_f32_16x16x32_bf16 v[96:99], v[174:177], v[190:193], v[96:99]
	v_mfma_f32_16x16x32_bf16 v[84:87], v[166:169], v[198:201], v[84:87]
	v_mfma_f32_16x16x32_bf16 v[80:83], v[174:177], v[198:201], v[80:83]
	v_mfma_f32_16x16x32_bf16 v[68:71], v[166:169], v[208:211], v[68:71]
	v_mfma_f32_16x16x32_bf16 v[64:67], v[174:177], v[208:211], v[64:67]
	v_mfma_f32_16x16x32_bf16 v[116:119], v[170:173], v[186:189], v[116:119]
	v_mfma_f32_16x16x32_bf16 v[112:115], v[178:181], v[186:189], v[112:115]
	v_mfma_f32_16x16x32_bf16 v[100:103], v[170:173], v[194:197], v[100:103]
	v_mfma_f32_16x16x32_bf16 v[96:99], v[178:181], v[194:197], v[96:99]
	v_mfma_f32_16x16x32_bf16 v[84:87], v[170:173], v[202:205], v[84:87]
	v_mfma_f32_16x16x32_bf16 v[80:83], v[178:181], v[202:205], v[80:83]
	v_mfma_f32_16x16x32_bf16 v[68:71], v[170:173], v[212:215], v[68:71]
	v_mfma_f32_16x16x32_bf16 v[64:67], v[178:181], v[212:215], v[64:67]
	s_barrier
	s_add_i32 s40, s62, s45
	s_mov_b32 m0, s40
	ds_read_b128 v[182:185], v155 offset:49152
	ds_read_b128 v[186:189], v155 offset:50176
	ds_read_b128 v[190:193], v155 offset:51200
	ds_read_b128 v[194:197], v155 offset:52224
	ds_read_b128 v[198:201], v155 offset:53248
	ds_read_b128 v[202:205], v155 offset:54272
	ds_read_b128 v[208:211], v155 offset:55296
	ds_read_b128 v[212:215], v155 offset:56320
	global_load_lds_dwordx4 v148, s[38:39]
	s_add_i32 m0, s40, 0x2000
	s_add_u32 s38, s38, 0x40080
	s_addc_u32 s39, s39, 0
	s_add_i32 s40, s63, s45
	global_load_lds_dwordx4 v149, s[98:99]
	s_mov_b32 m0, s40
	s_nop 0
	global_load_lds_dwordx4 v128, s[38:39]
	s_add_i32 m0, s40, 0x2000
	s_nop 0
	global_load_lds_dwordx4 v130, s[38:39]
	s_mov_b32 m0, s51
	s_nop 0
	global_load_lds_dwordx4 v148, s[100:101]
	s_mov_b32 m0, s52
	s_nop 0
	global_load_lds_dwordx4 v149, s[100:101]
	s_waitcnt vmcnt(8)
	s_waitcnt lgkmcnt(0)
	s_barrier
	s_waitcnt lgkmcnt(0)
	v_mfma_f32_16x16x32_bf16 v[60:63], v[140:143], v[182:185], v[60:63]
	v_mfma_f32_16x16x32_bf16 v[56:59], v[158:161], v[182:185], v[56:59]
	v_mfma_f32_16x16x32_bf16 v[44:47], v[140:143], v[190:193], v[44:47]
	v_mfma_f32_16x16x32_bf16 v[40:43], v[158:161], v[190:193], v[40:43]
	v_mfma_f32_16x16x32_bf16 v[28:31], v[140:143], v[198:201], v[28:31]
	v_mfma_f32_16x16x32_bf16 v[24:27], v[158:161], v[198:201], v[24:27]
	v_mfma_f32_16x16x32_bf16 v[12:15], v[140:143], v[208:211], v[12:15]
	v_mfma_f32_16x16x32_bf16 v[8:11], v[158:161], v[208:211], v[8:11]
	v_mfma_f32_16x16x32_bf16 v[60:63], v[144:147], v[186:189], v[60:63]
	v_mfma_f32_16x16x32_bf16 v[56:59], v[162:165], v[186:189], v[56:59]
	v_mfma_f32_16x16x32_bf16 v[44:47], v[144:147], v[194:197], v[44:47]
	v_mfma_f32_16x16x32_bf16 v[40:43], v[162:165], v[194:197], v[40:43]
	v_mfma_f32_16x16x32_bf16 v[28:31], v[144:147], v[202:205], v[28:31]
	v_mfma_f32_16x16x32_bf16 v[24:27], v[162:165], v[202:205], v[24:27]
	v_mfma_f32_16x16x32_bf16 v[12:15], v[144:147], v[212:215], v[12:15]
	v_mfma_f32_16x16x32_bf16 v[8:11], v[162:165], v[212:215], v[8:11]
	v_mfma_f32_16x16x32_bf16 v[52:55], v[166:169], v[182:185], v[52:55]
	v_mfma_f32_16x16x32_bf16 v[48:51], v[174:177], v[182:185], v[48:51]
	v_mfma_f32_16x16x32_bf16 v[36:39], v[166:169], v[190:193], v[36:39]
	v_mfma_f32_16x16x32_bf16 v[32:35], v[174:177], v[190:193], v[32:35]
	v_mfma_f32_16x16x32_bf16 v[20:23], v[166:169], v[198:201], v[20:23]
	v_mfma_f32_16x16x32_bf16 v[16:19], v[174:177], v[198:201], v[16:19]
	v_mfma_f32_16x16x32_bf16 v[4:7], v[166:169], v[208:211], v[4:7]
	v_mfma_f32_16x16x32_bf16 v[0:3], v[174:177], v[208:211], v[0:3]
	v_mfma_f32_16x16x32_bf16 v[52:55], v[170:173], v[186:189], v[52:55]
	v_mfma_f32_16x16x32_bf16 v[48:51], v[178:181], v[186:189], v[48:51]
	v_mfma_f32_16x16x32_bf16 v[36:39], v[170:173], v[194:197], v[36:39]
	v_mfma_f32_16x16x32_bf16 v[32:35], v[178:181], v[194:197], v[32:35]
	v_mfma_f32_16x16x32_bf16 v[20:23], v[170:173], v[202:205], v[20:23]
	v_mfma_f32_16x16x32_bf16 v[16:19], v[178:181], v[202:205], v[16:19]
	v_mfma_f32_16x16x32_bf16 v[4:7], v[170:173], v[212:215], v[4:7]
	v_mfma_f32_16x16x32_bf16 v[0:3], v[178:181], v[212:215], v[0:3]
	s_barrier
	s_add_i32 s61, s61, 2
	s_add_u32 s59, s59, 0x100
	s_addc_u32 s60, s60, 0
	s_add_u32 s36, s36, 0x100
	s_addc_u32 s37, s37, 0
	s_cmp_gt_u32 s61, 13
	s_cbranch_scc0 .LBB0_895
	s_and_b64 vcc, exec, s[24:25]
	s_cbranch_vccz .LBB0_898
	s_barrier

.LBB0_987:
	s_ashr_i32 s19, s18, 31
	s_lshl_b64 s[6:7], s[18:19], 19
	s_add_u32 s20, s34, s6
	s_addc_u32 s21, s35, s7
	s_and_b64 s[6:7], s[4:5], exec
	s_cselect_b32 s19, s21, s29
	s_cselect_b32 s49, s20, s28
	s_ashr_i32 s17, s16, 31
	s_lshl_b64 s[6:7], s[16:17], 19
	s_add_u32 s22, s36, s6
	s_addc_u32 s23, s37, s7
	s_and_b64 s[6:7], s[4:5], exec
	s_cselect_b32 s17, s23, s27
	s_cselect_b32 s50, s22, s26
	s_add_u32 s51, s26, 0x100
	s_addc_u32 s52, s27, 0
	s_add_u32 s6, s28, 0x40080
	v_mov_b32_e32 v0, 0
	s_addc_u32 s7, s29, 0
	s_mov_b32 s53, -2
	v_mov_b32_e32 v1, v0
	v_mov_b32_e32 v2, v0
	v_mov_b32_e32 v3, v0
	v_mov_b32_e32 v4, v0
	v_mov_b32_e32 v5, v0
	v_mov_b32_e32 v6, v0
	v_mov_b32_e32 v7, v0
	v_mov_b32_e32 v16, v0
	v_mov_b32_e32 v17, v0
	v_mov_b32_e32 v18, v0
	v_mov_b32_e32 v19, v0
	v_mov_b32_e32 v20, v0
	v_mov_b32_e32 v21, v0
	v_mov_b32_e32 v22, v0
	v_mov_b32_e32 v23, v0
	v_mov_b32_e32 v32, v0
	v_mov_b32_e32 v33, v0
	v_mov_b32_e32 v34, v0
	v_mov_b32_e32 v35, v0
	v_mov_b32_e32 v36, v0
	v_mov_b32_e32 v37, v0
	v_mov_b32_e32 v38, v0
	v_mov_b32_e32 v39, v0
	v_mov_b32_e32 v48, v0
	v_mov_b32_e32 v49, v0
	v_mov_b32_e32 v50, v0
	v_mov_b32_e32 v51, v0
	v_mov_b32_e32 v52, v0
	v_mov_b32_e32 v53, v0
	v_mov_b32_e32 v54, v0
	v_mov_b32_e32 v55, v0
	v_mov_b32_e32 v8, v0
	v_mov_b32_e32 v9, v0
	v_mov_b32_e32 v10, v0
	v_mov_b32_e32 v11, v0
	v_mov_b32_e32 v12, v0
	v_mov_b32_e32 v13, v0
	v_mov_b32_e32 v14, v0
	v_mov_b32_e32 v15, v0
	v_mov_b32_e32 v24, v0
	v_mov_b32_e32 v25, v0
	v_mov_b32_e32 v26, v0
	v_mov_b32_e32 v27, v0
	v_mov_b32_e32 v28, v0
	v_mov_b32_e32 v29, v0
	v_mov_b32_e32 v30, v0
	v_mov_b32_e32 v31, v0
	v_mov_b32_e32 v40, v0
	v_mov_b32_e32 v41, v0
	v_mov_b32_e32 v42, v0
	v_mov_b32_e32 v43, v0
	v_mov_b32_e32 v44, v0
	v_mov_b32_e32 v45, v0
	v_mov_b32_e32 v46, v0
	v_mov_b32_e32 v47, v0
	v_mov_b32_e32 v56, v0
	v_mov_b32_e32 v57, v0
	v_mov_b32_e32 v58, v0
	v_mov_b32_e32 v59, v0
	v_mov_b32_e32 v60, v0
	v_mov_b32_e32 v61, v0
	v_mov_b32_e32 v62, v0
	v_mov_b32_e32 v63, v0
	v_mov_b32_e32 v64, v0
	v_mov_b32_e32 v65, v0
	v_mov_b32_e32 v66, v0
	v_mov_b32_e32 v67, v0
	v_mov_b32_e32 v68, v0
	v_mov_b32_e32 v69, v0
	v_mov_b32_e32 v70, v0
	v_mov_b32_e32 v71, v0
	v_mov_b32_e32 v80, v0
	v_mov_b32_e32 v81, v0
	v_mov_b32_e32 v82, v0
	v_mov_b32_e32 v83, v0
	v_mov_b32_e32 v84, v0
	v_mov_b32_e32 v85, v0
	v_mov_b32_e32 v86, v0
	v_mov_b32_e32 v87, v0
	v_mov_b32_e32 v96, v0
	v_mov_b32_e32 v97, v0
	v_mov_b32_e32 v98, v0
	v_mov_b32_e32 v99, v0
	v_mov_b32_e32 v100, v0
	v_mov_b32_e32 v101, v0
	v_mov_b32_e32 v102, v0
	v_mov_b32_e32 v103, v0
	v_mov_b32_e32 v112, v0
	v_mov_b32_e32 v113, v0
	v_mov_b32_e32 v114, v0
	v_mov_b32_e32 v115, v0
	v_mov_b32_e32 v116, v0
	v_mov_b32_e32 v117, v0
	v_mov_b32_e32 v118, v0
	v_mov_b32_e32 v119, v0
	v_mov_b32_e32 v72, v0
	v_mov_b32_e32 v73, v0
	v_mov_b32_e32 v74, v0
	v_mov_b32_e32 v75, v0
	v_mov_b32_e32 v76, v0
	v_mov_b32_e32 v77, v0
	v_mov_b32_e32 v78, v0
	v_mov_b32_e32 v79, v0
	v_mov_b32_e32 v88, v0
	v_mov_b32_e32 v89, v0
	v_mov_b32_e32 v90, v0
	v_mov_b32_e32 v91, v0
	v_mov_b32_e32 v92, v0
	v_mov_b32_e32 v93, v0
	v_mov_b32_e32 v94, v0
	v_mov_b32_e32 v95, v0
	v_mov_b32_e32 v104, v0
	v_mov_b32_e32 v105, v0
	v_mov_b32_e32 v106, v0
	v_mov_b32_e32 v107, v0
	v_mov_b32_e32 v108, v0
	v_mov_b32_e32 v109, v0
	v_mov_b32_e32 v110, v0
	v_mov_b32_e32 v111, v0
	v_mov_b32_e32 v120, v0
	v_mov_b32_e32 v121, v0
	v_mov_b32_e32 v122, v0
	v_mov_b32_e32 v123, v0
	v_mov_b32_e32 v124, v0
	v_mov_b32_e32 v125, v0
	v_mov_b32_e32 v126, v0
	v_mov_b32_e32 v127, v0
	v_add_u32_e32 v204, 0x80, v128
	v_add_u32_e32 v205, 0x80, v130
	v_add_u32_e32 v220, 0x80, v132
	v_add_u32_e32 v221, 0x80, v134
.LBB0_988:
	ds_read_b128 v[144:147], v151
	ds_read_b128 v[156:159], v151 offset:1024
	ds_read_b128 v[160:163], v151 offset:2048
	ds_read_b128 v[164:167], v151 offset:3072
	ds_read_b128 v[168:171], v152
	ds_read_b128 v[172:175], v152 offset:1024
	ds_read_b128 v[176:179], v152 offset:2048
	ds_read_b128 v[180:183], v152 offset:3072
	s_add_u32 s26, s6, 0xfffc0080
	s_addc_u32 s27, s7, -1
	s_cmp_eq_u32 s53, 12
	s_cselect_b32 s29, s19, s27
	s_cselect_b32 s28, s49, s26
	s_cselect_b32 s27, s17, s52
	s_cselect_b32 s26, s50, s51
	s_add_i32 m0, s25, 0xc000
	ds_read_b128 v[184:187], v153
	ds_read_b128 v[188:191], v153 offset:1024
	ds_read_b128 v[192:195], v153 offset:2048
	ds_read_b128 v[196:199], v153 offset:3072
	ds_read_b128 v[200:203], v153 offset:4096
	ds_read_b128 v[208:211], v153 offset:5120
	ds_read_b128 v[212:215], v153 offset:6144
	ds_read_b128 v[216:219], v153 offset:7168
	global_load_lds_dwordx4 v138, s[6:7]
	s_add_i32 m0, s25, 0xe000
	s_nop 0
	global_load_lds_dwordx4 v136, s[6:7]
	s_waitcnt vmcnt(8)
	s_waitcnt lgkmcnt(0)
	s_barrier
	s_waitcnt lgkmcnt(0)
	v_mfma_f32_16x16x32_bf16 v[124:127], v[144:147], v[184:187], v[124:127]
	v_mfma_f32_16x16x32_bf16 v[120:123], v[160:163], v[184:187], v[120:123]
	v_mfma_f32_16x16x32_bf16 v[108:111], v[144:147], v[192:195], v[108:111]
	v_mfma_f32_16x16x32_bf16 v[104:107], v[160:163], v[192:195], v[104:107]
	v_mfma_f32_16x16x32_bf16 v[92:95], v[144:147], v[200:203], v[92:95]
	v_mfma_f32_16x16x32_bf16 v[88:91], v[160:163], v[200:203], v[88:91]
	v_mfma_f32_16x16x32_bf16 v[76:79], v[144:147], v[212:215], v[76:79]
	v_mfma_f32_16x16x32_bf16 v[72:75], v[160:163], v[212:215], v[72:75]
	v_mfma_f32_16x16x32_bf16 v[124:127], v[156:159], v[188:191], v[124:127]
	v_mfma_f32_16x16x32_bf16 v[120:123], v[164:167], v[188:191], v[120:123]
	v_mfma_f32_16x16x32_bf16 v[108:111], v[156:159], v[196:199], v[108:111]
	v_mfma_f32_16x16x32_bf16 v[104:107], v[164:167], v[196:199], v[104:107]
	v_mfma_f32_16x16x32_bf16 v[92:95], v[156:159], v[208:211], v[92:95]
	v_mfma_f32_16x16x32_bf16 v[88:91], v[164:167], v[208:211], v[88:91]
	v_mfma_f32_16x16x32_bf16 v[76:79], v[156:159], v[216:219], v[76:79]
	v_mfma_f32_16x16x32_bf16 v[72:75], v[164:167], v[216:219], v[72:75]
	v_mfma_f32_16x16x32_bf16 v[116:119], v[168:171], v[184:187], v[116:119]
	v_mfma_f32_16x16x32_bf16 v[112:115], v[176:179], v[184:187], v[112:115]
	v_mfma_f32_16x16x32_bf16 v[100:103], v[168:171], v[192:195], v[100:103]
	v_mfma_f32_16x16x32_bf16 v[96:99], v[176:179], v[192:195], v[96:99]
	v_mfma_f32_16x16x32_bf16 v[84:87], v[168:171], v[200:203], v[84:87]
	v_mfma_f32_16x16x32_bf16 v[80:83], v[176:179], v[200:203], v[80:83]
	v_mfma_f32_16x16x32_bf16 v[68:71], v[168:171], v[212:215], v[68:71]
	v_mfma_f32_16x16x32_bf16 v[64:67], v[176:179], v[212:215], v[64:67]
	v_mfma_f32_16x16x32_bf16 v[116:119], v[172:175], v[188:191], v[116:119]
	v_mfma_f32_16x16x32_bf16 v[112:115], v[180:183], v[188:191], v[112:115]
	v_mfma_f32_16x16x32_bf16 v[100:103], v[172:175], v[196:199], v[100:103]
	v_mfma_f32_16x16x32_bf16 v[96:99], v[180:183], v[196:199], v[96:99]
	v_mfma_f32_16x16x32_bf16 v[84:87], v[172:175], v[208:211], v[84:87]
	v_mfma_f32_16x16x32_bf16 v[80:83], v[180:183], v[208:211], v[80:83]
	v_mfma_f32_16x16x32_bf16 v[68:71], v[172:175], v[216:219], v[68:71]
	v_mfma_f32_16x16x32_bf16 v[64:67], v[180:183], v[216:219], v[64:67]
	s_barrier
	s_add_i32 s54, s45, s38
	s_mov_b32 m0, s54
	ds_read_b128 v[184:187], v153 offset:16384
	ds_read_b128 v[188:191], v153 offset:17408
	ds_read_b128 v[192:195], v153 offset:18432
	ds_read_b128 v[196:199], v153 offset:19456
	ds_read_b128 v[200:203], v153 offset:20480
	ds_read_b128 v[208:211], v153 offset:21504
	ds_read_b128 v[212:215], v153 offset:22528
	ds_read_b128 v[216:219], v153 offset:23552
	global_load_lds_dwordx4 v130, s[26:27]
	s_add_i32 m0, s54, 0x2000
	s_add_u32 s54, s26, 0x40000
	s_mov_b64 s[98:99], s[26:27]
	s_addc_u32 s55, s27, 0
	s_add_i32 s56, s46, s38
	global_load_lds_dwordx4 v134, s[26:27]
	s_mov_b32 m0, s56
	s_mov_b64 s[100:101], s[28:29]
	global_load_lds_dwordx4 v130, s[54:55]
	s_add_i32 m0, s56, 0x2000
	s_nop 0
	global_load_lds_dwordx4 v134, s[54:55]
	s_mov_b32 m0, s25
	s_nop 0
	global_load_lds_dwordx4 v128, s[28:29]
	s_mov_b32 m0, s39
	s_nop 0
	global_load_lds_dwordx4 v132, s[28:29]
	s_waitcnt vmcnt(8)
	s_waitcnt lgkmcnt(0)
	s_barrier
	s_waitcnt lgkmcnt(0)
	v_mfma_f32_16x16x32_bf16 v[60:63], v[144:147], v[184:187], v[60:63]
	v_mfma_f32_16x16x32_bf16 v[56:59], v[160:163], v[184:187], v[56:59]
	v_mfma_f32_16x16x32_bf16 v[44:47], v[144:147], v[192:195], v[44:47]
	v_mfma_f32_16x16x32_bf16 v[40:43], v[160:163], v[192:195], v[40:43]
	v_mfma_f32_16x16x32_bf16 v[28:31], v[144:147], v[200:203], v[28:31]
	v_mfma_f32_16x16x32_bf16 v[24:27], v[160:163], v[200:203], v[24:27]
	v_mfma_f32_16x16x32_bf16 v[12:15], v[144:147], v[212:215], v[12:15]
	v_mfma_f32_16x16x32_bf16 v[8:11], v[160:163], v[212:215], v[8:11]
	v_mfma_f32_16x16x32_bf16 v[60:63], v[156:159], v[188:191], v[60:63]
	v_mfma_f32_16x16x32_bf16 v[56:59], v[164:167], v[188:191], v[56:59]
	v_mfma_f32_16x16x32_bf16 v[44:47], v[156:159], v[196:199], v[44:47]
	v_mfma_f32_16x16x32_bf16 v[40:43], v[164:167], v[196:199], v[40:43]
	v_mfma_f32_16x16x32_bf16 v[28:31], v[156:159], v[208:211], v[28:31]
	v_mfma_f32_16x16x32_bf16 v[24:27], v[164:167], v[208:211], v[24:27]
	v_mfma_f32_16x16x32_bf16 v[12:15], v[156:159], v[216:219], v[12:15]
	v_mfma_f32_16x16x32_bf16 v[8:11], v[164:167], v[216:219], v[8:11]
	v_mfma_f32_16x16x32_bf16 v[52:55], v[168:171], v[184:187], v[52:55]
	v_mfma_f32_16x16x32_bf16 v[48:51], v[176:179], v[184:187], v[48:51]
	v_mfma_f32_16x16x32_bf16 v[36:39], v[168:171], v[192:195], v[36:39]
	v_mfma_f32_16x16x32_bf16 v[32:35], v[176:179], v[192:195], v[32:35]
	v_mfma_f32_16x16x32_bf16 v[20:23], v[168:171], v[200:203], v[20:23]
	v_mfma_f32_16x16x32_bf16 v[16:19], v[176:179], v[200:203], v[16:19]
	v_mfma_f32_16x16x32_bf16 v[4:7], v[168:171], v[212:215], v[4:7]
	v_mfma_f32_16x16x32_bf16 v[0:3], v[176:179], v[212:215], v[0:3]
	v_mfma_f32_16x16x32_bf16 v[52:55], v[172:175], v[188:191], v[52:55]
	v_mfma_f32_16x16x32_bf16 v[48:51], v[180:183], v[188:191], v[48:51]
	v_mfma_f32_16x16x32_bf16 v[36:39], v[172:175], v[196:199], v[36:39]
	v_mfma_f32_16x16x32_bf16 v[32:35], v[180:183], v[196:199], v[32:35]
	v_mfma_f32_16x16x32_bf16 v[20:23], v[172:175], v[208:211], v[20:23]
	v_mfma_f32_16x16x32_bf16 v[16:19], v[180:183], v[208:211], v[16:19]
	v_mfma_f32_16x16x32_bf16 v[4:7], v[172:175], v[216:219], v[4:7]
	v_mfma_f32_16x16x32_bf16 v[0:3], v[180:183], v[216:219], v[0:3]
	s_barrier
	s_add_i32 s54, 0, 0x18000
	v_add_u32_e32 v155, s54, v149
	s_add_i32 s55, 0, 0x1c000
	ds_read_b128 v[144:147], v155
	ds_read_b128 v[156:159], v155 offset:1024
	ds_read_b128 v[160:163], v155 offset:2048
	ds_read_b128 v[164:167], v155 offset:3072
	v_add_u32_e32 v155, s55, v149
	ds_read_b128 v[168:171], v155
	ds_read_b128 v[172:175], v155 offset:1024
	ds_read_b128 v[176:179], v155 offset:2048
	ds_read_b128 v[180:183], v155 offset:3072
	s_add_u32 s28, s28, 0x40000
	s_addc_u32 s29, s29, 0
	s_mov_b32 m0, s40
	ds_read_b128 v[184:187], v153 offset:32768
	ds_read_b128 v[188:191], v153 offset:33792
	ds_read_b128 v[192:195], v153 offset:34816
	ds_read_b128 v[196:199], v153 offset:35840
	ds_read_b128 v[200:203], v153 offset:36864
	ds_read_b128 v[208:211], v153 offset:37888
	ds_read_b128 v[212:215], v153 offset:38912
	ds_read_b128 v[216:219], v153 offset:39936
	global_load_lds_dwordx4 v128, s[28:29]
	s_mov_b32 m0, s41
	s_nop 0
	global_load_lds_dwordx4 v132, s[28:29]
	s_waitcnt vmcnt(8)
	s_waitcnt lgkmcnt(0)
	s_barrier
	s_waitcnt lgkmcnt(0)
	v_mfma_f32_16x16x32_bf16 v[124:127], v[144:147], v[184:187], v[124:127]
	v_mfma_f32_16x16x32_bf16 v[120:123], v[160:163], v[184:187], v[120:123]
	v_mfma_f32_16x16x32_bf16 v[108:111], v[144:147], v[192:195], v[108:111]
	v_mfma_f32_16x16x32_bf16 v[104:107], v[160:163], v[192:195], v[104:107]
	v_mfma_f32_16x16x32_bf16 v[92:95], v[144:147], v[200:203], v[92:95]
	v_mfma_f32_16x16x32_bf16 v[88:91], v[160:163], v[200:203], v[88:91]
	v_mfma_f32_16x16x32_bf16 v[76:79], v[144:147], v[212:215], v[76:79]
	v_mfma_f32_16x16x32_bf16 v[72:75], v[160:163], v[212:215], v[72:75]
	v_mfma_f32_16x16x32_bf16 v[124:127], v[156:159], v[188:191], v[124:127]
	v_mfma_f32_16x16x32_bf16 v[120:123], v[164:167], v[188:191], v[120:123]
	v_mfma_f32_16x16x32_bf16 v[108:111], v[156:159], v[196:199], v[108:111]
	v_mfma_f32_16x16x32_bf16 v[104:107], v[164:167], v[196:199], v[104:107]
	v_mfma_f32_16x16x32_bf16 v[92:95], v[156:159], v[208:211], v[92:95]
	v_mfma_f32_16x16x32_bf16 v[88:91], v[164:167], v[208:211], v[88:91]
	v_mfma_f32_16x16x32_bf16 v[76:79], v[156:159], v[216:219], v[76:79]
	v_mfma_f32_16x16x32_bf16 v[72:75], v[164:167], v[216:219], v[72:75]
	v_mfma_f32_16x16x32_bf16 v[116:119], v[168:171], v[184:187], v[116:119]
	v_mfma_f32_16x16x32_bf16 v[112:115], v[176:179], v[184:187], v[112:115]
	v_mfma_f32_16x16x32_bf16 v[100:103], v[168:171], v[192:195], v[100:103]
	v_mfma_f32_16x16x32_bf16 v[96:99], v[176:179], v[192:195], v[96:99]
	v_mfma_f32_16x16x32_bf16 v[84:87], v[168:171], v[200:203], v[84:87]
	v_mfma_f32_16x16x32_bf16 v[80:83], v[176:179], v[200:203], v[80:83]
	v_mfma_f32_16x16x32_bf16 v[68:71], v[168:171], v[212:215], v[68:71]
	v_mfma_f32_16x16x32_bf16 v[64:67], v[176:179], v[212:215], v[64:67]
	v_mfma_f32_16x16x32_bf16 v[116:119], v[172:175], v[188:191], v[116:119]
	v_mfma_f32_16x16x32_bf16 v[112:115], v[180:183], v[188:191], v[112:115]
	v_mfma_f32_16x16x32_bf16 v[100:103], v[172:175], v[196:199], v[100:103]
	v_mfma_f32_16x16x32_bf16 v[96:99], v[180:183], v[196:199], v[96:99]
	v_mfma_f32_16x16x32_bf16 v[84:87], v[172:175], v[208:211], v[84:87]
	v_mfma_f32_16x16x32_bf16 v[80:83], v[180:183], v[208:211], v[80:83]
	v_mfma_f32_16x16x32_bf16 v[68:71], v[172:175], v[216:219], v[68:71]
	v_mfma_f32_16x16x32_bf16 v[64:67], v[180:183], v[216:219], v[64:67]
	s_barrier
	s_add_i32 s28, s54, s38
	s_mov_b32 m0, s28
	ds_read_b128 v[184:187], v153 offset:49152
	ds_read_b128 v[188:191], v153 offset:50176
	ds_read_b128 v[192:195], v153 offset:51200
	ds_read_b128 v[196:199], v153 offset:52224
	ds_read_b128 v[200:203], v153 offset:53248
	ds_read_b128 v[208:211], v153 offset:54272
	ds_read_b128 v[212:215], v153 offset:55296
	ds_read_b128 v[216:219], v153 offset:56320
	global_load_lds_dwordx4 v205, s[26:27]
	s_add_i32 m0, s28, 0x2000
	s_add_u32 s26, s26, 0x40080
	s_addc_u32 s27, s27, 0
	s_add_i32 s28, s55, s38
	global_load_lds_dwordx4 v221, s[98:99]
	s_mov_b32 m0, s28
	s_nop 0
	global_load_lds_dwordx4 v130, s[26:27]
	s_add_i32 m0, s28, 0x2000
	s_nop 0
	global_load_lds_dwordx4 v134, s[26:27]
	s_mov_b32 m0, s43
	s_nop 0
	global_load_lds_dwordx4 v204, s[100:101]
	s_mov_b32 m0, s44
	s_nop 0
	global_load_lds_dwordx4 v220, s[100:101]
	s_waitcnt vmcnt(8)
	s_waitcnt lgkmcnt(0)
	s_barrier
	s_waitcnt lgkmcnt(0)
	v_mfma_f32_16x16x32_bf16 v[60:63], v[144:147], v[184:187], v[60:63]
	v_mfma_f32_16x16x32_bf16 v[56:59], v[160:163], v[184:187], v[56:59]
	v_mfma_f32_16x16x32_bf16 v[44:47], v[144:147], v[192:195], v[44:47]
	v_mfma_f32_16x16x32_bf16 v[40:43], v[160:163], v[192:195], v[40:43]
	v_mfma_f32_16x16x32_bf16 v[28:31], v[144:147], v[200:203], v[28:31]
	v_mfma_f32_16x16x32_bf16 v[24:27], v[160:163], v[200:203], v[24:27]
	v_mfma_f32_16x16x32_bf16 v[12:15], v[144:147], v[212:215], v[12:15]
	v_mfma_f32_16x16x32_bf16 v[8:11], v[160:163], v[212:215], v[8:11]
	v_mfma_f32_16x16x32_bf16 v[60:63], v[156:159], v[188:191], v[60:63]
	v_mfma_f32_16x16x32_bf16 v[56:59], v[164:167], v[188:191], v[56:59]
	v_mfma_f32_16x16x32_bf16 v[44:47], v[156:159], v[196:199], v[44:47]
	v_mfma_f32_16x16x32_bf16 v[40:43], v[164:167], v[196:199], v[40:43]
	v_mfma_f32_16x16x32_bf16 v[28:31], v[156:159], v[208:211], v[28:31]
	v_mfma_f32_16x16x32_bf16 v[24:27], v[164:167], v[208:211], v[24:27]
	v_mfma_f32_16x16x32_bf16 v[12:15], v[156:159], v[216:219], v[12:15]
	v_mfma_f32_16x16x32_bf16 v[8:11], v[164:167], v[216:219], v[8:11]
	v_mfma_f32_16x16x32_bf16 v[52:55], v[168:171], v[184:187], v[52:55]
	v_mfma_f32_16x16x32_bf16 v[48:51], v[176:179], v[184:187], v[48:51]
	v_mfma_f32_16x16x32_bf16 v[36:39], v[168:171], v[192:195], v[36:39]
	v_mfma_f32_16x16x32_bf16 v[32:35], v[176:179], v[192:195], v[32:35]
	v_mfma_f32_16x16x32_bf16 v[20:23], v[168:171], v[200:203], v[20:23]
	v_mfma_f32_16x16x32_bf16 v[16:19], v[176:179], v[200:203], v[16:19]
	v_mfma_f32_16x16x32_bf16 v[4:7], v[168:171], v[212:215], v[4:7]
	v_mfma_f32_16x16x32_bf16 v[0:3], v[176:179], v[212:215], v[0:3]
	v_mfma_f32_16x16x32_bf16 v[52:55], v[172:175], v[188:191], v[52:55]
	v_mfma_f32_16x16x32_bf16 v[48:51], v[180:183], v[188:191], v[48:51]
	v_mfma_f32_16x16x32_bf16 v[36:39], v[172:175], v[196:199], v[36:39]
	v_mfma_f32_16x16x32_bf16 v[32:35], v[180:183], v[196:199], v[32:35]
	v_mfma_f32_16x16x32_bf16 v[20:23], v[172:175], v[208:211], v[20:23]
	v_mfma_f32_16x16x32_bf16 v[16:19], v[180:183], v[208:211], v[16:19]
	v_mfma_f32_16x16x32_bf16 v[4:7], v[172:175], v[216:219], v[4:7]
	v_mfma_f32_16x16x32_bf16 v[0:3], v[180:183], v[216:219], v[0:3]
	s_barrier
	s_add_i32 s53, s53, 2
	s_add_u32 s51, s51, 0x100
	s_addc_u32 s52, s52, 0
	s_add_u32 s6, s6, 0x100
	s_addc_u32 s7, s7, 0
	s_cmp_gt_u32 s53, 13
	s_cbranch_scc0 .LBB0_988
	s_and_b64 vcc, exec, s[14:15]
	s_cbranch_vccz .LBB0_991
	s_barrier

.LBB0_1192:
	s_ashr_i32 s17, s16, 31
	s_lshl_b64 s[18:19], s[16:17], 18
	s_add_u32 s18, s6, s18
	s_addc_u32 s19, s7, s19
	s_and_b64 s[20:21], s[4:5], exec
	s_cselect_b32 s17, s19, s27
	s_cselect_b32 s46, s18, s26
	s_ashr_i32 s15, s14, 31
	s_lshl_b64 s[20:21], s[14:15], 18
	s_add_u32 s20, s34, s20
	s_addc_u32 s21, s35, s21
	s_and_b64 s[28:29], s[4:5], exec
	s_cselect_b32 s15, s21, s25
	s_cselect_b32 s47, s20, s24
	s_add_u32 s48, s24, 0x100
	s_addc_u32 s49, s25, 0
	s_add_u32 s24, s26, 0x20080
	v_mov_b32_e32 v0, 0
	s_addc_u32 s25, s27, 0
	s_mov_b32 s50, -2
	v_mov_b32_e32 v1, v0
	v_mov_b32_e32 v2, v0
	v_mov_b32_e32 v3, v0
	v_mov_b32_e32 v4, v0
	v_mov_b32_e32 v5, v0
	v_mov_b32_e32 v6, v0
	v_mov_b32_e32 v7, v0
	v_mov_b32_e32 v16, v0
	v_mov_b32_e32 v17, v0
	v_mov_b32_e32 v18, v0
	v_mov_b32_e32 v19, v0
	v_mov_b32_e32 v20, v0
	v_mov_b32_e32 v21, v0
	v_mov_b32_e32 v22, v0
	v_mov_b32_e32 v23, v0
	v_mov_b32_e32 v32, v0
	v_mov_b32_e32 v33, v0
	v_mov_b32_e32 v34, v0
	v_mov_b32_e32 v35, v0
	v_mov_b32_e32 v36, v0
	v_mov_b32_e32 v37, v0
	v_mov_b32_e32 v38, v0
	v_mov_b32_e32 v39, v0
	v_mov_b32_e32 v48, v0
	v_mov_b32_e32 v49, v0
	v_mov_b32_e32 v50, v0
	v_mov_b32_e32 v51, v0
	v_mov_b32_e32 v52, v0
	v_mov_b32_e32 v53, v0
	v_mov_b32_e32 v54, v0
	v_mov_b32_e32 v55, v0
	v_mov_b32_e32 v8, v0
	v_mov_b32_e32 v9, v0
	v_mov_b32_e32 v10, v0
	v_mov_b32_e32 v11, v0
	v_mov_b32_e32 v12, v0
	v_mov_b32_e32 v13, v0
	v_mov_b32_e32 v14, v0
	v_mov_b32_e32 v15, v0
	v_mov_b32_e32 v24, v0
	v_mov_b32_e32 v25, v0
	v_mov_b32_e32 v26, v0
	v_mov_b32_e32 v27, v0
	v_mov_b32_e32 v28, v0
	v_mov_b32_e32 v29, v0
	v_mov_b32_e32 v30, v0
	v_mov_b32_e32 v31, v0
	v_mov_b32_e32 v40, v0
	v_mov_b32_e32 v41, v0
	v_mov_b32_e32 v42, v0
	v_mov_b32_e32 v43, v0
	v_mov_b32_e32 v44, v0
	v_mov_b32_e32 v45, v0
	v_mov_b32_e32 v46, v0
	v_mov_b32_e32 v47, v0
	v_mov_b32_e32 v56, v0
	v_mov_b32_e32 v57, v0
	v_mov_b32_e32 v58, v0
	v_mov_b32_e32 v59, v0
	v_mov_b32_e32 v60, v0
	v_mov_b32_e32 v61, v0
	v_mov_b32_e32 v62, v0
	v_mov_b32_e32 v63, v0
	v_mov_b32_e32 v64, v0
	v_mov_b32_e32 v65, v0
	v_mov_b32_e32 v66, v0
	v_mov_b32_e32 v67, v0
	v_mov_b32_e32 v68, v0
	v_mov_b32_e32 v69, v0
	v_mov_b32_e32 v70, v0
	v_mov_b32_e32 v71, v0
	v_mov_b32_e32 v80, v0
	v_mov_b32_e32 v81, v0
	v_mov_b32_e32 v82, v0
	v_mov_b32_e32 v83, v0
	v_mov_b32_e32 v84, v0
	v_mov_b32_e32 v85, v0
	v_mov_b32_e32 v86, v0
	v_mov_b32_e32 v87, v0
	v_mov_b32_e32 v96, v0
	v_mov_b32_e32 v97, v0
	v_mov_b32_e32 v98, v0
	v_mov_b32_e32 v99, v0
	v_mov_b32_e32 v100, v0
	v_mov_b32_e32 v101, v0
	v_mov_b32_e32 v102, v0
	v_mov_b32_e32 v103, v0
	v_mov_b32_e32 v112, v0
	v_mov_b32_e32 v113, v0
	v_mov_b32_e32 v114, v0
	v_mov_b32_e32 v115, v0
	v_mov_b32_e32 v116, v0
	v_mov_b32_e32 v117, v0
	v_mov_b32_e32 v118, v0
	v_mov_b32_e32 v119, v0
	v_mov_b32_e32 v72, v0
	v_mov_b32_e32 v73, v0
	v_mov_b32_e32 v74, v0
	v_mov_b32_e32 v75, v0
	v_mov_b32_e32 v76, v0
	v_mov_b32_e32 v77, v0
	v_mov_b32_e32 v78, v0
	v_mov_b32_e32 v79, v0
	v_mov_b32_e32 v88, v0
	v_mov_b32_e32 v89, v0
	v_mov_b32_e32 v90, v0
	v_mov_b32_e32 v91, v0
	v_mov_b32_e32 v92, v0
	v_mov_b32_e32 v93, v0
	v_mov_b32_e32 v94, v0
	v_mov_b32_e32 v95, v0
	v_mov_b32_e32 v104, v0
	v_mov_b32_e32 v105, v0
	v_mov_b32_e32 v106, v0
	v_mov_b32_e32 v107, v0
	v_mov_b32_e32 v108, v0
	v_mov_b32_e32 v109, v0
	v_mov_b32_e32 v110, v0
	v_mov_b32_e32 v111, v0
	v_mov_b32_e32 v120, v0
	v_mov_b32_e32 v121, v0
	v_mov_b32_e32 v122, v0
	v_mov_b32_e32 v123, v0
	v_mov_b32_e32 v124, v0
	v_mov_b32_e32 v125, v0
	v_mov_b32_e32 v126, v0
	v_mov_b32_e32 v127, v0
	v_add_u32_e32 v216, 0x80, v128
	v_add_u32_e32 v217, 0x80, v130
	v_add_u32_e32 v218, 0x80, v132
	v_add_u32_e32 v219, 0x80, v134
.LBB0_1193:
	ds_read_b128 v[144:147], v151
	ds_read_b128 v[154:157], v151 offset:1024
	ds_read_b128 v[158:161], v151 offset:2048
	ds_read_b128 v[162:165], v151 offset:3072
	ds_read_b128 v[166:169], v152
	ds_read_b128 v[170:173], v152 offset:1024
	ds_read_b128 v[174:177], v152 offset:2048
	ds_read_b128 v[178:181], v152 offset:3072
	s_add_u32 s26, s24, 0xfffe0080
	s_addc_u32 s27, s25, -1
	s_cmp_eq_u32 s50, 4
	s_cselect_b32 s29, s17, s27
	s_cselect_b32 s28, s46, s26
	s_cselect_b32 s27, s15, s49
	s_cselect_b32 s26, s47, s48
	s_add_i32 m0, s23, 0xc000
	ds_read_b128 v[182:185], v153
	ds_read_b128 v[186:189], v153 offset:1024
	ds_read_b128 v[190:193], v153 offset:2048
	ds_read_b128 v[194:197], v153 offset:3072
	ds_read_b128 v[198:201], v153 offset:4096
	ds_read_b128 v[202:205], v153 offset:5120
	ds_read_b128 v[208:211], v153 offset:6144
	ds_read_b128 v[212:215], v153 offset:7168
	global_load_lds_dwordx4 v138, s[24:25]
	s_add_i32 m0, s23, 0xe000
	s_nop 0
	global_load_lds_dwordx4 v136, s[24:25]
	s_waitcnt vmcnt(8)
	s_waitcnt lgkmcnt(0)
	s_barrier
	s_waitcnt lgkmcnt(0)
	v_mfma_f32_16x16x32_bf16 v[124:127], v[144:147], v[182:185], v[124:127]
	v_mfma_f32_16x16x32_bf16 v[120:123], v[158:161], v[182:185], v[120:123]
	v_mfma_f32_16x16x32_bf16 v[108:111], v[144:147], v[190:193], v[108:111]
	v_mfma_f32_16x16x32_bf16 v[104:107], v[158:161], v[190:193], v[104:107]
	v_mfma_f32_16x16x32_bf16 v[92:95], v[144:147], v[198:201], v[92:95]
	v_mfma_f32_16x16x32_bf16 v[88:91], v[158:161], v[198:201], v[88:91]
	v_mfma_f32_16x16x32_bf16 v[76:79], v[144:147], v[208:211], v[76:79]
	v_mfma_f32_16x16x32_bf16 v[72:75], v[158:161], v[208:211], v[72:75]
	v_mfma_f32_16x16x32_bf16 v[124:127], v[154:157], v[186:189], v[124:127]
	v_mfma_f32_16x16x32_bf16 v[120:123], v[162:165], v[186:189], v[120:123]
	v_mfma_f32_16x16x32_bf16 v[108:111], v[154:157], v[194:197], v[108:111]
	v_mfma_f32_16x16x32_bf16 v[104:107], v[162:165], v[194:197], v[104:107]
	v_mfma_f32_16x16x32_bf16 v[92:95], v[154:157], v[202:205], v[92:95]
	v_mfma_f32_16x16x32_bf16 v[88:91], v[162:165], v[202:205], v[88:91]
	v_mfma_f32_16x16x32_bf16 v[76:79], v[154:157], v[212:215], v[76:79]
	v_mfma_f32_16x16x32_bf16 v[72:75], v[162:165], v[212:215], v[72:75]
	v_mfma_f32_16x16x32_bf16 v[116:119], v[166:169], v[182:185], v[116:119]
	v_mfma_f32_16x16x32_bf16 v[112:115], v[174:177], v[182:185], v[112:115]
	v_mfma_f32_16x16x32_bf16 v[100:103], v[166:169], v[190:193], v[100:103]
	v_mfma_f32_16x16x32_bf16 v[96:99], v[174:177], v[190:193], v[96:99]
	v_mfma_f32_16x16x32_bf16 v[84:87], v[166:169], v[198:201], v[84:87]
	v_mfma_f32_16x16x32_bf16 v[80:83], v[174:177], v[198:201], v[80:83]
	v_mfma_f32_16x16x32_bf16 v[68:71], v[166:169], v[208:211], v[68:71]
	v_mfma_f32_16x16x32_bf16 v[64:67], v[174:177], v[208:211], v[64:67]
	v_mfma_f32_16x16x32_bf16 v[116:119], v[170:173], v[186:189], v[116:119]
	v_mfma_f32_16x16x32_bf16 v[112:115], v[178:181], v[186:189], v[112:115]
	v_mfma_f32_16x16x32_bf16 v[100:103], v[170:173], v[194:197], v[100:103]
	v_mfma_f32_16x16x32_bf16 v[96:99], v[178:181], v[194:197], v[96:99]
	v_mfma_f32_16x16x32_bf16 v[84:87], v[170:173], v[202:205], v[84:87]
	v_mfma_f32_16x16x32_bf16 v[80:83], v[178:181], v[202:205], v[80:83]
	v_mfma_f32_16x16x32_bf16 v[68:71], v[170:173], v[212:215], v[68:71]
	v_mfma_f32_16x16x32_bf16 v[64:67], v[178:181], v[212:215], v[64:67]
	s_barrier
	s_add_i32 s51, s43, s36
	s_mov_b32 m0, s51
	ds_read_b128 v[182:185], v153 offset:16384
	ds_read_b128 v[186:189], v153 offset:17408
	ds_read_b128 v[190:193], v153 offset:18432
	ds_read_b128 v[194:197], v153 offset:19456
	ds_read_b128 v[198:201], v153 offset:20480
	ds_read_b128 v[202:205], v153 offset:21504
	ds_read_b128 v[208:211], v153 offset:22528
	ds_read_b128 v[212:215], v153 offset:23552
	global_load_lds_dwordx4 v130, s[26:27]
	s_add_i32 m0, s51, 0x2000
	s_add_u32 s52, s26, 0x20000
	s_mov_b64 s[98:99], s[26:27]
	s_addc_u32 s53, s27, 0
	s_add_i32 s51, s44, s36
	global_load_lds_dwordx4 v134, s[26:27]
	s_mov_b32 m0, s51
	s_mov_b64 s[100:101], s[28:29]
	global_load_lds_dwordx4 v130, s[52:53]
	s_add_i32 m0, s51, 0x2000
	s_nop 0
	global_load_lds_dwordx4 v134, s[52:53]
	s_mov_b32 m0, s23
	s_nop 0
	global_load_lds_dwordx4 v128, s[28:29]
	s_mov_b32 m0, s37
	s_nop 0
	global_load_lds_dwordx4 v132, s[28:29]
	s_waitcnt vmcnt(8)
	s_waitcnt lgkmcnt(0)
	s_barrier
	s_waitcnt lgkmcnt(0)
	v_mfma_f32_16x16x32_bf16 v[60:63], v[144:147], v[182:185], v[60:63]
	v_mfma_f32_16x16x32_bf16 v[56:59], v[158:161], v[182:185], v[56:59]
	v_mfma_f32_16x16x32_bf16 v[44:47], v[144:147], v[190:193], v[44:47]
	v_mfma_f32_16x16x32_bf16 v[40:43], v[158:161], v[190:193], v[40:43]
	v_mfma_f32_16x16x32_bf16 v[28:31], v[144:147], v[198:201], v[28:31]
	v_mfma_f32_16x16x32_bf16 v[24:27], v[158:161], v[198:201], v[24:27]
	v_mfma_f32_16x16x32_bf16 v[12:15], v[144:147], v[208:211], v[12:15]
	v_mfma_f32_16x16x32_bf16 v[8:11], v[158:161], v[208:211], v[8:11]
	v_mfma_f32_16x16x32_bf16 v[60:63], v[154:157], v[186:189], v[60:63]
	v_mfma_f32_16x16x32_bf16 v[56:59], v[162:165], v[186:189], v[56:59]
	v_mfma_f32_16x16x32_bf16 v[44:47], v[154:157], v[194:197], v[44:47]
	v_mfma_f32_16x16x32_bf16 v[40:43], v[162:165], v[194:197], v[40:43]
	v_mfma_f32_16x16x32_bf16 v[28:31], v[154:157], v[202:205], v[28:31]
	v_mfma_f32_16x16x32_bf16 v[24:27], v[162:165], v[202:205], v[24:27]
	v_mfma_f32_16x16x32_bf16 v[12:15], v[154:157], v[212:215], v[12:15]
	v_mfma_f32_16x16x32_bf16 v[8:11], v[162:165], v[212:215], v[8:11]
	v_mfma_f32_16x16x32_bf16 v[52:55], v[166:169], v[182:185], v[52:55]
	v_mfma_f32_16x16x32_bf16 v[48:51], v[174:177], v[182:185], v[48:51]
	v_mfma_f32_16x16x32_bf16 v[36:39], v[166:169], v[190:193], v[36:39]
	v_mfma_f32_16x16x32_bf16 v[32:35], v[174:177], v[190:193], v[32:35]
	v_mfma_f32_16x16x32_bf16 v[20:23], v[166:169], v[198:201], v[20:23]
	v_mfma_f32_16x16x32_bf16 v[16:19], v[174:177], v[198:201], v[16:19]
	v_mfma_f32_16x16x32_bf16 v[4:7], v[166:169], v[208:211], v[4:7]
	v_mfma_f32_16x16x32_bf16 v[0:3], v[174:177], v[208:211], v[0:3]
	v_mfma_f32_16x16x32_bf16 v[52:55], v[170:173], v[186:189], v[52:55]
	v_mfma_f32_16x16x32_bf16 v[48:51], v[178:181], v[186:189], v[48:51]
	v_mfma_f32_16x16x32_bf16 v[36:39], v[170:173], v[194:197], v[36:39]
	v_mfma_f32_16x16x32_bf16 v[32:35], v[178:181], v[194:197], v[32:35]
	v_mfma_f32_16x16x32_bf16 v[20:23], v[170:173], v[202:205], v[20:23]
	v_mfma_f32_16x16x32_bf16 v[16:19], v[178:181], v[202:205], v[16:19]
	v_mfma_f32_16x16x32_bf16 v[4:7], v[170:173], v[212:215], v[4:7]
	v_mfma_f32_16x16x32_bf16 v[0:3], v[178:181], v[212:215], v[0:3]
	s_barrier
	s_add_i32 s51, 0, 0x18000
	s_add_i32 s52, 0, 0x1c000
	v_add_u32_e32 v162, s51, v149
	v_add_u32_e32 v178, s52, v149
	ds_read_b128 v[144:147], v162
	ds_read_b128 v[154:157], v162 offset:1024
	ds_read_b128 v[158:161], v162 offset:2048
	ds_read_b128 v[162:165], v162 offset:3072
	ds_read_b128 v[166:169], v178
	ds_read_b128 v[170:173], v178 offset:1024
	ds_read_b128 v[174:177], v178 offset:2048
	ds_read_b128 v[178:181], v178 offset:3072
	s_add_u32 s28, s28, 0x20000
	s_addc_u32 s29, s29, 0
	s_mov_b32 m0, s38
	ds_read_b128 v[182:185], v153 offset:32768
	ds_read_b128 v[186:189], v153 offset:33792
	ds_read_b128 v[190:193], v153 offset:34816
	ds_read_b128 v[194:197], v153 offset:35840
	ds_read_b128 v[198:201], v153 offset:36864
	ds_read_b128 v[202:205], v153 offset:37888
	ds_read_b128 v[208:211], v153 offset:38912
	ds_read_b128 v[212:215], v153 offset:39936
	global_load_lds_dwordx4 v128, s[28:29]
	s_mov_b32 m0, s39
	s_nop 0
	global_load_lds_dwordx4 v132, s[28:29]
	s_waitcnt vmcnt(8)
	s_waitcnt lgkmcnt(0)
	s_barrier
	s_waitcnt lgkmcnt(0)
	v_mfma_f32_16x16x32_bf16 v[124:127], v[144:147], v[182:185], v[124:127]
	v_mfma_f32_16x16x32_bf16 v[120:123], v[158:161], v[182:185], v[120:123]
	v_mfma_f32_16x16x32_bf16 v[108:111], v[144:147], v[190:193], v[108:111]
	v_mfma_f32_16x16x32_bf16 v[104:107], v[158:161], v[190:193], v[104:107]
	v_mfma_f32_16x16x32_bf16 v[92:95], v[144:147], v[198:201], v[92:95]
	v_mfma_f32_16x16x32_bf16 v[88:91], v[158:161], v[198:201], v[88:91]
	v_mfma_f32_16x16x32_bf16 v[76:79], v[144:147], v[208:211], v[76:79]
	v_mfma_f32_16x16x32_bf16 v[72:75], v[158:161], v[208:211], v[72:75]
	v_mfma_f32_16x16x32_bf16 v[124:127], v[154:157], v[186:189], v[124:127]
	v_mfma_f32_16x16x32_bf16 v[120:123], v[162:165], v[186:189], v[120:123]
	v_mfma_f32_16x16x32_bf16 v[108:111], v[154:157], v[194:197], v[108:111]
	v_mfma_f32_16x16x32_bf16 v[104:107], v[162:165], v[194:197], v[104:107]
	v_mfma_f32_16x16x32_bf16 v[92:95], v[154:157], v[202:205], v[92:95]
	v_mfma_f32_16x16x32_bf16 v[88:91], v[162:165], v[202:205], v[88:91]
	v_mfma_f32_16x16x32_bf16 v[76:79], v[154:157], v[212:215], v[76:79]
	v_mfma_f32_16x16x32_bf16 v[72:75], v[162:165], v[212:215], v[72:75]
	v_mfma_f32_16x16x32_bf16 v[116:119], v[166:169], v[182:185], v[116:119]
	v_mfma_f32_16x16x32_bf16 v[112:115], v[174:177], v[182:185], v[112:115]
	v_mfma_f32_16x16x32_bf16 v[100:103], v[166:169], v[190:193], v[100:103]
	v_mfma_f32_16x16x32_bf16 v[96:99], v[174:177], v[190:193], v[96:99]
	v_mfma_f32_16x16x32_bf16 v[84:87], v[166:169], v[198:201], v[84:87]
	v_mfma_f32_16x16x32_bf16 v[80:83], v[174:177], v[198:201], v[80:83]
	v_mfma_f32_16x16x32_bf16 v[68:71], v[166:169], v[208:211], v[68:71]
	v_mfma_f32_16x16x32_bf16 v[64:67], v[174:177], v[208:211], v[64:67]
	v_mfma_f32_16x16x32_bf16 v[116:119], v[170:173], v[186:189], v[116:119]
	v_mfma_f32_16x16x32_bf16 v[112:115], v[178:181], v[186:189], v[112:115]
	v_mfma_f32_16x16x32_bf16 v[100:103], v[170:173], v[194:197], v[100:103]
	v_mfma_f32_16x16x32_bf16 v[96:99], v[178:181], v[194:197], v[96:99]
	v_mfma_f32_16x16x32_bf16 v[84:87], v[170:173], v[202:205], v[84:87]
	v_mfma_f32_16x16x32_bf16 v[80:83], v[178:181], v[202:205], v[80:83]
	v_mfma_f32_16x16x32_bf16 v[68:71], v[170:173], v[212:215], v[68:71]
	v_mfma_f32_16x16x32_bf16 v[64:67], v[178:181], v[212:215], v[64:67]
	s_barrier
	s_add_i32 s28, s51, s36
	s_mov_b32 m0, s28
	ds_read_b128 v[182:185], v153 offset:49152
	ds_read_b128 v[186:189], v153 offset:50176
	ds_read_b128 v[190:193], v153 offset:51200
	ds_read_b128 v[194:197], v153 offset:52224
	ds_read_b128 v[198:201], v153 offset:53248
	ds_read_b128 v[202:205], v153 offset:54272
	ds_read_b128 v[208:211], v153 offset:55296
	ds_read_b128 v[212:215], v153 offset:56320
	global_load_lds_dwordx4 v217, s[26:27]
	s_add_i32 m0, s28, 0x2000
	s_add_u32 s26, s26, 0x20080
	s_addc_u32 s27, s27, 0
	s_add_i32 s28, s52, s36
	global_load_lds_dwordx4 v219, s[98:99]
	s_mov_b32 m0, s28
	s_nop 0
	global_load_lds_dwordx4 v130, s[26:27]
	s_add_i32 m0, s28, 0x2000
	s_nop 0
	global_load_lds_dwordx4 v134, s[26:27]
	s_mov_b32 m0, s41
	s_nop 0
	global_load_lds_dwordx4 v216, s[100:101]
	s_mov_b32 m0, s42
	s_nop 0
	global_load_lds_dwordx4 v218, s[100:101]
	s_waitcnt vmcnt(8)
	s_waitcnt lgkmcnt(0)
	s_barrier
	s_waitcnt lgkmcnt(0)
	v_mfma_f32_16x16x32_bf16 v[60:63], v[144:147], v[182:185], v[60:63]
	v_mfma_f32_16x16x32_bf16 v[56:59], v[158:161], v[182:185], v[56:59]
	v_mfma_f32_16x16x32_bf16 v[44:47], v[144:147], v[190:193], v[44:47]
	v_mfma_f32_16x16x32_bf16 v[40:43], v[158:161], v[190:193], v[40:43]
	v_mfma_f32_16x16x32_bf16 v[28:31], v[144:147], v[198:201], v[28:31]
	v_mfma_f32_16x16x32_bf16 v[24:27], v[158:161], v[198:201], v[24:27]
	v_mfma_f32_16x16x32_bf16 v[12:15], v[144:147], v[208:211], v[12:15]
	v_mfma_f32_16x16x32_bf16 v[8:11], v[158:161], v[208:211], v[8:11]
	v_mfma_f32_16x16x32_bf16 v[60:63], v[154:157], v[186:189], v[60:63]
	v_mfma_f32_16x16x32_bf16 v[56:59], v[162:165], v[186:189], v[56:59]
	v_mfma_f32_16x16x32_bf16 v[44:47], v[154:157], v[194:197], v[44:47]
	v_mfma_f32_16x16x32_bf16 v[40:43], v[162:165], v[194:197], v[40:43]
	v_mfma_f32_16x16x32_bf16 v[28:31], v[154:157], v[202:205], v[28:31]
	v_mfma_f32_16x16x32_bf16 v[24:27], v[162:165], v[202:205], v[24:27]
	v_mfma_f32_16x16x32_bf16 v[12:15], v[154:157], v[212:215], v[12:15]
	v_mfma_f32_16x16x32_bf16 v[8:11], v[162:165], v[212:215], v[8:11]
	v_mfma_f32_16x16x32_bf16 v[52:55], v[166:169], v[182:185], v[52:55]
	v_mfma_f32_16x16x32_bf16 v[48:51], v[174:177], v[182:185], v[48:51]
	v_mfma_f32_16x16x32_bf16 v[36:39], v[166:169], v[190:193], v[36:39]
	v_mfma_f32_16x16x32_bf16 v[32:35], v[174:177], v[190:193], v[32:35]
	v_mfma_f32_16x16x32_bf16 v[20:23], v[166:169], v[198:201], v[20:23]
	v_mfma_f32_16x16x32_bf16 v[16:19], v[174:177], v[198:201], v[16:19]
	v_mfma_f32_16x16x32_bf16 v[4:7], v[166:169], v[208:211], v[4:7]
	v_mfma_f32_16x16x32_bf16 v[0:3], v[174:177], v[208:211], v[0:3]
	v_mfma_f32_16x16x32_bf16 v[52:55], v[170:173], v[186:189], v[52:55]
	v_mfma_f32_16x16x32_bf16 v[48:51], v[178:181], v[186:189], v[48:51]
	v_mfma_f32_16x16x32_bf16 v[36:39], v[170:173], v[194:197], v[36:39]
	v_mfma_f32_16x16x32_bf16 v[32:35], v[178:181], v[194:197], v[32:35]
	v_mfma_f32_16x16x32_bf16 v[20:23], v[170:173], v[202:205], v[20:23]
	v_mfma_f32_16x16x32_bf16 v[16:19], v[178:181], v[202:205], v[16:19]
	v_mfma_f32_16x16x32_bf16 v[4:7], v[170:173], v[212:215], v[4:7]
	v_mfma_f32_16x16x32_bf16 v[0:3], v[178:181], v[212:215], v[0:3]
	s_barrier
	s_add_i32 s50, s50, 2
	s_add_u32 s48, s48, 0x100
	s_addc_u32 s49, s49, 0
	s_add_u32 s24, s24, 0x100
	s_addc_u32 s25, s25, 0
	s_cmp_gt_u32 s50, 5
	s_cbranch_scc0 .LBB0_1193
	s_and_b64 vcc, exec, s[12:13]
	s_cbranch_vccz .LBB0_1196
	s_barrier

.LBB0_1364:
	s_ashr_i32 s19, s18, 31
	s_lshl_b64 s[20:21], s[18:19], 19
	s_add_u32 s20, s34, s20
	s_addc_u32 s21, s35, s21
	s_and_b64 s[22:23], s[4:5], exec
	s_cselect_b32 s19, s21, s27
	s_cselect_b32 s49, s20, s26
	s_ashr_i32 s17, s16, 31
	s_lshl_b64 s[22:23], s[16:17], 19
	s_add_u32 s22, s36, s22
	s_addc_u32 s23, s37, s23
	s_and_b64 s[28:29], s[4:5], exec
	s_cselect_b32 s17, s23, s25
	s_cselect_b32 s50, s22, s24
	s_add_u32 s51, s24, 0x100
	s_addc_u32 s52, s25, 0
	s_add_u32 s24, s26, 0x40080
	v_mov_b32_e32 v0, 0
	s_addc_u32 s25, s27, 0
	s_mov_b32 s53, -2
	v_mov_b32_e32 v1, v0
	v_mov_b32_e32 v2, v0
	v_mov_b32_e32 v3, v0
	v_mov_b32_e32 v4, v0
	v_mov_b32_e32 v5, v0
	v_mov_b32_e32 v6, v0
	v_mov_b32_e32 v7, v0
	v_mov_b32_e32 v16, v0
	v_mov_b32_e32 v17, v0
	v_mov_b32_e32 v18, v0
	v_mov_b32_e32 v19, v0
	v_mov_b32_e32 v20, v0
	v_mov_b32_e32 v21, v0
	v_mov_b32_e32 v22, v0
	v_mov_b32_e32 v23, v0
	v_mov_b32_e32 v32, v0
	v_mov_b32_e32 v33, v0
	v_mov_b32_e32 v34, v0
	v_mov_b32_e32 v35, v0
	v_mov_b32_e32 v36, v0
	v_mov_b32_e32 v37, v0
	v_mov_b32_e32 v38, v0
	v_mov_b32_e32 v39, v0
	v_mov_b32_e32 v48, v0
	v_mov_b32_e32 v49, v0
	v_mov_b32_e32 v50, v0
	v_mov_b32_e32 v51, v0
	v_mov_b32_e32 v52, v0
	v_mov_b32_e32 v53, v0
	v_mov_b32_e32 v54, v0
	v_mov_b32_e32 v55, v0
	v_mov_b32_e32 v8, v0
	v_mov_b32_e32 v9, v0
	v_mov_b32_e32 v10, v0
	v_mov_b32_e32 v11, v0
	v_mov_b32_e32 v12, v0
	v_mov_b32_e32 v13, v0
	v_mov_b32_e32 v14, v0
	v_mov_b32_e32 v15, v0
	v_mov_b32_e32 v24, v0
	v_mov_b32_e32 v25, v0
	v_mov_b32_e32 v26, v0
	v_mov_b32_e32 v27, v0
	v_mov_b32_e32 v28, v0
	v_mov_b32_e32 v29, v0
	v_mov_b32_e32 v30, v0
	v_mov_b32_e32 v31, v0
	v_mov_b32_e32 v40, v0
	v_mov_b32_e32 v41, v0
	v_mov_b32_e32 v42, v0
	v_mov_b32_e32 v43, v0
	v_mov_b32_e32 v44, v0
	v_mov_b32_e32 v45, v0
	v_mov_b32_e32 v46, v0
	v_mov_b32_e32 v47, v0
	v_mov_b32_e32 v56, v0
	v_mov_b32_e32 v57, v0
	v_mov_b32_e32 v58, v0
	v_mov_b32_e32 v59, v0
	v_mov_b32_e32 v60, v0
	v_mov_b32_e32 v61, v0
	v_mov_b32_e32 v62, v0
	v_mov_b32_e32 v63, v0
	v_mov_b32_e32 v64, v0
	v_mov_b32_e32 v65, v0
	v_mov_b32_e32 v66, v0
	v_mov_b32_e32 v67, v0
	v_mov_b32_e32 v68, v0
	v_mov_b32_e32 v69, v0
	v_mov_b32_e32 v70, v0
	v_mov_b32_e32 v71, v0
	v_mov_b32_e32 v80, v0
	v_mov_b32_e32 v81, v0
	v_mov_b32_e32 v82, v0
	v_mov_b32_e32 v83, v0
	v_mov_b32_e32 v84, v0
	v_mov_b32_e32 v85, v0
	v_mov_b32_e32 v86, v0
	v_mov_b32_e32 v87, v0
	v_mov_b32_e32 v96, v0
	v_mov_b32_e32 v97, v0
	v_mov_b32_e32 v98, v0
	v_mov_b32_e32 v99, v0
	v_mov_b32_e32 v100, v0
	v_mov_b32_e32 v101, v0
	v_mov_b32_e32 v102, v0
	v_mov_b32_e32 v103, v0
	v_mov_b32_e32 v112, v0
	v_mov_b32_e32 v113, v0
	v_mov_b32_e32 v114, v0
	v_mov_b32_e32 v115, v0
	v_mov_b32_e32 v116, v0
	v_mov_b32_e32 v117, v0
	v_mov_b32_e32 v118, v0
	v_mov_b32_e32 v119, v0
	v_mov_b32_e32 v72, v0
	v_mov_b32_e32 v73, v0
	v_mov_b32_e32 v74, v0
	v_mov_b32_e32 v75, v0
	v_mov_b32_e32 v76, v0
	v_mov_b32_e32 v77, v0
	v_mov_b32_e32 v78, v0
	v_mov_b32_e32 v79, v0
	v_mov_b32_e32 v88, v0
	v_mov_b32_e32 v89, v0
	v_mov_b32_e32 v90, v0
	v_mov_b32_e32 v91, v0
	v_mov_b32_e32 v92, v0
	v_mov_b32_e32 v93, v0
	v_mov_b32_e32 v94, v0
	v_mov_b32_e32 v95, v0
	v_mov_b32_e32 v104, v0
	v_mov_b32_e32 v105, v0
	v_mov_b32_e32 v106, v0
	v_mov_b32_e32 v107, v0
	v_mov_b32_e32 v108, v0
	v_mov_b32_e32 v109, v0
	v_mov_b32_e32 v110, v0
	v_mov_b32_e32 v111, v0
	v_mov_b32_e32 v120, v0
	v_mov_b32_e32 v121, v0
	v_mov_b32_e32 v122, v0
	v_mov_b32_e32 v123, v0
	v_mov_b32_e32 v124, v0
	v_mov_b32_e32 v125, v0
	v_mov_b32_e32 v126, v0
	v_mov_b32_e32 v127, v0
	v_add_u32_e32 v204, 0x80, v128
	v_add_u32_e32 v205, 0x80, v130
	v_add_u32_e32 v220, 0x80, v132
	v_add_u32_e32 v221, 0x80, v134
.LBB0_1365:
	ds_read_b128 v[144:147], v151
	ds_read_b128 v[156:159], v151 offset:1024
	ds_read_b128 v[160:163], v151 offset:2048
	ds_read_b128 v[164:167], v151 offset:3072
	ds_read_b128 v[168:171], v152
	ds_read_b128 v[172:175], v152 offset:1024
	ds_read_b128 v[176:179], v152 offset:2048
	ds_read_b128 v[180:183], v152 offset:3072
	s_add_u32 s26, s24, 0xfffc0080
	s_addc_u32 s27, s25, -1
	s_cmp_eq_u32 s53, 12
	s_cselect_b32 s29, s19, s27
	s_cselect_b32 s28, s49, s26
	s_cselect_b32 s27, s17, s52
	s_cselect_b32 s26, s50, s51
	s_add_i32 m0, s39, 0xc000
	ds_read_b128 v[184:187], v153
	ds_read_b128 v[188:191], v153 offset:1024
	ds_read_b128 v[192:195], v153 offset:2048
	ds_read_b128 v[196:199], v153 offset:3072
	ds_read_b128 v[200:203], v153 offset:4096
	ds_read_b128 v[208:211], v153 offset:5120
	ds_read_b128 v[212:215], v153 offset:6144
	ds_read_b128 v[216:219], v153 offset:7168
	global_load_lds_dwordx4 v138, s[24:25]
	s_add_i32 m0, s39, 0xe000
	s_nop 0
	global_load_lds_dwordx4 v136, s[24:25]
	s_waitcnt vmcnt(8)
	s_waitcnt lgkmcnt(0)
	s_barrier
	s_waitcnt lgkmcnt(0)
	v_mfma_f32_16x16x32_bf16 v[124:127], v[144:147], v[184:187], v[124:127]
	v_mfma_f32_16x16x32_bf16 v[120:123], v[160:163], v[184:187], v[120:123]
	v_mfma_f32_16x16x32_bf16 v[108:111], v[144:147], v[192:195], v[108:111]
	v_mfma_f32_16x16x32_bf16 v[104:107], v[160:163], v[192:195], v[104:107]
	v_mfma_f32_16x16x32_bf16 v[92:95], v[144:147], v[200:203], v[92:95]
	v_mfma_f32_16x16x32_bf16 v[88:91], v[160:163], v[200:203], v[88:91]
	v_mfma_f32_16x16x32_bf16 v[76:79], v[144:147], v[212:215], v[76:79]
	v_mfma_f32_16x16x32_bf16 v[72:75], v[160:163], v[212:215], v[72:75]
	v_mfma_f32_16x16x32_bf16 v[124:127], v[156:159], v[188:191], v[124:127]
	v_mfma_f32_16x16x32_bf16 v[120:123], v[164:167], v[188:191], v[120:123]
	v_mfma_f32_16x16x32_bf16 v[108:111], v[156:159], v[196:199], v[108:111]
	v_mfma_f32_16x16x32_bf16 v[104:107], v[164:167], v[196:199], v[104:107]
	v_mfma_f32_16x16x32_bf16 v[92:95], v[156:159], v[208:211], v[92:95]
	v_mfma_f32_16x16x32_bf16 v[88:91], v[164:167], v[208:211], v[88:91]
	v_mfma_f32_16x16x32_bf16 v[76:79], v[156:159], v[216:219], v[76:79]
	v_mfma_f32_16x16x32_bf16 v[72:75], v[164:167], v[216:219], v[72:75]
	v_mfma_f32_16x16x32_bf16 v[116:119], v[168:171], v[184:187], v[116:119]
	v_mfma_f32_16x16x32_bf16 v[112:115], v[176:179], v[184:187], v[112:115]
	v_mfma_f32_16x16x32_bf16 v[100:103], v[168:171], v[192:195], v[100:103]
	v_mfma_f32_16x16x32_bf16 v[96:99], v[176:179], v[192:195], v[96:99]
	v_mfma_f32_16x16x32_bf16 v[84:87], v[168:171], v[200:203], v[84:87]
	v_mfma_f32_16x16x32_bf16 v[80:83], v[176:179], v[200:203], v[80:83]
	v_mfma_f32_16x16x32_bf16 v[68:71], v[168:171], v[212:215], v[68:71]
	v_mfma_f32_16x16x32_bf16 v[64:67], v[176:179], v[212:215], v[64:67]
	v_mfma_f32_16x16x32_bf16 v[116:119], v[172:175], v[188:191], v[116:119]
	v_mfma_f32_16x16x32_bf16 v[112:115], v[180:183], v[188:191], v[112:115]
	v_mfma_f32_16x16x32_bf16 v[100:103], v[172:175], v[196:199], v[100:103]
	v_mfma_f32_16x16x32_bf16 v[96:99], v[180:183], v[196:199], v[96:99]
	v_mfma_f32_16x16x32_bf16 v[84:87], v[172:175], v[208:211], v[84:87]
	v_mfma_f32_16x16x32_bf16 v[80:83], v[180:183], v[208:211], v[80:83]
	v_mfma_f32_16x16x32_bf16 v[68:71], v[172:175], v[216:219], v[68:71]
	v_mfma_f32_16x16x32_bf16 v[64:67], v[180:183], v[216:219], v[64:67]
	s_barrier
	s_add_i32 s54, s46, s38
	s_mov_b32 m0, s54
	ds_read_b128 v[184:187], v153 offset:16384
	ds_read_b128 v[188:191], v153 offset:17408
	ds_read_b128 v[192:195], v153 offset:18432
	ds_read_b128 v[196:199], v153 offset:19456
	ds_read_b128 v[200:203], v153 offset:20480
	ds_read_b128 v[208:211], v153 offset:21504
	ds_read_b128 v[212:215], v153 offset:22528
	ds_read_b128 v[216:219], v153 offset:23552
	global_load_lds_dwordx4 v130, s[26:27]
	s_add_i32 m0, s54, 0x2000
	s_add_u32 s54, s26, 0x40000
	s_mov_b64 s[98:99], s[26:27]
	s_addc_u32 s55, s27, 0
	s_add_i32 s56, s47, s38
	global_load_lds_dwordx4 v134, s[26:27]
	s_mov_b32 m0, s56
	s_mov_b64 s[100:101], s[28:29]
	global_load_lds_dwordx4 v130, s[54:55]
	s_add_i32 m0, s56, 0x2000
	s_nop 0
	global_load_lds_dwordx4 v134, s[54:55]
	s_mov_b32 m0, s39
	s_nop 0
	global_load_lds_dwordx4 v128, s[28:29]
	s_mov_b32 m0, s40
	s_nop 0
	global_load_lds_dwordx4 v132, s[28:29]
	s_waitcnt vmcnt(8)
	s_waitcnt lgkmcnt(0)
	s_barrier
	s_waitcnt lgkmcnt(0)
	v_mfma_f32_16x16x32_bf16 v[60:63], v[144:147], v[184:187], v[60:63]
	v_mfma_f32_16x16x32_bf16 v[56:59], v[160:163], v[184:187], v[56:59]
	v_mfma_f32_16x16x32_bf16 v[44:47], v[144:147], v[192:195], v[44:47]
	v_mfma_f32_16x16x32_bf16 v[40:43], v[160:163], v[192:195], v[40:43]
	v_mfma_f32_16x16x32_bf16 v[28:31], v[144:147], v[200:203], v[28:31]
	v_mfma_f32_16x16x32_bf16 v[24:27], v[160:163], v[200:203], v[24:27]
	v_mfma_f32_16x16x32_bf16 v[12:15], v[144:147], v[212:215], v[12:15]
	v_mfma_f32_16x16x32_bf16 v[8:11], v[160:163], v[212:215], v[8:11]
	v_mfma_f32_16x16x32_bf16 v[60:63], v[156:159], v[188:191], v[60:63]
	v_mfma_f32_16x16x32_bf16 v[56:59], v[164:167], v[188:191], v[56:59]
	v_mfma_f32_16x16x32_bf16 v[44:47], v[156:159], v[196:199], v[44:47]
	v_mfma_f32_16x16x32_bf16 v[40:43], v[164:167], v[196:199], v[40:43]
	v_mfma_f32_16x16x32_bf16 v[28:31], v[156:159], v[208:211], v[28:31]
	v_mfma_f32_16x16x32_bf16 v[24:27], v[164:167], v[208:211], v[24:27]
	v_mfma_f32_16x16x32_bf16 v[12:15], v[156:159], v[216:219], v[12:15]
	v_mfma_f32_16x16x32_bf16 v[8:11], v[164:167], v[216:219], v[8:11]
	v_mfma_f32_16x16x32_bf16 v[52:55], v[168:171], v[184:187], v[52:55]
	v_mfma_f32_16x16x32_bf16 v[48:51], v[176:179], v[184:187], v[48:51]
	v_mfma_f32_16x16x32_bf16 v[36:39], v[168:171], v[192:195], v[36:39]
	v_mfma_f32_16x16x32_bf16 v[32:35], v[176:179], v[192:195], v[32:35]
	v_mfma_f32_16x16x32_bf16 v[20:23], v[168:171], v[200:203], v[20:23]
	v_mfma_f32_16x16x32_bf16 v[16:19], v[176:179], v[200:203], v[16:19]
	v_mfma_f32_16x16x32_bf16 v[4:7], v[168:171], v[212:215], v[4:7]
	v_mfma_f32_16x16x32_bf16 v[0:3], v[176:179], v[212:215], v[0:3]
	v_mfma_f32_16x16x32_bf16 v[52:55], v[172:175], v[188:191], v[52:55]
	v_mfma_f32_16x16x32_bf16 v[48:51], v[180:183], v[188:191], v[48:51]
	v_mfma_f32_16x16x32_bf16 v[36:39], v[172:175], v[196:199], v[36:39]
	v_mfma_f32_16x16x32_bf16 v[32:35], v[180:183], v[196:199], v[32:35]
	v_mfma_f32_16x16x32_bf16 v[20:23], v[172:175], v[208:211], v[20:23]
	v_mfma_f32_16x16x32_bf16 v[16:19], v[180:183], v[208:211], v[16:19]
	v_mfma_f32_16x16x32_bf16 v[4:7], v[172:175], v[216:219], v[4:7]
	v_mfma_f32_16x16x32_bf16 v[0:3], v[180:183], v[216:219], v[0:3]
	s_barrier
	s_add_i32 s54, 0, 0x18000
	v_add_u32_e32 v155, s54, v149
	s_add_i32 s55, 0, 0x1c000
	ds_read_b128 v[144:147], v155
	ds_read_b128 v[156:159], v155 offset:1024
	ds_read_b128 v[160:163], v155 offset:2048
	ds_read_b128 v[164:167], v155 offset:3072
	v_add_u32_e32 v155, s55, v149
	ds_read_b128 v[168:171], v155
	ds_read_b128 v[172:175], v155 offset:1024
	ds_read_b128 v[176:179], v155 offset:2048
	ds_read_b128 v[180:183], v155 offset:3072
	s_add_u32 s28, s28, 0x40000
	s_addc_u32 s29, s29, 0
	s_mov_b32 m0, s41
	ds_read_b128 v[184:187], v153 offset:32768
	ds_read_b128 v[188:191], v153 offset:33792
	ds_read_b128 v[192:195], v153 offset:34816
	ds_read_b128 v[196:199], v153 offset:35840
	ds_read_b128 v[200:203], v153 offset:36864
	ds_read_b128 v[208:211], v153 offset:37888
	ds_read_b128 v[212:215], v153 offset:38912
	ds_read_b128 v[216:219], v153 offset:39936
	global_load_lds_dwordx4 v128, s[28:29]
	s_mov_b32 m0, s42
	s_nop 0
	global_load_lds_dwordx4 v132, s[28:29]
	s_waitcnt vmcnt(8)
	s_waitcnt lgkmcnt(0)
	s_barrier
	s_waitcnt lgkmcnt(0)
	v_mfma_f32_16x16x32_bf16 v[124:127], v[144:147], v[184:187], v[124:127]
	v_mfma_f32_16x16x32_bf16 v[120:123], v[160:163], v[184:187], v[120:123]
	v_mfma_f32_16x16x32_bf16 v[108:111], v[144:147], v[192:195], v[108:111]
	v_mfma_f32_16x16x32_bf16 v[104:107], v[160:163], v[192:195], v[104:107]
	v_mfma_f32_16x16x32_bf16 v[92:95], v[144:147], v[200:203], v[92:95]
	v_mfma_f32_16x16x32_bf16 v[88:91], v[160:163], v[200:203], v[88:91]
	v_mfma_f32_16x16x32_bf16 v[76:79], v[144:147], v[212:215], v[76:79]
	v_mfma_f32_16x16x32_bf16 v[72:75], v[160:163], v[212:215], v[72:75]
	v_mfma_f32_16x16x32_bf16 v[124:127], v[156:159], v[188:191], v[124:127]
	v_mfma_f32_16x16x32_bf16 v[120:123], v[164:167], v[188:191], v[120:123]
	v_mfma_f32_16x16x32_bf16 v[108:111], v[156:159], v[196:199], v[108:111]
	v_mfma_f32_16x16x32_bf16 v[104:107], v[164:167], v[196:199], v[104:107]
	v_mfma_f32_16x16x32_bf16 v[92:95], v[156:159], v[208:211], v[92:95]
	v_mfma_f32_16x16x32_bf16 v[88:91], v[164:167], v[208:211], v[88:91]
	v_mfma_f32_16x16x32_bf16 v[76:79], v[156:159], v[216:219], v[76:79]
	v_mfma_f32_16x16x32_bf16 v[72:75], v[164:167], v[216:219], v[72:75]
	v_mfma_f32_16x16x32_bf16 v[116:119], v[168:171], v[184:187], v[116:119]
	v_mfma_f32_16x16x32_bf16 v[112:115], v[176:179], v[184:187], v[112:115]
	v_mfma_f32_16x16x32_bf16 v[100:103], v[168:171], v[192:195], v[100:103]
	v_mfma_f32_16x16x32_bf16 v[96:99], v[176:179], v[192:195], v[96:99]
	v_mfma_f32_16x16x32_bf16 v[84:87], v[168:171], v[200:203], v[84:87]
	v_mfma_f32_16x16x32_bf16 v[80:83], v[176:179], v[200:203], v[80:83]
	v_mfma_f32_16x16x32_bf16 v[68:71], v[168:171], v[212:215], v[68:71]
	v_mfma_f32_16x16x32_bf16 v[64:67], v[176:179], v[212:215], v[64:67]
	v_mfma_f32_16x16x32_bf16 v[116:119], v[172:175], v[188:191], v[116:119]
	v_mfma_f32_16x16x32_bf16 v[112:115], v[180:183], v[188:191], v[112:115]
	v_mfma_f32_16x16x32_bf16 v[100:103], v[172:175], v[196:199], v[100:103]
	v_mfma_f32_16x16x32_bf16 v[96:99], v[180:183], v[196:199], v[96:99]
	v_mfma_f32_16x16x32_bf16 v[84:87], v[172:175], v[208:211], v[84:87]
	v_mfma_f32_16x16x32_bf16 v[80:83], v[180:183], v[208:211], v[80:83]
	v_mfma_f32_16x16x32_bf16 v[68:71], v[172:175], v[216:219], v[68:71]
	v_mfma_f32_16x16x32_bf16 v[64:67], v[180:183], v[216:219], v[64:67]
	s_barrier
	s_add_i32 s28, s54, s38
	s_mov_b32 m0, s28
	ds_read_b128 v[184:187], v153 offset:49152
	ds_read_b128 v[188:191], v153 offset:50176
	ds_read_b128 v[192:195], v153 offset:51200
	ds_read_b128 v[196:199], v153 offset:52224
	ds_read_b128 v[200:203], v153 offset:53248
	ds_read_b128 v[208:211], v153 offset:54272
	ds_read_b128 v[212:215], v153 offset:55296
	ds_read_b128 v[216:219], v153 offset:56320
	global_load_lds_dwordx4 v205, s[26:27]
	s_add_i32 m0, s28, 0x2000
	s_add_u32 s26, s26, 0x40080
	s_addc_u32 s27, s27, 0
	s_add_i32 s28, s55, s38
	global_load_lds_dwordx4 v221, s[98:99]
	s_mov_b32 m0, s28
	s_nop 0
	global_load_lds_dwordx4 v130, s[26:27]
	s_add_i32 m0, s28, 0x2000
	s_nop 0
	global_load_lds_dwordx4 v134, s[26:27]
	s_mov_b32 m0, s44
	s_nop 0
	global_load_lds_dwordx4 v204, s[100:101]
	s_mov_b32 m0, s45
	s_nop 0
	global_load_lds_dwordx4 v220, s[100:101]
	s_waitcnt vmcnt(8)
	s_waitcnt lgkmcnt(0)
	s_barrier
	s_waitcnt lgkmcnt(0)
	v_mfma_f32_16x16x32_bf16 v[60:63], v[144:147], v[184:187], v[60:63]
	v_mfma_f32_16x16x32_bf16 v[56:59], v[160:163], v[184:187], v[56:59]
	v_mfma_f32_16x16x32_bf16 v[44:47], v[144:147], v[192:195], v[44:47]
	v_mfma_f32_16x16x32_bf16 v[40:43], v[160:163], v[192:195], v[40:43]
	v_mfma_f32_16x16x32_bf16 v[28:31], v[144:147], v[200:203], v[28:31]
	v_mfma_f32_16x16x32_bf16 v[24:27], v[160:163], v[200:203], v[24:27]
	v_mfma_f32_16x16x32_bf16 v[12:15], v[144:147], v[212:215], v[12:15]
	v_mfma_f32_16x16x32_bf16 v[8:11], v[160:163], v[212:215], v[8:11]
	v_mfma_f32_16x16x32_bf16 v[60:63], v[156:159], v[188:191], v[60:63]
	v_mfma_f32_16x16x32_bf16 v[56:59], v[164:167], v[188:191], v[56:59]
	v_mfma_f32_16x16x32_bf16 v[44:47], v[156:159], v[196:199], v[44:47]
	v_mfma_f32_16x16x32_bf16 v[40:43], v[164:167], v[196:199], v[40:43]
	v_mfma_f32_16x16x32_bf16 v[28:31], v[156:159], v[208:211], v[28:31]
	v_mfma_f32_16x16x32_bf16 v[24:27], v[164:167], v[208:211], v[24:27]
	v_mfma_f32_16x16x32_bf16 v[12:15], v[156:159], v[216:219], v[12:15]
	v_mfma_f32_16x16x32_bf16 v[8:11], v[164:167], v[216:219], v[8:11]
	v_mfma_f32_16x16x32_bf16 v[52:55], v[168:171], v[184:187], v[52:55]
	v_mfma_f32_16x16x32_bf16 v[48:51], v[176:179], v[184:187], v[48:51]
	v_mfma_f32_16x16x32_bf16 v[36:39], v[168:171], v[192:195], v[36:39]
	v_mfma_f32_16x16x32_bf16 v[32:35], v[176:179], v[192:195], v[32:35]
	v_mfma_f32_16x16x32_bf16 v[20:23], v[168:171], v[200:203], v[20:23]
	v_mfma_f32_16x16x32_bf16 v[16:19], v[176:179], v[200:203], v[16:19]
	v_mfma_f32_16x16x32_bf16 v[4:7], v[168:171], v[212:215], v[4:7]
	v_mfma_f32_16x16x32_bf16 v[0:3], v[176:179], v[212:215], v[0:3]
	v_mfma_f32_16x16x32_bf16 v[52:55], v[172:175], v[188:191], v[52:55]
	v_mfma_f32_16x16x32_bf16 v[48:51], v[180:183], v[188:191], v[48:51]
	v_mfma_f32_16x16x32_bf16 v[36:39], v[172:175], v[196:199], v[36:39]
	v_mfma_f32_16x16x32_bf16 v[32:35], v[180:183], v[196:199], v[32:35]
	v_mfma_f32_16x16x32_bf16 v[20:23], v[172:175], v[208:211], v[20:23]
	v_mfma_f32_16x16x32_bf16 v[16:19], v[180:183], v[208:211], v[16:19]
	v_mfma_f32_16x16x32_bf16 v[4:7], v[172:175], v[216:219], v[4:7]
	v_mfma_f32_16x16x32_bf16 v[0:3], v[180:183], v[216:219], v[0:3]
	s_barrier
	s_add_i32 s53, s53, 2
	s_add_u32 s51, s51, 0x100
	s_addc_u32 s52, s52, 0
	s_add_u32 s24, s24, 0x100
	s_addc_u32 s25, s25, 0
	s_cmp_gt_u32 s53, 13
	s_cbranch_scc0 .LBB0_1365
	s_and_b64 vcc, exec, s[14:15]
	s_cbranch_vccz .LBB0_1368
	s_barrier

.LBB0_1560:
	s_ashr_i32 s29, s28, 31
	s_lshl_b64 s[30:31], s[28:29], 19
	s_add_u32 s30, s12, s30
	s_addc_u32 s31, s13, s31
	s_and_b64 s[34:35], s[6:7], exec
	s_cselect_b32 s3, s31, s39
	s_cselect_b32 s29, s30, s38
	s_ashr_i32 s27, s26, 31
	s_lshl_b64 s[34:35], s[26:27], 19
	s_add_u32 s34, s43, s34
	s_addc_u32 s35, s44, s35
	s_and_b64 s[40:41], s[6:7], exec
	s_cselect_b32 s27, s35, s37
	s_cselect_b32 s58, s34, s36
	s_add_u32 s59, s36, 0x100
	s_addc_u32 s60, s37, 0
	s_add_u32 s36, s38, 0x40080
	v_mov_b32_e32 v0, 0
	s_addc_u32 s37, s39, 0
	s_mov_b32 s61, -2
	v_mov_b32_e32 v1, v0
	v_mov_b32_e32 v2, v0
	v_mov_b32_e32 v3, v0
	v_mov_b32_e32 v4, v0
	v_mov_b32_e32 v5, v0
	v_mov_b32_e32 v6, v0
	v_mov_b32_e32 v7, v0
	v_mov_b32_e32 v16, v0
	v_mov_b32_e32 v17, v0
	v_mov_b32_e32 v18, v0
	v_mov_b32_e32 v19, v0
	v_mov_b32_e32 v20, v0
	v_mov_b32_e32 v21, v0
	v_mov_b32_e32 v22, v0
	v_mov_b32_e32 v23, v0
	v_mov_b32_e32 v32, v0
	v_mov_b32_e32 v33, v0
	v_mov_b32_e32 v34, v0
	v_mov_b32_e32 v35, v0
	v_mov_b32_e32 v36, v0
	v_mov_b32_e32 v37, v0
	v_mov_b32_e32 v38, v0
	v_mov_b32_e32 v39, v0
	v_mov_b32_e32 v48, v0
	v_mov_b32_e32 v49, v0
	v_mov_b32_e32 v50, v0
	v_mov_b32_e32 v51, v0
	v_mov_b32_e32 v52, v0
	v_mov_b32_e32 v53, v0
	v_mov_b32_e32 v54, v0
	v_mov_b32_e32 v55, v0
	v_mov_b32_e32 v8, v0
	v_mov_b32_e32 v9, v0
	v_mov_b32_e32 v10, v0
	v_mov_b32_e32 v11, v0
	v_mov_b32_e32 v12, v0
	v_mov_b32_e32 v13, v0
	v_mov_b32_e32 v14, v0
	v_mov_b32_e32 v15, v0
	v_mov_b32_e32 v24, v0
	v_mov_b32_e32 v25, v0
	v_mov_b32_e32 v26, v0
	v_mov_b32_e32 v27, v0
	v_mov_b32_e32 v28, v0
	v_mov_b32_e32 v29, v0
	v_mov_b32_e32 v30, v0
	v_mov_b32_e32 v31, v0
	v_mov_b32_e32 v40, v0
	v_mov_b32_e32 v41, v0
	v_mov_b32_e32 v42, v0
	v_mov_b32_e32 v43, v0
	v_mov_b32_e32 v44, v0
	v_mov_b32_e32 v45, v0
	v_mov_b32_e32 v46, v0
	v_mov_b32_e32 v47, v0
	v_mov_b32_e32 v56, v0
	v_mov_b32_e32 v57, v0
	v_mov_b32_e32 v58, v0
	v_mov_b32_e32 v59, v0
	v_mov_b32_e32 v60, v0
	v_mov_b32_e32 v61, v0
	v_mov_b32_e32 v62, v0
	v_mov_b32_e32 v63, v0
	v_mov_b32_e32 v64, v0
	v_mov_b32_e32 v65, v0
	v_mov_b32_e32 v66, v0
	v_mov_b32_e32 v67, v0
	v_mov_b32_e32 v68, v0
	v_mov_b32_e32 v69, v0
	v_mov_b32_e32 v70, v0
	v_mov_b32_e32 v71, v0
	v_mov_b32_e32 v80, v0
	v_mov_b32_e32 v81, v0
	v_mov_b32_e32 v82, v0
	v_mov_b32_e32 v83, v0
	v_mov_b32_e32 v84, v0
	v_mov_b32_e32 v85, v0
	v_mov_b32_e32 v86, v0
	v_mov_b32_e32 v87, v0
	v_mov_b32_e32 v96, v0
	v_mov_b32_e32 v97, v0
	v_mov_b32_e32 v98, v0
	v_mov_b32_e32 v99, v0
	v_mov_b32_e32 v100, v0
	v_mov_b32_e32 v101, v0
	v_mov_b32_e32 v102, v0
	v_mov_b32_e32 v103, v0
	v_mov_b32_e32 v112, v0
	v_mov_b32_e32 v113, v0
	v_mov_b32_e32 v114, v0
	v_mov_b32_e32 v115, v0
	v_mov_b32_e32 v116, v0
	v_mov_b32_e32 v117, v0
	v_mov_b32_e32 v118, v0
	v_mov_b32_e32 v119, v0
	v_mov_b32_e32 v72, v0
	v_mov_b32_e32 v73, v0
	v_mov_b32_e32 v74, v0
	v_mov_b32_e32 v75, v0
	v_mov_b32_e32 v76, v0
	v_mov_b32_e32 v77, v0
	v_mov_b32_e32 v78, v0
	v_mov_b32_e32 v79, v0
	v_mov_b32_e32 v88, v0
	v_mov_b32_e32 v89, v0
	v_mov_b32_e32 v90, v0
	v_mov_b32_e32 v91, v0
	v_mov_b32_e32 v92, v0
	v_mov_b32_e32 v93, v0
	v_mov_b32_e32 v94, v0
	v_mov_b32_e32 v95, v0
	v_mov_b32_e32 v104, v0
	v_mov_b32_e32 v105, v0
	v_mov_b32_e32 v106, v0
	v_mov_b32_e32 v107, v0
	v_mov_b32_e32 v108, v0
	v_mov_b32_e32 v109, v0
	v_mov_b32_e32 v110, v0
	v_mov_b32_e32 v111, v0
	v_mov_b32_e32 v120, v0
	v_mov_b32_e32 v121, v0
	v_mov_b32_e32 v122, v0
	v_mov_b32_e32 v123, v0
	v_mov_b32_e32 v124, v0
	v_mov_b32_e32 v125, v0
	v_mov_b32_e32 v126, v0
	v_mov_b32_e32 v127, v0
	v_add_u32_e32 v204, 0x80, v128
	v_add_u32_e32 v205, 0x80, v130
.LBB0_1561:
	ds_read_b128 v[140:143], v151
	ds_read_b128 v[144:147], v151 offset:1024
	ds_read_b128 v[156:159], v151 offset:2048
	ds_read_b128 v[160:163], v151 offset:3072
	ds_read_b128 v[164:167], v152
	ds_read_b128 v[168:171], v152 offset:1024
	ds_read_b128 v[172:175], v152 offset:2048
	ds_read_b128 v[176:179], v152 offset:3072
	s_add_u32 s38, s36, 0xfffc0080
	s_addc_u32 s39, s37, -1
	s_cmp_eq_u32 s61, 12
	s_cselect_b32 s41, s3, s39
	s_cselect_b32 s40, s29, s38
	s_cselect_b32 s39, s27, s60
	s_cselect_b32 s38, s58, s59
	s_add_i32 m0, s46, 0xc000
	ds_read_b128 v[180:183], v153
	ds_read_b128 v[184:187], v153 offset:1024
	ds_read_b128 v[188:191], v153 offset:2048
	ds_read_b128 v[192:195], v153 offset:3072
	ds_read_b128 v[196:199], v153 offset:4096
	ds_read_b128 v[200:203], v153 offset:5120
	ds_read_b128 v[208:211], v153 offset:6144
	ds_read_b128 v[212:215], v153 offset:7168
	global_load_lds_dwordx4 v134, s[36:37]
	s_add_i32 m0, s46, 0xe000
	s_nop 0
	global_load_lds_dwordx4 v132, s[36:37]
	s_waitcnt vmcnt(8)
	s_waitcnt lgkmcnt(0)
	s_barrier
	s_waitcnt lgkmcnt(0)
	v_mfma_f32_16x16x32_bf16 v[124:127], v[140:143], v[180:183], v[124:127]
	v_mfma_f32_16x16x32_bf16 v[120:123], v[156:159], v[180:183], v[120:123]
	v_mfma_f32_16x16x32_bf16 v[108:111], v[140:143], v[188:191], v[108:111]
	v_mfma_f32_16x16x32_bf16 v[104:107], v[156:159], v[188:191], v[104:107]
	v_mfma_f32_16x16x32_bf16 v[92:95], v[140:143], v[196:199], v[92:95]
	v_mfma_f32_16x16x32_bf16 v[88:91], v[156:159], v[196:199], v[88:91]
	v_mfma_f32_16x16x32_bf16 v[76:79], v[140:143], v[208:211], v[76:79]
	v_mfma_f32_16x16x32_bf16 v[72:75], v[156:159], v[208:211], v[72:75]
	v_mfma_f32_16x16x32_bf16 v[124:127], v[144:147], v[184:187], v[124:127]
	v_mfma_f32_16x16x32_bf16 v[120:123], v[160:163], v[184:187], v[120:123]
	v_mfma_f32_16x16x32_bf16 v[108:111], v[144:147], v[192:195], v[108:111]
	v_mfma_f32_16x16x32_bf16 v[104:107], v[160:163], v[192:195], v[104:107]
	v_mfma_f32_16x16x32_bf16 v[92:95], v[144:147], v[200:203], v[92:95]
	v_mfma_f32_16x16x32_bf16 v[88:91], v[160:163], v[200:203], v[88:91]
	v_mfma_f32_16x16x32_bf16 v[76:79], v[144:147], v[212:215], v[76:79]
	v_mfma_f32_16x16x32_bf16 v[72:75], v[160:163], v[212:215], v[72:75]
	v_mfma_f32_16x16x32_bf16 v[116:119], v[164:167], v[180:183], v[116:119]
	v_mfma_f32_16x16x32_bf16 v[112:115], v[172:175], v[180:183], v[112:115]
	v_mfma_f32_16x16x32_bf16 v[100:103], v[164:167], v[188:191], v[100:103]
	v_mfma_f32_16x16x32_bf16 v[96:99], v[172:175], v[188:191], v[96:99]
	v_mfma_f32_16x16x32_bf16 v[84:87], v[164:167], v[196:199], v[84:87]
	v_mfma_f32_16x16x32_bf16 v[80:83], v[172:175], v[196:199], v[80:83]
	v_mfma_f32_16x16x32_bf16 v[68:71], v[164:167], v[208:211], v[68:71]
	v_mfma_f32_16x16x32_bf16 v[64:67], v[172:175], v[208:211], v[64:67]
	v_mfma_f32_16x16x32_bf16 v[116:119], v[168:171], v[184:187], v[116:119]
	v_mfma_f32_16x16x32_bf16 v[112:115], v[176:179], v[184:187], v[112:115]
	v_mfma_f32_16x16x32_bf16 v[100:103], v[168:171], v[192:195], v[100:103]
	v_mfma_f32_16x16x32_bf16 v[96:99], v[176:179], v[192:195], v[96:99]
	v_mfma_f32_16x16x32_bf16 v[84:87], v[168:171], v[200:203], v[84:87]
	v_mfma_f32_16x16x32_bf16 v[80:83], v[176:179], v[200:203], v[80:83]
	v_mfma_f32_16x16x32_bf16 v[68:71], v[168:171], v[212:215], v[68:71]
	v_mfma_f32_16x16x32_bf16 v[64:67], v[176:179], v[212:215], v[64:67]
	s_barrier
	s_add_i32 s62, s54, s45
	s_mov_b32 m0, s62
	ds_read_b128 v[180:183], v153 offset:16384
	ds_read_b128 v[184:187], v153 offset:17408
	ds_read_b128 v[188:191], v153 offset:18432
	ds_read_b128 v[192:195], v153 offset:19456
	ds_read_b128 v[196:199], v153 offset:20480
	ds_read_b128 v[200:203], v153 offset:21504
	ds_read_b128 v[208:211], v153 offset:22528
	ds_read_b128 v[212:215], v153 offset:23552
	global_load_lds_dwordx4 v128, s[38:39]
	s_add_i32 m0, s62, 0x2000
	s_add_u32 s62, s38, 0x40000
	s_mov_b64 s[98:99], s[38:39]
	s_addc_u32 s63, s39, 0
	s_add_i32 s64, s55, s45
	global_load_lds_dwordx4 v130, s[38:39]
	s_mov_b32 m0, s64
	s_mov_b64 s[100:101], s[40:41]
	global_load_lds_dwordx4 v128, s[62:63]
	s_add_i32 m0, s64, 0x2000
	s_nop 0
	global_load_lds_dwordx4 v130, s[62:63]
	s_mov_b32 m0, s46
	s_nop 0
	global_load_lds_dwordx4 v128, s[40:41]
	s_mov_b32 m0, s47
	s_nop 0
	global_load_lds_dwordx4 v130, s[40:41]
	s_waitcnt vmcnt(8)
	s_waitcnt lgkmcnt(0)
	s_barrier
	s_waitcnt lgkmcnt(0)
	v_mfma_f32_16x16x32_bf16 v[60:63], v[140:143], v[180:183], v[60:63]
	v_mfma_f32_16x16x32_bf16 v[56:59], v[156:159], v[180:183], v[56:59]
	v_mfma_f32_16x16x32_bf16 v[44:47], v[140:143], v[188:191], v[44:47]
	v_mfma_f32_16x16x32_bf16 v[40:43], v[156:159], v[188:191], v[40:43]
	v_mfma_f32_16x16x32_bf16 v[28:31], v[140:143], v[196:199], v[28:31]
	v_mfma_f32_16x16x32_bf16 v[24:27], v[156:159], v[196:199], v[24:27]
	v_mfma_f32_16x16x32_bf16 v[12:15], v[140:143], v[208:211], v[12:15]
	v_mfma_f32_16x16x32_bf16 v[8:11], v[156:159], v[208:211], v[8:11]
	v_mfma_f32_16x16x32_bf16 v[60:63], v[144:147], v[184:187], v[60:63]
	v_mfma_f32_16x16x32_bf16 v[56:59], v[160:163], v[184:187], v[56:59]
	v_mfma_f32_16x16x32_bf16 v[44:47], v[144:147], v[192:195], v[44:47]
	v_mfma_f32_16x16x32_bf16 v[40:43], v[160:163], v[192:195], v[40:43]
	v_mfma_f32_16x16x32_bf16 v[28:31], v[144:147], v[200:203], v[28:31]
	v_mfma_f32_16x16x32_bf16 v[24:27], v[160:163], v[200:203], v[24:27]
	v_mfma_f32_16x16x32_bf16 v[12:15], v[144:147], v[212:215], v[12:15]
	v_mfma_f32_16x16x32_bf16 v[8:11], v[160:163], v[212:215], v[8:11]
	v_mfma_f32_16x16x32_bf16 v[52:55], v[164:167], v[180:183], v[52:55]
	v_mfma_f32_16x16x32_bf16 v[48:51], v[172:175], v[180:183], v[48:51]
	v_mfma_f32_16x16x32_bf16 v[36:39], v[164:167], v[188:191], v[36:39]
	v_mfma_f32_16x16x32_bf16 v[32:35], v[172:175], v[188:191], v[32:35]
	v_mfma_f32_16x16x32_bf16 v[20:23], v[164:167], v[196:199], v[20:23]
	v_mfma_f32_16x16x32_bf16 v[16:19], v[172:175], v[196:199], v[16:19]
	v_mfma_f32_16x16x32_bf16 v[4:7], v[164:167], v[208:211], v[4:7]
	v_mfma_f32_16x16x32_bf16 v[0:3], v[172:175], v[208:211], v[0:3]
	v_mfma_f32_16x16x32_bf16 v[52:55], v[168:171], v[184:187], v[52:55]
	v_mfma_f32_16x16x32_bf16 v[48:51], v[176:179], v[184:187], v[48:51]
	v_mfma_f32_16x16x32_bf16 v[36:39], v[168:171], v[192:195], v[36:39]
	v_mfma_f32_16x16x32_bf16 v[32:35], v[176:179], v[192:195], v[32:35]
	v_mfma_f32_16x16x32_bf16 v[20:23], v[168:171], v[200:203], v[20:23]
	v_mfma_f32_16x16x32_bf16 v[16:19], v[176:179], v[200:203], v[16:19]
	v_mfma_f32_16x16x32_bf16 v[4:7], v[168:171], v[212:215], v[4:7]
	v_mfma_f32_16x16x32_bf16 v[0:3], v[176:179], v[212:215], v[0:3]
	s_barrier
	s_add_i32 s62, 0, 0x18000
	v_add_u32_e32 v155, s62, v149
	s_add_i32 s63, 0, 0x1c000
	ds_read_b128 v[140:143], v155
	ds_read_b128 v[144:147], v155 offset:1024
	ds_read_b128 v[156:159], v155 offset:2048
	ds_read_b128 v[160:163], v155 offset:3072
	v_add_u32_e32 v155, s63, v149
	ds_read_b128 v[164:167], v155
	ds_read_b128 v[168:171], v155 offset:1024
	ds_read_b128 v[172:175], v155 offset:2048
	ds_read_b128 v[176:179], v155 offset:3072
	s_add_u32 s40, s40, 0x40000
	s_addc_u32 s41, s41, 0
	s_mov_b32 m0, s48
	ds_read_b128 v[180:183], v153 offset:32768
	ds_read_b128 v[184:187], v153 offset:33792
	ds_read_b128 v[188:191], v153 offset:34816
	ds_read_b128 v[192:195], v153 offset:35840
	ds_read_b128 v[196:199], v153 offset:36864
	ds_read_b128 v[200:203], v153 offset:37888
	ds_read_b128 v[208:211], v153 offset:38912
	ds_read_b128 v[212:215], v153 offset:39936
	global_load_lds_dwordx4 v128, s[40:41]
	s_mov_b32 m0, s49
	s_nop 0
	global_load_lds_dwordx4 v130, s[40:41]
	s_waitcnt vmcnt(8)
	s_waitcnt lgkmcnt(0)
	s_barrier
	s_waitcnt lgkmcnt(0)
	v_mfma_f32_16x16x32_bf16 v[124:127], v[140:143], v[180:183], v[124:127]
	v_mfma_f32_16x16x32_bf16 v[120:123], v[156:159], v[180:183], v[120:123]
	v_mfma_f32_16x16x32_bf16 v[108:111], v[140:143], v[188:191], v[108:111]
	v_mfma_f32_16x16x32_bf16 v[104:107], v[156:159], v[188:191], v[104:107]
	v_mfma_f32_16x16x32_bf16 v[92:95], v[140:143], v[196:199], v[92:95]
	v_mfma_f32_16x16x32_bf16 v[88:91], v[156:159], v[196:199], v[88:91]
	v_mfma_f32_16x16x32_bf16 v[76:79], v[140:143], v[208:211], v[76:79]
	v_mfma_f32_16x16x32_bf16 v[72:75], v[156:159], v[208:211], v[72:75]
	v_mfma_f32_16x16x32_bf16 v[124:127], v[144:147], v[184:187], v[124:127]
	v_mfma_f32_16x16x32_bf16 v[120:123], v[160:163], v[184:187], v[120:123]
	v_mfma_f32_16x16x32_bf16 v[108:111], v[144:147], v[192:195], v[108:111]
	v_mfma_f32_16x16x32_bf16 v[104:107], v[160:163], v[192:195], v[104:107]
	v_mfma_f32_16x16x32_bf16 v[92:95], v[144:147], v[200:203], v[92:95]
	v_mfma_f32_16x16x32_bf16 v[88:91], v[160:163], v[200:203], v[88:91]
	v_mfma_f32_16x16x32_bf16 v[76:79], v[144:147], v[212:215], v[76:79]
	v_mfma_f32_16x16x32_bf16 v[72:75], v[160:163], v[212:215], v[72:75]
	v_mfma_f32_16x16x32_bf16 v[116:119], v[164:167], v[180:183], v[116:119]
	v_mfma_f32_16x16x32_bf16 v[112:115], v[172:175], v[180:183], v[112:115]
	v_mfma_f32_16x16x32_bf16 v[100:103], v[164:167], v[188:191], v[100:103]
	v_mfma_f32_16x16x32_bf16 v[96:99], v[172:175], v[188:191], v[96:99]
	v_mfma_f32_16x16x32_bf16 v[84:87], v[164:167], v[196:199], v[84:87]
	v_mfma_f32_16x16x32_bf16 v[80:83], v[172:175], v[196:199], v[80:83]
	v_mfma_f32_16x16x32_bf16 v[68:71], v[164:167], v[208:211], v[68:71]
	v_mfma_f32_16x16x32_bf16 v[64:67], v[172:175], v[208:211], v[64:67]
	v_mfma_f32_16x16x32_bf16 v[116:119], v[168:171], v[184:187], v[116:119]
	v_mfma_f32_16x16x32_bf16 v[112:115], v[176:179], v[184:187], v[112:115]
	v_mfma_f32_16x16x32_bf16 v[100:103], v[168:171], v[192:195], v[100:103]
	v_mfma_f32_16x16x32_bf16 v[96:99], v[176:179], v[192:195], v[96:99]
	v_mfma_f32_16x16x32_bf16 v[84:87], v[168:171], v[200:203], v[84:87]
	v_mfma_f32_16x16x32_bf16 v[80:83], v[176:179], v[200:203], v[80:83]
	v_mfma_f32_16x16x32_bf16 v[68:71], v[168:171], v[212:215], v[68:71]
	v_mfma_f32_16x16x32_bf16 v[64:67], v[176:179], v[212:215], v[64:67]
	s_barrier
	s_add_i32 s40, s62, s45
	s_mov_b32 m0, s40
	ds_read_b128 v[180:183], v153 offset:49152
	ds_read_b128 v[184:187], v153 offset:50176
	ds_read_b128 v[188:191], v153 offset:51200
	ds_read_b128 v[192:195], v153 offset:52224
	ds_read_b128 v[196:199], v153 offset:53248
	ds_read_b128 v[200:203], v153 offset:54272
	ds_read_b128 v[208:211], v153 offset:55296
	ds_read_b128 v[212:215], v153 offset:56320
	global_load_lds_dwordx4 v204, s[38:39]
	s_add_i32 m0, s40, 0x2000
	s_add_u32 s38, s38, 0x40080
	s_addc_u32 s39, s39, 0
	s_add_i32 s40, s63, s45
	global_load_lds_dwordx4 v205, s[98:99]
	s_mov_b32 m0, s40
	s_nop 0
	global_load_lds_dwordx4 v128, s[38:39]
	s_add_i32 m0, s40, 0x2000
	s_nop 0
	global_load_lds_dwordx4 v130, s[38:39]
	s_mov_b32 m0, s51
	s_nop 0
	global_load_lds_dwordx4 v204, s[100:101]
	s_mov_b32 m0, s52
	s_nop 0
	global_load_lds_dwordx4 v205, s[100:101]
	s_waitcnt vmcnt(8)
	s_waitcnt lgkmcnt(0)
	s_barrier
	s_waitcnt lgkmcnt(0)
	v_mfma_f32_16x16x32_bf16 v[60:63], v[140:143], v[180:183], v[60:63]
	v_mfma_f32_16x16x32_bf16 v[56:59], v[156:159], v[180:183], v[56:59]
	v_mfma_f32_16x16x32_bf16 v[44:47], v[140:143], v[188:191], v[44:47]
	v_mfma_f32_16x16x32_bf16 v[40:43], v[156:159], v[188:191], v[40:43]
	v_mfma_f32_16x16x32_bf16 v[28:31], v[140:143], v[196:199], v[28:31]
	v_mfma_f32_16x16x32_bf16 v[24:27], v[156:159], v[196:199], v[24:27]
	v_mfma_f32_16x16x32_bf16 v[12:15], v[140:143], v[208:211], v[12:15]
	v_mfma_f32_16x16x32_bf16 v[8:11], v[156:159], v[208:211], v[8:11]
	v_mfma_f32_16x16x32_bf16 v[60:63], v[144:147], v[184:187], v[60:63]
	v_mfma_f32_16x16x32_bf16 v[56:59], v[160:163], v[184:187], v[56:59]
	v_mfma_f32_16x16x32_bf16 v[44:47], v[144:147], v[192:195], v[44:47]
	v_mfma_f32_16x16x32_bf16 v[40:43], v[160:163], v[192:195], v[40:43]
	v_mfma_f32_16x16x32_bf16 v[28:31], v[144:147], v[200:203], v[28:31]
	v_mfma_f32_16x16x32_bf16 v[24:27], v[160:163], v[200:203], v[24:27]
	v_mfma_f32_16x16x32_bf16 v[12:15], v[144:147], v[212:215], v[12:15]
	v_mfma_f32_16x16x32_bf16 v[8:11], v[160:163], v[212:215], v[8:11]
	v_mfma_f32_16x16x32_bf16 v[52:55], v[164:167], v[180:183], v[52:55]
	v_mfma_f32_16x16x32_bf16 v[48:51], v[172:175], v[180:183], v[48:51]
	v_mfma_f32_16x16x32_bf16 v[36:39], v[164:167], v[188:191], v[36:39]
	v_mfma_f32_16x16x32_bf16 v[32:35], v[172:175], v[188:191], v[32:35]
	v_mfma_f32_16x16x32_bf16 v[20:23], v[164:167], v[196:199], v[20:23]
	v_mfma_f32_16x16x32_bf16 v[16:19], v[172:175], v[196:199], v[16:19]
	v_mfma_f32_16x16x32_bf16 v[4:7], v[164:167], v[208:211], v[4:7]
	v_mfma_f32_16x16x32_bf16 v[0:3], v[172:175], v[208:211], v[0:3]
	v_mfma_f32_16x16x32_bf16 v[52:55], v[168:171], v[184:187], v[52:55]
	v_mfma_f32_16x16x32_bf16 v[48:51], v[176:179], v[184:187], v[48:51]
	v_mfma_f32_16x16x32_bf16 v[36:39], v[168:171], v[192:195], v[36:39]
	v_mfma_f32_16x16x32_bf16 v[32:35], v[176:179], v[192:195], v[32:35]
	v_mfma_f32_16x16x32_bf16 v[20:23], v[168:171], v[200:203], v[20:23]
	v_mfma_f32_16x16x32_bf16 v[16:19], v[176:179], v[200:203], v[16:19]
	v_mfma_f32_16x16x32_bf16 v[4:7], v[168:171], v[212:215], v[4:7]
	v_mfma_f32_16x16x32_bf16 v[0:3], v[176:179], v[212:215], v[0:3]
	s_barrier
	s_add_i32 s61, s61, 2
	s_add_u32 s59, s59, 0x100
	s_addc_u32 s60, s60, 0
	s_add_u32 s36, s36, 0x100
	s_addc_u32 s37, s37, 0
	s_cmp_gt_u32 s61, 13
	s_cbranch_scc0 .LBB0_1561
	s_and_b64 vcc, exec, s[24:25]
	s_cbranch_vccz .LBB0_1564
	s_barrier

.LBB0_1645:
	s_ashr_i32 s19, s18, 31
	s_lshl_b64 s[20:21], s[18:19], 19
	s_add_u32 s20, s8, s20
	s_addc_u32 s21, s9, s21
	s_and_b64 s[22:23], s[4:5], exec
	s_cselect_b32 s19, s21, s27
	s_cselect_b32 s50, s20, s26
	s_ashr_i32 s17, s16, 31
	s_lshl_b64 s[22:23], s[16:17], 19
	s_add_u32 s22, s31, s22
	s_addc_u32 s23, s34, s23
	s_and_b64 s[28:29], s[4:5], exec
	s_cselect_b32 s17, s23, s25
	s_cselect_b32 s51, s22, s24
	s_add_u32 s52, s24, 0x100
	s_addc_u32 s53, s25, 0
	s_add_u32 s24, s26, 0x40080
	v_mov_b32_e32 v0, 0
	s_addc_u32 s25, s27, 0
	s_mov_b32 s54, -2
	v_mov_b32_e32 v1, v0
	v_mov_b32_e32 v2, v0
	v_mov_b32_e32 v3, v0
	v_mov_b32_e32 v4, v0
	v_mov_b32_e32 v5, v0
	v_mov_b32_e32 v6, v0
	v_mov_b32_e32 v7, v0
	v_mov_b32_e32 v16, v0
	v_mov_b32_e32 v17, v0
	v_mov_b32_e32 v18, v0
	v_mov_b32_e32 v19, v0
	v_mov_b32_e32 v20, v0
	v_mov_b32_e32 v21, v0
	v_mov_b32_e32 v22, v0
	v_mov_b32_e32 v23, v0
	v_mov_b32_e32 v32, v0
	v_mov_b32_e32 v33, v0
	v_mov_b32_e32 v34, v0
	v_mov_b32_e32 v35, v0
	v_mov_b32_e32 v36, v0
	v_mov_b32_e32 v37, v0
	v_mov_b32_e32 v38, v0
	v_mov_b32_e32 v39, v0
	v_mov_b32_e32 v48, v0
	v_mov_b32_e32 v49, v0
	v_mov_b32_e32 v50, v0
	v_mov_b32_e32 v51, v0
	v_mov_b32_e32 v52, v0
	v_mov_b32_e32 v53, v0
	v_mov_b32_e32 v54, v0
	v_mov_b32_e32 v55, v0
	v_mov_b32_e32 v8, v0
	v_mov_b32_e32 v9, v0
	v_mov_b32_e32 v10, v0
	v_mov_b32_e32 v11, v0
	v_mov_b32_e32 v12, v0
	v_mov_b32_e32 v13, v0
	v_mov_b32_e32 v14, v0
	v_mov_b32_e32 v15, v0
	v_mov_b32_e32 v24, v0
	v_mov_b32_e32 v25, v0
	v_mov_b32_e32 v26, v0
	v_mov_b32_e32 v27, v0
	v_mov_b32_e32 v28, v0
	v_mov_b32_e32 v29, v0
	v_mov_b32_e32 v30, v0
	v_mov_b32_e32 v31, v0
	v_mov_b32_e32 v40, v0
	v_mov_b32_e32 v41, v0
	v_mov_b32_e32 v42, v0
	v_mov_b32_e32 v43, v0
	v_mov_b32_e32 v44, v0
	v_mov_b32_e32 v45, v0
	v_mov_b32_e32 v46, v0
	v_mov_b32_e32 v47, v0
	v_mov_b32_e32 v56, v0
	v_mov_b32_e32 v57, v0
	v_mov_b32_e32 v58, v0
	v_mov_b32_e32 v59, v0
	v_mov_b32_e32 v60, v0
	v_mov_b32_e32 v61, v0
	v_mov_b32_e32 v62, v0
	v_mov_b32_e32 v63, v0
	v_mov_b32_e32 v64, v0
	v_mov_b32_e32 v65, v0
	v_mov_b32_e32 v66, v0
	v_mov_b32_e32 v67, v0
	v_mov_b32_e32 v68, v0
	v_mov_b32_e32 v69, v0
	v_mov_b32_e32 v70, v0
	v_mov_b32_e32 v71, v0
	v_mov_b32_e32 v80, v0
	v_mov_b32_e32 v81, v0
	v_mov_b32_e32 v82, v0
	v_mov_b32_e32 v83, v0
	v_mov_b32_e32 v84, v0
	v_mov_b32_e32 v85, v0
	v_mov_b32_e32 v86, v0
	v_mov_b32_e32 v87, v0
	v_mov_b32_e32 v96, v0
	v_mov_b32_e32 v97, v0
	v_mov_b32_e32 v98, v0
	v_mov_b32_e32 v99, v0
	v_mov_b32_e32 v100, v0
	v_mov_b32_e32 v101, v0
	v_mov_b32_e32 v102, v0
	v_mov_b32_e32 v103, v0
	v_mov_b32_e32 v112, v0
	v_mov_b32_e32 v113, v0
	v_mov_b32_e32 v114, v0
	v_mov_b32_e32 v115, v0
	v_mov_b32_e32 v116, v0
	v_mov_b32_e32 v117, v0
	v_mov_b32_e32 v118, v0
	v_mov_b32_e32 v119, v0
	v_mov_b32_e32 v72, v0
	v_mov_b32_e32 v73, v0
	v_mov_b32_e32 v74, v0
	v_mov_b32_e32 v75, v0
	v_mov_b32_e32 v76, v0
	v_mov_b32_e32 v77, v0
	v_mov_b32_e32 v78, v0
	v_mov_b32_e32 v79, v0
	v_mov_b32_e32 v88, v0
	v_mov_b32_e32 v89, v0
	v_mov_b32_e32 v90, v0
	v_mov_b32_e32 v91, v0
	v_mov_b32_e32 v92, v0
	v_mov_b32_e32 v93, v0
	v_mov_b32_e32 v94, v0
	v_mov_b32_e32 v95, v0
	v_mov_b32_e32 v104, v0
	v_mov_b32_e32 v105, v0
	v_mov_b32_e32 v106, v0
	v_mov_b32_e32 v107, v0
	v_mov_b32_e32 v108, v0
	v_mov_b32_e32 v109, v0
	v_mov_b32_e32 v110, v0
	v_mov_b32_e32 v111, v0
	v_mov_b32_e32 v120, v0
	v_mov_b32_e32 v121, v0
	v_mov_b32_e32 v122, v0
	v_mov_b32_e32 v123, v0
	v_mov_b32_e32 v124, v0
	v_mov_b32_e32 v125, v0
	v_mov_b32_e32 v126, v0
	v_mov_b32_e32 v127, v0
	v_add_u32_e32 v204, 0x80, v128
	v_add_u32_e32 v205, 0x80, v130
	v_add_u32_e32 v220, 0x80, v132
	v_add_u32_e32 v221, 0x80, v134
.LBB0_1646:
	ds_read_b128 v[144:147], v151
	ds_read_b128 v[156:159], v151 offset:1024
	ds_read_b128 v[160:163], v151 offset:2048
	ds_read_b128 v[164:167], v151 offset:3072
	ds_read_b128 v[168:171], v152
	ds_read_b128 v[172:175], v152 offset:1024
	ds_read_b128 v[176:179], v152 offset:2048
	ds_read_b128 v[180:183], v152 offset:3072
	s_add_u32 s26, s24, 0xfffc0080
	s_addc_u32 s27, s25, -1
	s_cmp_eq_u32 s54, 12
	s_cselect_b32 s29, s19, s27
	s_cselect_b32 s28, s50, s26
	s_cselect_b32 s27, s17, s53
	s_cselect_b32 s26, s51, s52
	s_add_i32 m0, s38, 0xc000
	ds_read_b128 v[184:187], v153
	ds_read_b128 v[188:191], v153 offset:1024
	ds_read_b128 v[192:195], v153 offset:2048
	ds_read_b128 v[196:199], v153 offset:3072
	ds_read_b128 v[200:203], v153 offset:4096
	ds_read_b128 v[208:211], v153 offset:5120
	ds_read_b128 v[212:215], v153 offset:6144
	ds_read_b128 v[216:219], v153 offset:7168
	global_load_lds_dwordx4 v138, s[24:25]
	s_add_i32 m0, s38, 0xe000
	s_nop 0
	global_load_lds_dwordx4 v136, s[24:25]
	s_waitcnt vmcnt(8)
	s_waitcnt lgkmcnt(0)
	s_barrier
	s_waitcnt lgkmcnt(0)
	v_mfma_f32_16x16x32_bf16 v[124:127], v[144:147], v[184:187], v[124:127]
	v_mfma_f32_16x16x32_bf16 v[120:123], v[160:163], v[184:187], v[120:123]
	v_mfma_f32_16x16x32_bf16 v[108:111], v[144:147], v[192:195], v[108:111]
	v_mfma_f32_16x16x32_bf16 v[104:107], v[160:163], v[192:195], v[104:107]
	v_mfma_f32_16x16x32_bf16 v[92:95], v[144:147], v[200:203], v[92:95]
	v_mfma_f32_16x16x32_bf16 v[88:91], v[160:163], v[200:203], v[88:91]
	v_mfma_f32_16x16x32_bf16 v[76:79], v[144:147], v[212:215], v[76:79]
	v_mfma_f32_16x16x32_bf16 v[72:75], v[160:163], v[212:215], v[72:75]
	v_mfma_f32_16x16x32_bf16 v[124:127], v[156:159], v[188:191], v[124:127]
	v_mfma_f32_16x16x32_bf16 v[120:123], v[164:167], v[188:191], v[120:123]
	v_mfma_f32_16x16x32_bf16 v[108:111], v[156:159], v[196:199], v[108:111]
	v_mfma_f32_16x16x32_bf16 v[104:107], v[164:167], v[196:199], v[104:107]
	v_mfma_f32_16x16x32_bf16 v[92:95], v[156:159], v[208:211], v[92:95]
	v_mfma_f32_16x16x32_bf16 v[88:91], v[164:167], v[208:211], v[88:91]
	v_mfma_f32_16x16x32_bf16 v[76:79], v[156:159], v[216:219], v[76:79]
	v_mfma_f32_16x16x32_bf16 v[72:75], v[164:167], v[216:219], v[72:75]
	v_mfma_f32_16x16x32_bf16 v[116:119], v[168:171], v[184:187], v[116:119]
	v_mfma_f32_16x16x32_bf16 v[112:115], v[176:179], v[184:187], v[112:115]
	v_mfma_f32_16x16x32_bf16 v[100:103], v[168:171], v[192:195], v[100:103]
	v_mfma_f32_16x16x32_bf16 v[96:99], v[176:179], v[192:195], v[96:99]
	v_mfma_f32_16x16x32_bf16 v[84:87], v[168:171], v[200:203], v[84:87]
	v_mfma_f32_16x16x32_bf16 v[80:83], v[176:179], v[200:203], v[80:83]
	v_mfma_f32_16x16x32_bf16 v[68:71], v[168:171], v[212:215], v[68:71]
	v_mfma_f32_16x16x32_bf16 v[64:67], v[176:179], v[212:215], v[64:67]
	v_mfma_f32_16x16x32_bf16 v[116:119], v[172:175], v[188:191], v[116:119]
	v_mfma_f32_16x16x32_bf16 v[112:115], v[180:183], v[188:191], v[112:115]
	v_mfma_f32_16x16x32_bf16 v[100:103], v[172:175], v[196:199], v[100:103]
	v_mfma_f32_16x16x32_bf16 v[96:99], v[180:183], v[196:199], v[96:99]
	v_mfma_f32_16x16x32_bf16 v[84:87], v[172:175], v[208:211], v[84:87]
	v_mfma_f32_16x16x32_bf16 v[80:83], v[180:183], v[208:211], v[80:83]
	v_mfma_f32_16x16x32_bf16 v[68:71], v[172:175], v[216:219], v[68:71]
	v_mfma_f32_16x16x32_bf16 v[64:67], v[180:183], v[216:219], v[64:67]
	s_barrier
	s_add_i32 s55, s47, s35
	s_mov_b32 m0, s55
	ds_read_b128 v[184:187], v153 offset:16384
	ds_read_b128 v[188:191], v153 offset:17408
	ds_read_b128 v[192:195], v153 offset:18432
	ds_read_b128 v[196:199], v153 offset:19456
	ds_read_b128 v[200:203], v153 offset:20480
	ds_read_b128 v[208:211], v153 offset:21504
	ds_read_b128 v[212:215], v153 offset:22528
	ds_read_b128 v[216:219], v153 offset:23552
	global_load_lds_dwordx4 v132, s[26:27]
	s_add_i32 m0, s55, 0x2000
	s_add_u32 s56, s26, 0x40000
	s_mov_b64 s[98:99], s[26:27]
	s_addc_u32 s57, s27, 0
	s_add_i32 s55, s48, s35
	global_load_lds_dwordx4 v128, s[26:27]
	s_mov_b32 m0, s55
	s_mov_b64 s[100:101], s[28:29]
	global_load_lds_dwordx4 v132, s[56:57]
	s_add_i32 m0, s55, 0x2000
	s_nop 0
	global_load_lds_dwordx4 v128, s[56:57]
	s_mov_b32 m0, s38
	s_nop 0
	global_load_lds_dwordx4 v134, s[28:29]
	s_mov_b32 m0, s39
	s_nop 0
	global_load_lds_dwordx4 v130, s[28:29]
	s_waitcnt vmcnt(8)
	s_waitcnt lgkmcnt(0)
	s_barrier
	s_waitcnt lgkmcnt(0)
	v_mfma_f32_16x16x32_bf16 v[60:63], v[144:147], v[184:187], v[60:63]
	v_mfma_f32_16x16x32_bf16 v[56:59], v[160:163], v[184:187], v[56:59]
	v_mfma_f32_16x16x32_bf16 v[44:47], v[144:147], v[192:195], v[44:47]
	v_mfma_f32_16x16x32_bf16 v[40:43], v[160:163], v[192:195], v[40:43]
	v_mfma_f32_16x16x32_bf16 v[28:31], v[144:147], v[200:203], v[28:31]
	v_mfma_f32_16x16x32_bf16 v[24:27], v[160:163], v[200:203], v[24:27]
	v_mfma_f32_16x16x32_bf16 v[12:15], v[144:147], v[212:215], v[12:15]
	v_mfma_f32_16x16x32_bf16 v[8:11], v[160:163], v[212:215], v[8:11]
	v_mfma_f32_16x16x32_bf16 v[60:63], v[156:159], v[188:191], v[60:63]
	v_mfma_f32_16x16x32_bf16 v[56:59], v[164:167], v[188:191], v[56:59]
	v_mfma_f32_16x16x32_bf16 v[44:47], v[156:159], v[196:199], v[44:47]
	v_mfma_f32_16x16x32_bf16 v[40:43], v[164:167], v[196:199], v[40:43]
	v_mfma_f32_16x16x32_bf16 v[28:31], v[156:159], v[208:211], v[28:31]
	v_mfma_f32_16x16x32_bf16 v[24:27], v[164:167], v[208:211], v[24:27]
	v_mfma_f32_16x16x32_bf16 v[12:15], v[156:159], v[216:219], v[12:15]
	v_mfma_f32_16x16x32_bf16 v[8:11], v[164:167], v[216:219], v[8:11]
	v_mfma_f32_16x16x32_bf16 v[52:55], v[168:171], v[184:187], v[52:55]
	v_mfma_f32_16x16x32_bf16 v[48:51], v[176:179], v[184:187], v[48:51]
	v_mfma_f32_16x16x32_bf16 v[36:39], v[168:171], v[192:195], v[36:39]
	v_mfma_f32_16x16x32_bf16 v[32:35], v[176:179], v[192:195], v[32:35]
	v_mfma_f32_16x16x32_bf16 v[20:23], v[168:171], v[200:203], v[20:23]
	v_mfma_f32_16x16x32_bf16 v[16:19], v[176:179], v[200:203], v[16:19]
	v_mfma_f32_16x16x32_bf16 v[4:7], v[168:171], v[212:215], v[4:7]
	v_mfma_f32_16x16x32_bf16 v[0:3], v[176:179], v[212:215], v[0:3]
	v_mfma_f32_16x16x32_bf16 v[52:55], v[172:175], v[188:191], v[52:55]
	v_mfma_f32_16x16x32_bf16 v[48:51], v[180:183], v[188:191], v[48:51]
	v_mfma_f32_16x16x32_bf16 v[36:39], v[172:175], v[196:199], v[36:39]
	v_mfma_f32_16x16x32_bf16 v[32:35], v[180:183], v[196:199], v[32:35]
	v_mfma_f32_16x16x32_bf16 v[20:23], v[172:175], v[208:211], v[20:23]
	v_mfma_f32_16x16x32_bf16 v[16:19], v[180:183], v[208:211], v[16:19]
	v_mfma_f32_16x16x32_bf16 v[4:7], v[172:175], v[216:219], v[4:7]
	v_mfma_f32_16x16x32_bf16 v[0:3], v[180:183], v[216:219], v[0:3]
	s_barrier
	s_add_i32 s55, 0, 0x18000
	s_add_i32 s56, 0, 0x1c000
	v_add_u32_e32 v164, s55, v149
	v_add_u32_e32 v180, s56, v149
	ds_read_b128 v[144:147], v164
	ds_read_b128 v[156:159], v164 offset:1024
	ds_read_b128 v[160:163], v164 offset:2048
	ds_read_b128 v[164:167], v164 offset:3072
	ds_read_b128 v[168:171], v180
	ds_read_b128 v[172:175], v180 offset:1024
	ds_read_b128 v[176:179], v180 offset:2048
	ds_read_b128 v[180:183], v180 offset:3072
	s_add_u32 s28, s28, 0x40000
	s_addc_u32 s29, s29, 0
	s_mov_b32 m0, s40
	ds_read_b128 v[184:187], v153 offset:32768
	ds_read_b128 v[188:191], v153 offset:33792
	ds_read_b128 v[192:195], v153 offset:34816
	ds_read_b128 v[196:199], v153 offset:35840
	ds_read_b128 v[200:203], v153 offset:36864
	ds_read_b128 v[208:211], v153 offset:37888
	ds_read_b128 v[212:215], v153 offset:38912
	ds_read_b128 v[216:219], v153 offset:39936
	global_load_lds_dwordx4 v134, s[28:29]
	s_mov_b32 m0, s41
	s_nop 0
	global_load_lds_dwordx4 v130, s[28:29]
	s_waitcnt vmcnt(8)
	s_waitcnt lgkmcnt(0)
	s_barrier
	s_waitcnt lgkmcnt(0)
	v_mfma_f32_16x16x32_bf16 v[124:127], v[144:147], v[184:187], v[124:127]
	v_mfma_f32_16x16x32_bf16 v[120:123], v[160:163], v[184:187], v[120:123]
	v_mfma_f32_16x16x32_bf16 v[108:111], v[144:147], v[192:195], v[108:111]
	v_mfma_f32_16x16x32_bf16 v[104:107], v[160:163], v[192:195], v[104:107]
	v_mfma_f32_16x16x32_bf16 v[92:95], v[144:147], v[200:203], v[92:95]
	v_mfma_f32_16x16x32_bf16 v[88:91], v[160:163], v[200:203], v[88:91]
	v_mfma_f32_16x16x32_bf16 v[76:79], v[144:147], v[212:215], v[76:79]
	v_mfma_f32_16x16x32_bf16 v[72:75], v[160:163], v[212:215], v[72:75]
	v_mfma_f32_16x16x32_bf16 v[124:127], v[156:159], v[188:191], v[124:127]
	v_mfma_f32_16x16x32_bf16 v[120:123], v[164:167], v[188:191], v[120:123]
	v_mfma_f32_16x16x32_bf16 v[108:111], v[156:159], v[196:199], v[108:111]
	v_mfma_f32_16x16x32_bf16 v[104:107], v[164:167], v[196:199], v[104:107]
	v_mfma_f32_16x16x32_bf16 v[92:95], v[156:159], v[208:211], v[92:95]
	v_mfma_f32_16x16x32_bf16 v[88:91], v[164:167], v[208:211], v[88:91]
	v_mfma_f32_16x16x32_bf16 v[76:79], v[156:159], v[216:219], v[76:79]
	v_mfma_f32_16x16x32_bf16 v[72:75], v[164:167], v[216:219], v[72:75]
	v_mfma_f32_16x16x32_bf16 v[116:119], v[168:171], v[184:187], v[116:119]
	v_mfma_f32_16x16x32_bf16 v[112:115], v[176:179], v[184:187], v[112:115]
	v_mfma_f32_16x16x32_bf16 v[100:103], v[168:171], v[192:195], v[100:103]
	v_mfma_f32_16x16x32_bf16 v[96:99], v[176:179], v[192:195], v[96:99]
	v_mfma_f32_16x16x32_bf16 v[84:87], v[168:171], v[200:203], v[84:87]
	v_mfma_f32_16x16x32_bf16 v[80:83], v[176:179], v[200:203], v[80:83]
	v_mfma_f32_16x16x32_bf16 v[68:71], v[168:171], v[212:215], v[68:71]
	v_mfma_f32_16x16x32_bf16 v[64:67], v[176:179], v[212:215], v[64:67]
	v_mfma_f32_16x16x32_bf16 v[116:119], v[172:175], v[188:191], v[116:119]
	v_mfma_f32_16x16x32_bf16 v[112:115], v[180:183], v[188:191], v[112:115]
	v_mfma_f32_16x16x32_bf16 v[100:103], v[172:175], v[196:199], v[100:103]
	v_mfma_f32_16x16x32_bf16 v[96:99], v[180:183], v[196:199], v[96:99]
	v_mfma_f32_16x16x32_bf16 v[84:87], v[172:175], v[208:211], v[84:87]
	v_mfma_f32_16x16x32_bf16 v[80:83], v[180:183], v[208:211], v[80:83]
	v_mfma_f32_16x16x32_bf16 v[68:71], v[172:175], v[216:219], v[68:71]
	v_mfma_f32_16x16x32_bf16 v[64:67], v[180:183], v[216:219], v[64:67]
	s_barrier
	s_add_i32 s28, s55, s35
	s_mov_b32 m0, s28
	ds_read_b128 v[184:187], v153 offset:49152
	ds_read_b128 v[188:191], v153 offset:50176
	ds_read_b128 v[192:195], v153 offset:51200
	ds_read_b128 v[196:199], v153 offset:52224
	ds_read_b128 v[200:203], v153 offset:53248
	ds_read_b128 v[208:211], v153 offset:54272
	ds_read_b128 v[212:215], v153 offset:55296
	ds_read_b128 v[216:219], v153 offset:56320
	global_load_lds_dwordx4 v220, s[26:27]
	s_add_i32 m0, s28, 0x2000
	s_add_u32 s26, s26, 0x40080
	s_addc_u32 s27, s27, 0
	s_add_i32 s28, s56, s35
	global_load_lds_dwordx4 v204, s[98:99]
	s_mov_b32 m0, s28
	s_nop 0
	global_load_lds_dwordx4 v132, s[26:27]
	s_add_i32 m0, s28, 0x2000
	s_nop 0
	global_load_lds_dwordx4 v128, s[26:27]
	s_mov_b32 m0, s45
	s_nop 0
	global_load_lds_dwordx4 v221, s[100:101]
	s_mov_b32 m0, s46
	s_nop 0
	global_load_lds_dwordx4 v205, s[100:101]
	s_waitcnt vmcnt(8)
	s_waitcnt lgkmcnt(0)
	s_barrier
	s_waitcnt lgkmcnt(0)
	v_mfma_f32_16x16x32_bf16 v[60:63], v[144:147], v[184:187], v[60:63]
	v_mfma_f32_16x16x32_bf16 v[56:59], v[160:163], v[184:187], v[56:59]
	v_mfma_f32_16x16x32_bf16 v[44:47], v[144:147], v[192:195], v[44:47]
	v_mfma_f32_16x16x32_bf16 v[40:43], v[160:163], v[192:195], v[40:43]
	v_mfma_f32_16x16x32_bf16 v[28:31], v[144:147], v[200:203], v[28:31]
	v_mfma_f32_16x16x32_bf16 v[24:27], v[160:163], v[200:203], v[24:27]
	v_mfma_f32_16x16x32_bf16 v[12:15], v[144:147], v[212:215], v[12:15]
	v_mfma_f32_16x16x32_bf16 v[8:11], v[160:163], v[212:215], v[8:11]
	v_mfma_f32_16x16x32_bf16 v[60:63], v[156:159], v[188:191], v[60:63]
	v_mfma_f32_16x16x32_bf16 v[56:59], v[164:167], v[188:191], v[56:59]
	v_mfma_f32_16x16x32_bf16 v[44:47], v[156:159], v[196:199], v[44:47]
	v_mfma_f32_16x16x32_bf16 v[40:43], v[164:167], v[196:199], v[40:43]
	v_mfma_f32_16x16x32_bf16 v[28:31], v[156:159], v[208:211], v[28:31]
	v_mfma_f32_16x16x32_bf16 v[24:27], v[164:167], v[208:211], v[24:27]
	v_mfma_f32_16x16x32_bf16 v[12:15], v[156:159], v[216:219], v[12:15]
	v_mfma_f32_16x16x32_bf16 v[8:11], v[164:167], v[216:219], v[8:11]
	v_mfma_f32_16x16x32_bf16 v[52:55], v[168:171], v[184:187], v[52:55]
	v_mfma_f32_16x16x32_bf16 v[48:51], v[176:179], v[184:187], v[48:51]
	v_mfma_f32_16x16x32_bf16 v[36:39], v[168:171], v[192:195], v[36:39]
	v_mfma_f32_16x16x32_bf16 v[32:35], v[176:179], v[192:195], v[32:35]
	v_mfma_f32_16x16x32_bf16 v[20:23], v[168:171], v[200:203], v[20:23]
	v_mfma_f32_16x16x32_bf16 v[16:19], v[176:179], v[200:203], v[16:19]
	v_mfma_f32_16x16x32_bf16 v[4:7], v[168:171], v[212:215], v[4:7]
	v_mfma_f32_16x16x32_bf16 v[0:3], v[176:179], v[212:215], v[0:3]
	v_mfma_f32_16x16x32_bf16 v[52:55], v[172:175], v[188:191], v[52:55]
	v_mfma_f32_16x16x32_bf16 v[48:51], v[180:183], v[188:191], v[48:51]
	v_mfma_f32_16x16x32_bf16 v[36:39], v[172:175], v[196:199], v[36:39]
	v_mfma_f32_16x16x32_bf16 v[32:35], v[180:183], v[196:199], v[32:35]
	v_mfma_f32_16x16x32_bf16 v[20:23], v[172:175], v[208:211], v[20:23]
	v_mfma_f32_16x16x32_bf16 v[16:19], v[180:183], v[208:211], v[16:19]
	v_mfma_f32_16x16x32_bf16 v[4:7], v[172:175], v[216:219], v[4:7]
	v_mfma_f32_16x16x32_bf16 v[0:3], v[180:183], v[216:219], v[0:3]
	s_barrier
	s_add_i32 s54, s54, 2
	s_add_u32 s52, s52, 0x100
	s_addc_u32 s53, s53, 0
	s_add_u32 s24, s24, 0x100
	s_addc_u32 s25, s25, 0
	s_cmp_gt_u32 s54, 13
	s_cbranch_scc0 .LBB0_1646
	s_and_b64 vcc, exec, s[14:15]
	s_cbranch_vccz .LBB0_1649
	s_barrier

.LBB0_3040:
	s_ashr_i32 s29, s28, 31
	s_lshl_b64 s[30:31], s[28:29], 19
	s_add_u32 s30, s8, s30
	s_addc_u32 s31, s9, s31
	s_and_b64 s[34:35], s[6:7], exec
	s_cselect_b32 s3, s31, s39
	s_cselect_b32 s29, s30, s38
	s_ashr_i32 s27, s26, 31
	s_lshl_b64 s[34:35], s[26:27], 19
	s_add_u32 s34, s43, s34
	s_addc_u32 s35, s44, s35
	s_and_b64 s[40:41], s[6:7], exec
	s_cselect_b32 s27, s35, s37
	s_cselect_b32 s58, s34, s36
	s_add_u32 s59, s36, 0x100
	s_addc_u32 s60, s37, 0
	s_add_u32 s36, s38, 0x40080
	v_mov_b32_e32 v0, 0
	s_addc_u32 s37, s39, 0
	s_mov_b32 s61, -2
	v_mov_b32_e32 v1, v0
	v_mov_b32_e32 v2, v0
	v_mov_b32_e32 v3, v0
	v_mov_b32_e32 v4, v0
	v_mov_b32_e32 v5, v0
	v_mov_b32_e32 v6, v0
	v_mov_b32_e32 v7, v0
	v_mov_b32_e32 v16, v0
	v_mov_b32_e32 v17, v0
	v_mov_b32_e32 v18, v0
	v_mov_b32_e32 v19, v0
	v_mov_b32_e32 v20, v0
	v_mov_b32_e32 v21, v0
	v_mov_b32_e32 v22, v0
	v_mov_b32_e32 v23, v0
	v_mov_b32_e32 v32, v0
	v_mov_b32_e32 v33, v0
	v_mov_b32_e32 v34, v0
	v_mov_b32_e32 v35, v0
	v_mov_b32_e32 v36, v0
	v_mov_b32_e32 v37, v0
	v_mov_b32_e32 v38, v0
	v_mov_b32_e32 v39, v0
	v_mov_b32_e32 v48, v0
	v_mov_b32_e32 v49, v0
	v_mov_b32_e32 v50, v0
	v_mov_b32_e32 v51, v0
	v_mov_b32_e32 v52, v0
	v_mov_b32_e32 v53, v0
	v_mov_b32_e32 v54, v0
	v_mov_b32_e32 v55, v0
	v_mov_b32_e32 v8, v0
	v_mov_b32_e32 v9, v0
	v_mov_b32_e32 v10, v0
	v_mov_b32_e32 v11, v0
	v_mov_b32_e32 v12, v0
	v_mov_b32_e32 v13, v0
	v_mov_b32_e32 v14, v0
	v_mov_b32_e32 v15, v0
	v_mov_b32_e32 v24, v0
	v_mov_b32_e32 v25, v0
	v_mov_b32_e32 v26, v0
	v_mov_b32_e32 v27, v0
	v_mov_b32_e32 v28, v0
	v_mov_b32_e32 v29, v0
	v_mov_b32_e32 v30, v0
	v_mov_b32_e32 v31, v0
	v_mov_b32_e32 v40, v0
	v_mov_b32_e32 v41, v0
	v_mov_b32_e32 v42, v0
	v_mov_b32_e32 v43, v0
	v_mov_b32_e32 v44, v0
	v_mov_b32_e32 v45, v0
	v_mov_b32_e32 v46, v0
	v_mov_b32_e32 v47, v0
	v_mov_b32_e32 v56, v0
	v_mov_b32_e32 v57, v0
	v_mov_b32_e32 v58, v0
	v_mov_b32_e32 v59, v0
	v_mov_b32_e32 v60, v0
	v_mov_b32_e32 v61, v0
	v_mov_b32_e32 v62, v0
	v_mov_b32_e32 v63, v0
	v_mov_b32_e32 v64, v0
	v_mov_b32_e32 v65, v0
	v_mov_b32_e32 v66, v0
	v_mov_b32_e32 v67, v0
	v_mov_b32_e32 v68, v0
	v_mov_b32_e32 v69, v0
	v_mov_b32_e32 v70, v0
	v_mov_b32_e32 v71, v0
	v_mov_b32_e32 v80, v0
	v_mov_b32_e32 v81, v0
	v_mov_b32_e32 v82, v0
	v_mov_b32_e32 v83, v0
	v_mov_b32_e32 v84, v0
	v_mov_b32_e32 v85, v0
	v_mov_b32_e32 v86, v0
	v_mov_b32_e32 v87, v0
	v_mov_b32_e32 v96, v0
	v_mov_b32_e32 v97, v0
	v_mov_b32_e32 v98, v0
	v_mov_b32_e32 v99, v0
	v_mov_b32_e32 v100, v0
	v_mov_b32_e32 v101, v0
	v_mov_b32_e32 v102, v0
	v_mov_b32_e32 v103, v0
	v_mov_b32_e32 v112, v0
	v_mov_b32_e32 v113, v0
	v_mov_b32_e32 v114, v0
	v_mov_b32_e32 v115, v0
	v_mov_b32_e32 v116, v0
	v_mov_b32_e32 v117, v0
	v_mov_b32_e32 v118, v0
	v_mov_b32_e32 v119, v0
	v_mov_b32_e32 v72, v0
	v_mov_b32_e32 v73, v0
	v_mov_b32_e32 v74, v0
	v_mov_b32_e32 v75, v0
	v_mov_b32_e32 v76, v0
	v_mov_b32_e32 v77, v0
	v_mov_b32_e32 v78, v0
	v_mov_b32_e32 v79, v0
	v_mov_b32_e32 v88, v0
	v_mov_b32_e32 v89, v0
	v_mov_b32_e32 v90, v0
	v_mov_b32_e32 v91, v0
	v_mov_b32_e32 v92, v0
	v_mov_b32_e32 v93, v0
	v_mov_b32_e32 v94, v0
	v_mov_b32_e32 v95, v0
	v_mov_b32_e32 v104, v0
	v_mov_b32_e32 v105, v0
	v_mov_b32_e32 v106, v0
	v_mov_b32_e32 v107, v0
	v_mov_b32_e32 v108, v0
	v_mov_b32_e32 v109, v0
	v_mov_b32_e32 v110, v0
	v_mov_b32_e32 v111, v0
	v_mov_b32_e32 v120, v0
	v_mov_b32_e32 v121, v0
	v_mov_b32_e32 v122, v0
	v_mov_b32_e32 v123, v0
	v_mov_b32_e32 v124, v0
	v_mov_b32_e32 v125, v0
	v_mov_b32_e32 v126, v0
	v_mov_b32_e32 v127, v0
	v_add_u32_e32 v204, 0x80, v128
	v_add_u32_e32 v205, 0x80, v130
